# same as previous plus all s_setprio toggles removed (no effect expected on this role-split GEMM loop)
# speedup vs baseline: 1.0035x; 1.0035x over previous
.LBB0_49:
	ds_read_b128 v[152:155], v148
	ds_read_b128 v[156:159], v148 offset:1024
	ds_read_b128 v[160:163], v148 offset:2048
	ds_read_b128 v[164:167], v148 offset:3072
	ds_read_b128 v[168:171], v149
	ds_read_b128 v[172:175], v149 offset:1024
	ds_read_b128 v[176:179], v149 offset:2048
	ds_read_b128 v[180:183], v149 offset:3072
	s_add_u32 s33, s34, 0xfff80080
	s_addc_u32 s36, s35, -1
	s_cmp_eq_u32 s58, 28
	s_cselect_b32 s39, s17, s36
	s_cselect_b32 s38, s54, s33
	s_cselect_b32 s37, s15, s57
	s_cselect_b32 s36, s55, s56
	v_lshl_add_u64 v[216:217], s[34:35], 0, v[138:139]
	s_add_i32 m0, s31, 0xc000
	ds_read_b128 v[184:187], v150
	ds_read_b128 v[188:191], v150 offset:1024
	ds_read_b128 v[192:195], v150 offset:2048
	ds_read_b128 v[196:199], v150 offset:3072
	ds_read_b128 v[200:203], v150 offset:4096
	ds_read_b128 v[204:207], v150 offset:5120
	ds_read_b128 v[208:211], v150 offset:6144
	ds_read_b128 v[212:215], v150 offset:7168
	global_load_lds_dwordx4 v[216:217], off
	v_lshl_add_u64 v[216:217], s[34:35], 0, v[140:141]
	s_add_i32 m0, s31, 0xe000
	s_nop 0
	global_load_lds_dwordx4 v[216:217], off
	s_waitcnt vmcnt(8)
	s_waitcnt lgkmcnt(0)
	s_barrier
	s_waitcnt lgkmcnt(0)
	v_mfma_f32_16x16x32_bf16 v[124:127], v[152:155], v[184:187], v[124:127]
	v_mfma_f32_16x16x32_bf16 v[120:123], v[160:163], v[184:187], v[120:123]
	v_mfma_f32_16x16x32_bf16 v[108:111], v[152:155], v[192:195], v[108:111]
	v_mfma_f32_16x16x32_bf16 v[104:107], v[160:163], v[192:195], v[104:107]
	v_mfma_f32_16x16x32_bf16 v[92:95], v[152:155], v[200:203], v[92:95]
	v_mfma_f32_16x16x32_bf16 v[88:91], v[160:163], v[200:203], v[88:91]
	v_mfma_f32_16x16x32_bf16 v[76:79], v[152:155], v[208:211], v[76:79]
	v_mfma_f32_16x16x32_bf16 v[72:75], v[160:163], v[208:211], v[72:75]
	v_mfma_f32_16x16x32_bf16 v[124:127], v[156:159], v[188:191], v[124:127]
	v_mfma_f32_16x16x32_bf16 v[120:123], v[164:167], v[188:191], v[120:123]
	v_mfma_f32_16x16x32_bf16 v[108:111], v[156:159], v[196:199], v[108:111]
	v_mfma_f32_16x16x32_bf16 v[104:107], v[164:167], v[196:199], v[104:107]
	v_mfma_f32_16x16x32_bf16 v[92:95], v[156:159], v[204:207], v[92:95]
	v_mfma_f32_16x16x32_bf16 v[88:91], v[164:167], v[204:207], v[88:91]
	v_mfma_f32_16x16x32_bf16 v[76:79], v[156:159], v[212:215], v[76:79]
	v_mfma_f32_16x16x32_bf16 v[72:75], v[164:167], v[212:215], v[72:75]
	v_mfma_f32_16x16x32_bf16 v[116:119], v[168:171], v[184:187], v[116:119]
	v_mfma_f32_16x16x32_bf16 v[112:115], v[176:179], v[184:187], v[112:115]
	v_mfma_f32_16x16x32_bf16 v[100:103], v[168:171], v[192:195], v[100:103]
	v_mfma_f32_16x16x32_bf16 v[96:99], v[176:179], v[192:195], v[96:99]
	v_mfma_f32_16x16x32_bf16 v[84:87], v[168:171], v[200:203], v[84:87]
	v_mfma_f32_16x16x32_bf16 v[80:83], v[176:179], v[200:203], v[80:83]
	v_mfma_f32_16x16x32_bf16 v[68:71], v[168:171], v[208:211], v[68:71]
	v_mfma_f32_16x16x32_bf16 v[64:67], v[176:179], v[208:211], v[64:67]
	v_mfma_f32_16x16x32_bf16 v[116:119], v[172:175], v[188:191], v[116:119]
	v_mfma_f32_16x16x32_bf16 v[112:115], v[180:183], v[188:191], v[112:115]
	v_mfma_f32_16x16x32_bf16 v[100:103], v[172:175], v[196:199], v[100:103]
	v_mfma_f32_16x16x32_bf16 v[96:99], v[180:183], v[196:199], v[96:99]
	v_mfma_f32_16x16x32_bf16 v[84:87], v[172:175], v[204:207], v[84:87]
	v_mfma_f32_16x16x32_bf16 v[80:83], v[180:183], v[204:207], v[80:83]
	v_mfma_f32_16x16x32_bf16 v[68:71], v[172:175], v[212:215], v[68:71]
	v_mfma_f32_16x16x32_bf16 v[64:67], v[180:183], v[212:215], v[64:67]
	s_barrier
	s_add_i32 s33, s50, s40
	v_lshl_add_u64 v[216:217], s[36:37], 0, v[132:133]
	s_mov_b32 m0, s33
	ds_read_b128 v[184:187], v150 offset:16384
	ds_read_b128 v[188:191], v150 offset:17408
	ds_read_b128 v[192:195], v150 offset:18432
	ds_read_b128 v[196:199], v150 offset:19456
	ds_read_b128 v[200:203], v150 offset:20480
	ds_read_b128 v[204:207], v150 offset:21504
	ds_read_b128 v[208:211], v150 offset:22528
	ds_read_b128 v[212:215], v150 offset:23552
	global_load_lds_dwordx4 v[216:217], off
	s_add_i32 m0, s33, 0x2000
	s_add_u32 s60, s36, 0x80000
	v_lshl_add_u64 v[218:219], s[36:37], 0, v[136:137]
	s_addc_u32 s61, s37, 0
	s_add_i32 s33, s51, s40
	global_load_lds_dwordx4 v[218:219], off
	v_lshl_add_u64 v[222:223], s[60:61], 0, v[132:133]
	s_mov_b32 m0, s33
	v_lshl_add_u64 v[224:225], s[38:39], 0, v[134:135]
	global_load_lds_dwordx4 v[222:223], off
	v_lshl_add_u64 v[222:223], s[60:61], 0, v[136:137]
	s_add_i32 m0, s33, 0x2000
	s_nop 0
	global_load_lds_dwordx4 v[222:223], off
	v_lshl_add_u64 v[222:223], s[38:39], 0, v[130:131]
	s_mov_b32 m0, s31
	s_nop 0
	global_load_lds_dwordx4 v[222:223], off
	s_mov_b32 m0, s43
	s_nop 0
	global_load_lds_dwordx4 v[224:225], off
	s_waitcnt vmcnt(8)
	s_waitcnt lgkmcnt(0)
	s_barrier
	s_waitcnt lgkmcnt(0)
	v_mfma_f32_16x16x32_bf16 v[60:63], v[152:155], v[184:187], v[60:63]
	v_mfma_f32_16x16x32_bf16 v[56:59], v[160:163], v[184:187], v[56:59]
	v_mfma_f32_16x16x32_bf16 v[44:47], v[152:155], v[192:195], v[44:47]
	v_mfma_f32_16x16x32_bf16 v[40:43], v[160:163], v[192:195], v[40:43]
	v_mfma_f32_16x16x32_bf16 v[28:31], v[152:155], v[200:203], v[28:31]
	v_mfma_f32_16x16x32_bf16 v[24:27], v[160:163], v[200:203], v[24:27]
	v_mfma_f32_16x16x32_bf16 v[12:15], v[152:155], v[208:211], v[12:15]
	v_mfma_f32_16x16x32_bf16 v[8:11], v[160:163], v[208:211], v[8:11]
	v_mfma_f32_16x16x32_bf16 v[60:63], v[156:159], v[188:191], v[60:63]
	v_mfma_f32_16x16x32_bf16 v[56:59], v[164:167], v[188:191], v[56:59]
	v_mfma_f32_16x16x32_bf16 v[44:47], v[156:159], v[196:199], v[44:47]
	v_mfma_f32_16x16x32_bf16 v[40:43], v[164:167], v[196:199], v[40:43]
	v_mfma_f32_16x16x32_bf16 v[28:31], v[156:159], v[204:207], v[28:31]
	v_mfma_f32_16x16x32_bf16 v[24:27], v[164:167], v[204:207], v[24:27]
	v_mfma_f32_16x16x32_bf16 v[12:15], v[156:159], v[212:215], v[12:15]
	v_mfma_f32_16x16x32_bf16 v[8:11], v[164:167], v[212:215], v[8:11]
	v_mfma_f32_16x16x32_bf16 v[52:55], v[168:171], v[184:187], v[52:55]
	v_mfma_f32_16x16x32_bf16 v[48:51], v[176:179], v[184:187], v[48:51]
	v_mfma_f32_16x16x32_bf16 v[36:39], v[168:171], v[192:195], v[36:39]
	v_mfma_f32_16x16x32_bf16 v[32:35], v[176:179], v[192:195], v[32:35]
	v_mfma_f32_16x16x32_bf16 v[20:23], v[168:171], v[200:203], v[20:23]
	v_mfma_f32_16x16x32_bf16 v[16:19], v[176:179], v[200:203], v[16:19]
	v_mfma_f32_16x16x32_bf16 v[4:7], v[168:171], v[208:211], v[4:7]
	v_mfma_f32_16x16x32_bf16 v[0:3], v[176:179], v[208:211], v[0:3]
	v_mfma_f32_16x16x32_bf16 v[52:55], v[172:175], v[188:191], v[52:55]
	v_mfma_f32_16x16x32_bf16 v[48:51], v[180:183], v[188:191], v[48:51]
	v_mfma_f32_16x16x32_bf16 v[36:39], v[172:175], v[196:199], v[36:39]
	v_mfma_f32_16x16x32_bf16 v[32:35], v[180:183], v[196:199], v[32:35]
	v_mfma_f32_16x16x32_bf16 v[20:23], v[172:175], v[204:207], v[20:23]
	v_mfma_f32_16x16x32_bf16 v[16:19], v[180:183], v[204:207], v[16:19]
	v_mfma_f32_16x16x32_bf16 v[4:7], v[172:175], v[212:215], v[4:7]
	v_mfma_f32_16x16x32_bf16 v[0:3], v[180:183], v[212:215], v[0:3]
	s_barrier
	s_add_i32 s33, 0, 0x18000
	v_add_u32_e32 v151, s33, v146
	s_add_i32 s59, 0, 0x1c000
	ds_read_b128 v[152:155], v151
	ds_read_b128 v[156:159], v151 offset:1024
	ds_read_b128 v[160:163], v151 offset:2048
	ds_read_b128 v[164:167], v151 offset:3072
	v_add_u32_e32 v151, s59, v146
	ds_read_b128 v[168:171], v151
	ds_read_b128 v[172:175], v151 offset:1024
	ds_read_b128 v[176:179], v151 offset:2048
	ds_read_b128 v[180:183], v151 offset:3072
	s_add_u32 s38, s38, 0x80000
	s_addc_u32 s39, s39, 0
	s_mov_b32 m0, s44
	v_lshl_add_u64 v[226:227], s[38:39], 0, v[130:131]
	ds_read_b128 v[184:187], v150 offset:32768
	ds_read_b128 v[188:191], v150 offset:33792
	ds_read_b128 v[192:195], v150 offset:34816
	ds_read_b128 v[196:199], v150 offset:35840
	ds_read_b128 v[200:203], v150 offset:36864
	ds_read_b128 v[204:207], v150 offset:37888
	ds_read_b128 v[208:211], v150 offset:38912
	ds_read_b128 v[212:215], v150 offset:39936
	global_load_lds_dwordx4 v[226:227], off
	v_lshl_add_u64 v[226:227], s[38:39], 0, v[134:135]
	s_mov_b32 m0, s45
	s_nop 0
	global_load_lds_dwordx4 v[226:227], off
	s_waitcnt vmcnt(8)
	s_waitcnt lgkmcnt(0)
	s_barrier
	s_waitcnt lgkmcnt(0)
	v_mfma_f32_16x16x32_bf16 v[124:127], v[152:155], v[184:187], v[124:127]
	v_mfma_f32_16x16x32_bf16 v[120:123], v[160:163], v[184:187], v[120:123]
	v_mfma_f32_16x16x32_bf16 v[108:111], v[152:155], v[192:195], v[108:111]
	v_mfma_f32_16x16x32_bf16 v[104:107], v[160:163], v[192:195], v[104:107]
	v_mfma_f32_16x16x32_bf16 v[92:95], v[152:155], v[200:203], v[92:95]
	v_mfma_f32_16x16x32_bf16 v[88:91], v[160:163], v[200:203], v[88:91]
	v_mfma_f32_16x16x32_bf16 v[76:79], v[152:155], v[208:211], v[76:79]
	v_mfma_f32_16x16x32_bf16 v[72:75], v[160:163], v[208:211], v[72:75]
	v_mfma_f32_16x16x32_bf16 v[124:127], v[156:159], v[188:191], v[124:127]
	v_mfma_f32_16x16x32_bf16 v[120:123], v[164:167], v[188:191], v[120:123]
	v_mfma_f32_16x16x32_bf16 v[108:111], v[156:159], v[196:199], v[108:111]
	v_mfma_f32_16x16x32_bf16 v[104:107], v[164:167], v[196:199], v[104:107]
	v_mfma_f32_16x16x32_bf16 v[92:95], v[156:159], v[204:207], v[92:95]
	v_mfma_f32_16x16x32_bf16 v[88:91], v[164:167], v[204:207], v[88:91]
	v_mfma_f32_16x16x32_bf16 v[76:79], v[156:159], v[212:215], v[76:79]
	v_mfma_f32_16x16x32_bf16 v[72:75], v[164:167], v[212:215], v[72:75]
	v_mfma_f32_16x16x32_bf16 v[116:119], v[168:171], v[184:187], v[116:119]
	v_mfma_f32_16x16x32_bf16 v[112:115], v[176:179], v[184:187], v[112:115]
	v_mfma_f32_16x16x32_bf16 v[100:103], v[168:171], v[192:195], v[100:103]
	v_mfma_f32_16x16x32_bf16 v[96:99], v[176:179], v[192:195], v[96:99]
	v_mfma_f32_16x16x32_bf16 v[84:87], v[168:171], v[200:203], v[84:87]
	v_mfma_f32_16x16x32_bf16 v[80:83], v[176:179], v[200:203], v[80:83]
	v_mfma_f32_16x16x32_bf16 v[68:71], v[168:171], v[208:211], v[68:71]
	v_mfma_f32_16x16x32_bf16 v[64:67], v[176:179], v[208:211], v[64:67]
	v_mfma_f32_16x16x32_bf16 v[116:119], v[172:175], v[188:191], v[116:119]
	v_mfma_f32_16x16x32_bf16 v[112:115], v[180:183], v[188:191], v[112:115]
	v_mfma_f32_16x16x32_bf16 v[100:103], v[172:175], v[196:199], v[100:103]
	v_mfma_f32_16x16x32_bf16 v[96:99], v[180:183], v[196:199], v[96:99]
	v_mfma_f32_16x16x32_bf16 v[84:87], v[172:175], v[204:207], v[84:87]
	v_mfma_f32_16x16x32_bf16 v[80:83], v[180:183], v[204:207], v[80:83]
	v_mfma_f32_16x16x32_bf16 v[68:71], v[172:175], v[212:215], v[68:71]
	v_mfma_f32_16x16x32_bf16 v[64:67], v[180:183], v[212:215], v[64:67]
	s_barrier
	s_add_i32 s33, s33, s40
	v_lshl_add_u64 v[216:217], v[216:217], 0, s[8:9]
	s_mov_b32 m0, s33
	ds_read_b128 v[184:187], v150 offset:49152
	ds_read_b128 v[188:191], v150 offset:50176
	ds_read_b128 v[192:195], v150 offset:51200
	ds_read_b128 v[196:199], v150 offset:52224
	ds_read_b128 v[200:203], v150 offset:53248
	ds_read_b128 v[204:207], v150 offset:54272
	ds_read_b128 v[208:211], v150 offset:55296
	ds_read_b128 v[212:215], v150 offset:56320
	global_load_lds_dwordx4 v[216:217], off
	s_add_i32 m0, s33, 0x2000
	s_add_u32 s36, s36, 0x80080
	v_lshl_add_u64 v[216:217], v[218:219], 0, s[8:9]
	s_addc_u32 s37, s37, 0
	s_add_i32 s33, s59, s40
	global_load_lds_dwordx4 v[216:217], off
	v_lshl_add_u64 v[216:217], s[36:37], 0, v[132:133]
	s_mov_b32 m0, s33
	s_nop 0
	global_load_lds_dwordx4 v[216:217], off
	v_lshl_add_u64 v[216:217], s[36:37], 0, v[136:137]
	s_add_i32 m0, s33, 0x2000
	s_nop 0
	global_load_lds_dwordx4 v[216:217], off
	v_lshl_add_u64 v[216:217], v[222:223], 0, s[8:9]
	s_mov_b32 m0, s48
	s_nop 0
	global_load_lds_dwordx4 v[216:217], off
	v_lshl_add_u64 v[216:217], v[224:225], 0, s[8:9]
	s_mov_b32 m0, s49
	s_nop 0
	global_load_lds_dwordx4 v[216:217], off
	s_waitcnt vmcnt(8)
	s_waitcnt lgkmcnt(0)
	s_barrier
	s_waitcnt lgkmcnt(0)
	v_mfma_f32_16x16x32_bf16 v[60:63], v[152:155], v[184:187], v[60:63]
	v_mfma_f32_16x16x32_bf16 v[56:59], v[160:163], v[184:187], v[56:59]
	v_mfma_f32_16x16x32_bf16 v[44:47], v[152:155], v[192:195], v[44:47]
	v_mfma_f32_16x16x32_bf16 v[40:43], v[160:163], v[192:195], v[40:43]
	v_mfma_f32_16x16x32_bf16 v[28:31], v[152:155], v[200:203], v[28:31]
	v_mfma_f32_16x16x32_bf16 v[24:27], v[160:163], v[200:203], v[24:27]
	v_mfma_f32_16x16x32_bf16 v[12:15], v[152:155], v[208:211], v[12:15]
	v_mfma_f32_16x16x32_bf16 v[8:11], v[160:163], v[208:211], v[8:11]
	v_mfma_f32_16x16x32_bf16 v[60:63], v[156:159], v[188:191], v[60:63]
	v_mfma_f32_16x16x32_bf16 v[56:59], v[164:167], v[188:191], v[56:59]
	v_mfma_f32_16x16x32_bf16 v[44:47], v[156:159], v[196:199], v[44:47]
	v_mfma_f32_16x16x32_bf16 v[40:43], v[164:167], v[196:199], v[40:43]
	v_mfma_f32_16x16x32_bf16 v[28:31], v[156:159], v[204:207], v[28:31]
	v_mfma_f32_16x16x32_bf16 v[24:27], v[164:167], v[204:207], v[24:27]
	v_mfma_f32_16x16x32_bf16 v[12:15], v[156:159], v[212:215], v[12:15]
	v_mfma_f32_16x16x32_bf16 v[8:11], v[164:167], v[212:215], v[8:11]
	v_mfma_f32_16x16x32_bf16 v[52:55], v[168:171], v[184:187], v[52:55]
	v_mfma_f32_16x16x32_bf16 v[48:51], v[176:179], v[184:187], v[48:51]
	v_mfma_f32_16x16x32_bf16 v[36:39], v[168:171], v[192:195], v[36:39]
	v_mfma_f32_16x16x32_bf16 v[32:35], v[176:179], v[192:195], v[32:35]
	v_mfma_f32_16x16x32_bf16 v[20:23], v[168:171], v[200:203], v[20:23]
	v_mfma_f32_16x16x32_bf16 v[16:19], v[176:179], v[200:203], v[16:19]
	v_mfma_f32_16x16x32_bf16 v[4:7], v[168:171], v[208:211], v[4:7]
	v_mfma_f32_16x16x32_bf16 v[0:3], v[176:179], v[208:211], v[0:3]
	v_mfma_f32_16x16x32_bf16 v[52:55], v[172:175], v[188:191], v[52:55]
	v_mfma_f32_16x16x32_bf16 v[48:51], v[180:183], v[188:191], v[48:51]
	v_mfma_f32_16x16x32_bf16 v[36:39], v[172:175], v[196:199], v[36:39]
	v_mfma_f32_16x16x32_bf16 v[32:35], v[180:183], v[196:199], v[32:35]
	v_mfma_f32_16x16x32_bf16 v[20:23], v[172:175], v[204:207], v[20:23]
	v_mfma_f32_16x16x32_bf16 v[16:19], v[180:183], v[204:207], v[16:19]
	v_mfma_f32_16x16x32_bf16 v[4:7], v[172:175], v[212:215], v[4:7]
	v_mfma_f32_16x16x32_bf16 v[0:3], v[180:183], v[212:215], v[0:3]
	s_barrier
	s_add_i32 s58, s58, 2
	s_add_u32 s34, s34, 0x100
	s_addc_u32 s35, s35, 0
	s_add_u32 s56, s56, 0x100
	s_addc_u32 s57, s57, 0
	s_cmp_gt_u32 s58, 29
	s_cbranch_scc0 .LBB0_49
	s_and_b64 vcc, exec, s[10:11]
	s_cbranch_vccz .LBB0_52
	s_barrier

.LBB0_111:
	ds_read_b128 v[140:143], v149
	ds_read_b128 v[152:155], v149 offset:1024
	ds_read_b128 v[156:159], v149 offset:2048
	ds_read_b128 v[160:163], v149 offset:3072
	ds_read_b128 v[164:167], v150
	ds_read_b128 v[168:171], v150 offset:1024
	ds_read_b128 v[172:175], v150 offset:2048
	ds_read_b128 v[176:179], v150 offset:3072
	s_add_u32 s28, s24, 0xffea0080
	s_addc_u32 s29, s25, -1
	s_cmpk_eq_i32 s52, 0x54
	s_cselect_b32 s31, s3, s29
	s_cselect_b32 s30, s2, s28
	s_cselect_b32 s29, s19, s51
	s_cselect_b32 s28, s18, s50
	v_lshl_add_u64 v[144:145], s[24:25], 0, v[132:133]
	s_add_i32 m0, s36, 0xc000
	ds_read_b128 v[180:183], v151
	ds_read_b128 v[184:187], v151 offset:1024
	ds_read_b128 v[188:191], v151 offset:2048
	ds_read_b128 v[192:195], v151 offset:3072
	ds_read_b128 v[196:199], v151 offset:4096
	ds_read_b128 v[200:203], v151 offset:5120
	ds_read_b128 v[204:207], v151 offset:6144
	ds_read_b128 v[208:211], v151 offset:7168
	global_load_lds_dwordx4 v[144:145], off
	v_lshl_add_u64 v[144:145], s[24:25], 0, v[134:135]
	s_add_i32 m0, s36, 0xe000
	s_nop 0
	global_load_lds_dwordx4 v[144:145], off
	s_waitcnt vmcnt(8)
	s_waitcnt lgkmcnt(0)
	s_barrier
	s_waitcnt lgkmcnt(0)
	v_mfma_f32_16x16x32_bf16 v[124:127], v[140:143], v[180:183], v[124:127]
	v_mfma_f32_16x16x32_bf16 v[120:123], v[156:159], v[180:183], v[120:123]
	v_mfma_f32_16x16x32_bf16 v[108:111], v[140:143], v[188:191], v[108:111]
	v_mfma_f32_16x16x32_bf16 v[104:107], v[156:159], v[188:191], v[104:107]
	v_mfma_f32_16x16x32_bf16 v[92:95], v[140:143], v[196:199], v[92:95]
	v_mfma_f32_16x16x32_bf16 v[88:91], v[156:159], v[196:199], v[88:91]
	v_mfma_f32_16x16x32_bf16 v[76:79], v[140:143], v[204:207], v[76:79]
	v_mfma_f32_16x16x32_bf16 v[72:75], v[156:159], v[204:207], v[72:75]
	v_mfma_f32_16x16x32_bf16 v[124:127], v[152:155], v[184:187], v[124:127]
	v_mfma_f32_16x16x32_bf16 v[120:123], v[160:163], v[184:187], v[120:123]
	v_mfma_f32_16x16x32_bf16 v[108:111], v[152:155], v[192:195], v[108:111]
	v_mfma_f32_16x16x32_bf16 v[104:107], v[160:163], v[192:195], v[104:107]
	v_mfma_f32_16x16x32_bf16 v[92:95], v[152:155], v[200:203], v[92:95]
	v_mfma_f32_16x16x32_bf16 v[88:91], v[160:163], v[200:203], v[88:91]
	v_mfma_f32_16x16x32_bf16 v[76:79], v[152:155], v[208:211], v[76:79]
	v_mfma_f32_16x16x32_bf16 v[72:75], v[160:163], v[208:211], v[72:75]
	v_mfma_f32_16x16x32_bf16 v[116:119], v[164:167], v[180:183], v[116:119]
	v_mfma_f32_16x16x32_bf16 v[112:115], v[172:175], v[180:183], v[112:115]
	v_mfma_f32_16x16x32_bf16 v[100:103], v[164:167], v[188:191], v[100:103]
	v_mfma_f32_16x16x32_bf16 v[96:99], v[172:175], v[188:191], v[96:99]
	v_mfma_f32_16x16x32_bf16 v[84:87], v[164:167], v[196:199], v[84:87]
	v_mfma_f32_16x16x32_bf16 v[80:83], v[172:175], v[196:199], v[80:83]
	v_mfma_f32_16x16x32_bf16 v[68:71], v[164:167], v[204:207], v[68:71]
	v_mfma_f32_16x16x32_bf16 v[64:67], v[172:175], v[204:207], v[64:67]
	v_mfma_f32_16x16x32_bf16 v[116:119], v[168:171], v[184:187], v[116:119]
	v_mfma_f32_16x16x32_bf16 v[112:115], v[176:179], v[184:187], v[112:115]
	v_mfma_f32_16x16x32_bf16 v[100:103], v[168:171], v[192:195], v[100:103]
	v_mfma_f32_16x16x32_bf16 v[96:99], v[176:179], v[192:195], v[96:99]
	v_mfma_f32_16x16x32_bf16 v[84:87], v[168:171], v[200:203], v[84:87]
	v_mfma_f32_16x16x32_bf16 v[80:83], v[176:179], v[200:203], v[80:83]
	v_mfma_f32_16x16x32_bf16 v[68:71], v[168:171], v[208:211], v[68:71]
	v_mfma_f32_16x16x32_bf16 v[64:67], v[176:179], v[208:211], v[64:67]
	s_barrier
	s_add_i32 s33, s44, s35
	v_lshl_add_u64 v[144:145], s[28:29], 0, v[128:129]
	s_mov_b32 m0, s33
	ds_read_b128 v[180:183], v151 offset:16384
	ds_read_b128 v[184:187], v151 offset:17408
	ds_read_b128 v[188:191], v151 offset:18432
	ds_read_b128 v[192:195], v151 offset:19456
	ds_read_b128 v[196:199], v151 offset:20480
	ds_read_b128 v[200:203], v151 offset:21504
	ds_read_b128 v[204:207], v151 offset:22528
	ds_read_b128 v[208:211], v151 offset:23552
	global_load_lds_dwordx4 v[144:145], off
	s_add_i32 m0, s33, 0x2000
	s_add_u32 s54, s28, 0x160000
	v_lshl_add_u64 v[212:213], s[28:29], 0, v[130:131]
	s_addc_u32 s55, s29, 0
	s_add_i32 s33, s45, s35
	global_load_lds_dwordx4 v[212:213], off
	v_lshl_add_u64 v[214:215], s[54:55], 0, v[128:129]
	s_mov_b32 m0, s33
	v_lshl_add_u64 v[216:217], s[30:31], 0, v[130:131]
	global_load_lds_dwordx4 v[214:215], off
	v_lshl_add_u64 v[214:215], s[54:55], 0, v[130:131]
	s_add_i32 m0, s33, 0x2000
	s_nop 0
	global_load_lds_dwordx4 v[214:215], off
	v_lshl_add_u64 v[214:215], s[30:31], 0, v[128:129]
	s_mov_b32 m0, s36
	s_nop 0
	global_load_lds_dwordx4 v[214:215], off
	s_mov_b32 m0, s37
	s_nop 0
	global_load_lds_dwordx4 v[216:217], off
	s_waitcnt vmcnt(8)
	s_waitcnt lgkmcnt(0)
	s_barrier
	s_waitcnt lgkmcnt(0)
	v_mfma_f32_16x16x32_bf16 v[60:63], v[140:143], v[180:183], v[60:63]
	v_mfma_f32_16x16x32_bf16 v[56:59], v[156:159], v[180:183], v[56:59]
	v_mfma_f32_16x16x32_bf16 v[44:47], v[140:143], v[188:191], v[44:47]
	v_mfma_f32_16x16x32_bf16 v[40:43], v[156:159], v[188:191], v[40:43]
	v_mfma_f32_16x16x32_bf16 v[28:31], v[140:143], v[196:199], v[28:31]
	v_mfma_f32_16x16x32_bf16 v[24:27], v[156:159], v[196:199], v[24:27]
	v_mfma_f32_16x16x32_bf16 v[12:15], v[140:143], v[204:207], v[12:15]
	v_mfma_f32_16x16x32_bf16 v[8:11], v[156:159], v[204:207], v[8:11]
	v_mfma_f32_16x16x32_bf16 v[60:63], v[152:155], v[184:187], v[60:63]
	v_mfma_f32_16x16x32_bf16 v[56:59], v[160:163], v[184:187], v[56:59]
	v_mfma_f32_16x16x32_bf16 v[44:47], v[152:155], v[192:195], v[44:47]
	v_mfma_f32_16x16x32_bf16 v[40:43], v[160:163], v[192:195], v[40:43]
	v_mfma_f32_16x16x32_bf16 v[28:31], v[152:155], v[200:203], v[28:31]
	v_mfma_f32_16x16x32_bf16 v[24:27], v[160:163], v[200:203], v[24:27]
	v_mfma_f32_16x16x32_bf16 v[12:15], v[152:155], v[208:211], v[12:15]
	v_mfma_f32_16x16x32_bf16 v[8:11], v[160:163], v[208:211], v[8:11]
	v_mfma_f32_16x16x32_bf16 v[52:55], v[164:167], v[180:183], v[52:55]
	v_mfma_f32_16x16x32_bf16 v[48:51], v[172:175], v[180:183], v[48:51]
	v_mfma_f32_16x16x32_bf16 v[36:39], v[164:167], v[188:191], v[36:39]
	v_mfma_f32_16x16x32_bf16 v[32:35], v[172:175], v[188:191], v[32:35]
	v_mfma_f32_16x16x32_bf16 v[20:23], v[164:167], v[196:199], v[20:23]
	v_mfma_f32_16x16x32_bf16 v[16:19], v[172:175], v[196:199], v[16:19]
	v_mfma_f32_16x16x32_bf16 v[4:7], v[164:167], v[204:207], v[4:7]
	v_mfma_f32_16x16x32_bf16 v[0:3], v[172:175], v[204:207], v[0:3]
	v_mfma_f32_16x16x32_bf16 v[52:55], v[168:171], v[184:187], v[52:55]
	v_mfma_f32_16x16x32_bf16 v[48:51], v[176:179], v[184:187], v[48:51]
	v_mfma_f32_16x16x32_bf16 v[36:39], v[168:171], v[192:195], v[36:39]
	v_mfma_f32_16x16x32_bf16 v[32:35], v[176:179], v[192:195], v[32:35]
	v_mfma_f32_16x16x32_bf16 v[20:23], v[168:171], v[200:203], v[20:23]
	v_mfma_f32_16x16x32_bf16 v[16:19], v[176:179], v[200:203], v[16:19]
	v_mfma_f32_16x16x32_bf16 v[4:7], v[168:171], v[208:211], v[4:7]
	v_mfma_f32_16x16x32_bf16 v[0:3], v[176:179], v[208:211], v[0:3]
	s_barrier
	s_add_i32 s33, 0, 0x18000
	s_add_i32 s53, 0, 0x1c000
	v_add_u32_e32 v160, s33, v147
	v_add_u32_e32 v176, s53, v147
	ds_read_b128 v[140:143], v160
	ds_read_b128 v[152:155], v160 offset:1024
	ds_read_b128 v[156:159], v160 offset:2048
	ds_read_b128 v[160:163], v160 offset:3072
	ds_read_b128 v[164:167], v176
	ds_read_b128 v[168:171], v176 offset:1024
	ds_read_b128 v[172:175], v176 offset:2048
	ds_read_b128 v[176:179], v176 offset:3072
	s_add_u32 s30, s30, 0x160000
	s_addc_u32 s31, s31, 0
	s_mov_b32 m0, s38
	v_lshl_add_u64 v[218:219], s[30:31], 0, v[128:129]
	ds_read_b128 v[180:183], v151 offset:32768
	ds_read_b128 v[184:187], v151 offset:33792
	ds_read_b128 v[188:191], v151 offset:34816
	ds_read_b128 v[192:195], v151 offset:35840
	ds_read_b128 v[196:199], v151 offset:36864
	ds_read_b128 v[200:203], v151 offset:37888
	ds_read_b128 v[204:207], v151 offset:38912
	ds_read_b128 v[208:211], v151 offset:39936
	global_load_lds_dwordx4 v[218:219], off
	v_lshl_add_u64 v[218:219], s[30:31], 0, v[130:131]
	s_mov_b32 m0, s39
	s_nop 0
	global_load_lds_dwordx4 v[218:219], off
	s_waitcnt vmcnt(8)
	s_waitcnt lgkmcnt(0)
	s_barrier
	s_waitcnt lgkmcnt(0)
	v_mfma_f32_16x16x32_bf16 v[124:127], v[140:143], v[180:183], v[124:127]
	v_mfma_f32_16x16x32_bf16 v[120:123], v[156:159], v[180:183], v[120:123]
	v_mfma_f32_16x16x32_bf16 v[108:111], v[140:143], v[188:191], v[108:111]
	v_mfma_f32_16x16x32_bf16 v[104:107], v[156:159], v[188:191], v[104:107]
	v_mfma_f32_16x16x32_bf16 v[92:95], v[140:143], v[196:199], v[92:95]
	v_mfma_f32_16x16x32_bf16 v[88:91], v[156:159], v[196:199], v[88:91]
	v_mfma_f32_16x16x32_bf16 v[76:79], v[140:143], v[204:207], v[76:79]
	v_mfma_f32_16x16x32_bf16 v[72:75], v[156:159], v[204:207], v[72:75]
	v_mfma_f32_16x16x32_bf16 v[124:127], v[152:155], v[184:187], v[124:127]
	v_mfma_f32_16x16x32_bf16 v[120:123], v[160:163], v[184:187], v[120:123]
	v_mfma_f32_16x16x32_bf16 v[108:111], v[152:155], v[192:195], v[108:111]
	v_mfma_f32_16x16x32_bf16 v[104:107], v[160:163], v[192:195], v[104:107]
	v_mfma_f32_16x16x32_bf16 v[92:95], v[152:155], v[200:203], v[92:95]
	v_mfma_f32_16x16x32_bf16 v[88:91], v[160:163], v[200:203], v[88:91]
	v_mfma_f32_16x16x32_bf16 v[76:79], v[152:155], v[208:211], v[76:79]
	v_mfma_f32_16x16x32_bf16 v[72:75], v[160:163], v[208:211], v[72:75]
	v_mfma_f32_16x16x32_bf16 v[116:119], v[164:167], v[180:183], v[116:119]
	v_mfma_f32_16x16x32_bf16 v[112:115], v[172:175], v[180:183], v[112:115]
	v_mfma_f32_16x16x32_bf16 v[100:103], v[164:167], v[188:191], v[100:103]
	v_mfma_f32_16x16x32_bf16 v[96:99], v[172:175], v[188:191], v[96:99]
	v_mfma_f32_16x16x32_bf16 v[84:87], v[164:167], v[196:199], v[84:87]
	v_mfma_f32_16x16x32_bf16 v[80:83], v[172:175], v[196:199], v[80:83]
	v_mfma_f32_16x16x32_bf16 v[68:71], v[164:167], v[204:207], v[68:71]
	v_mfma_f32_16x16x32_bf16 v[64:67], v[172:175], v[204:207], v[64:67]
	v_mfma_f32_16x16x32_bf16 v[116:119], v[168:171], v[184:187], v[116:119]
	v_mfma_f32_16x16x32_bf16 v[112:115], v[176:179], v[184:187], v[112:115]
	v_mfma_f32_16x16x32_bf16 v[100:103], v[168:171], v[192:195], v[100:103]
	v_mfma_f32_16x16x32_bf16 v[96:99], v[176:179], v[192:195], v[96:99]
	v_mfma_f32_16x16x32_bf16 v[84:87], v[168:171], v[200:203], v[84:87]
	v_mfma_f32_16x16x32_bf16 v[80:83], v[176:179], v[200:203], v[80:83]
	v_mfma_f32_16x16x32_bf16 v[68:71], v[168:171], v[208:211], v[68:71]
	v_mfma_f32_16x16x32_bf16 v[64:67], v[176:179], v[208:211], v[64:67]
	s_barrier
	s_add_i32 s30, s33, s35
	v_lshl_add_u64 v[144:145], v[144:145], 0, s[10:11]
	s_mov_b32 m0, s30
	ds_read_b128 v[180:183], v151 offset:49152
	ds_read_b128 v[184:187], v151 offset:50176
	ds_read_b128 v[188:191], v151 offset:51200
	ds_read_b128 v[192:195], v151 offset:52224
	ds_read_b128 v[196:199], v151 offset:53248
	ds_read_b128 v[200:203], v151 offset:54272
	ds_read_b128 v[204:207], v151 offset:55296
	ds_read_b128 v[208:211], v151 offset:56320
	global_load_lds_dwordx4 v[144:145], off
	s_add_i32 m0, s30, 0x2000
	s_add_u32 s28, s28, 0x160080
	v_lshl_add_u64 v[144:145], v[212:213], 0, s[10:11]
	s_addc_u32 s29, s29, 0
	s_add_i32 s30, s53, s35
	global_load_lds_dwordx4 v[144:145], off
	v_lshl_add_u64 v[144:145], s[28:29], 0, v[128:129]
	s_mov_b32 m0, s30
	s_nop 0
	global_load_lds_dwordx4 v[144:145], off
	v_lshl_add_u64 v[144:145], s[28:29], 0, v[130:131]
	s_add_i32 m0, s30, 0x2000
	s_nop 0
	global_load_lds_dwordx4 v[144:145], off
	v_lshl_add_u64 v[144:145], v[214:215], 0, s[10:11]
	s_mov_b32 m0, s41
	s_nop 0
	global_load_lds_dwordx4 v[144:145], off
	v_lshl_add_u64 v[144:145], v[216:217], 0, s[10:11]
	s_mov_b32 m0, s42
	s_nop 0
	global_load_lds_dwordx4 v[144:145], off
	s_waitcnt vmcnt(8)
	s_waitcnt lgkmcnt(0)
	s_barrier
	s_waitcnt lgkmcnt(0)
	v_mfma_f32_16x16x32_bf16 v[60:63], v[140:143], v[180:183], v[60:63]
	v_mfma_f32_16x16x32_bf16 v[56:59], v[156:159], v[180:183], v[56:59]
	v_mfma_f32_16x16x32_bf16 v[44:47], v[140:143], v[188:191], v[44:47]
	v_mfma_f32_16x16x32_bf16 v[40:43], v[156:159], v[188:191], v[40:43]
	v_mfma_f32_16x16x32_bf16 v[28:31], v[140:143], v[196:199], v[28:31]
	v_mfma_f32_16x16x32_bf16 v[24:27], v[156:159], v[196:199], v[24:27]
	v_mfma_f32_16x16x32_bf16 v[12:15], v[140:143], v[204:207], v[12:15]
	v_mfma_f32_16x16x32_bf16 v[8:11], v[156:159], v[204:207], v[8:11]
	v_mfma_f32_16x16x32_bf16 v[60:63], v[152:155], v[184:187], v[60:63]
	v_mfma_f32_16x16x32_bf16 v[56:59], v[160:163], v[184:187], v[56:59]
	v_mfma_f32_16x16x32_bf16 v[44:47], v[152:155], v[192:195], v[44:47]
	v_mfma_f32_16x16x32_bf16 v[40:43], v[160:163], v[192:195], v[40:43]
	v_mfma_f32_16x16x32_bf16 v[28:31], v[152:155], v[200:203], v[28:31]
	v_mfma_f32_16x16x32_bf16 v[24:27], v[160:163], v[200:203], v[24:27]
	v_mfma_f32_16x16x32_bf16 v[12:15], v[152:155], v[208:211], v[12:15]
	v_mfma_f32_16x16x32_bf16 v[8:11], v[160:163], v[208:211], v[8:11]
	v_mfma_f32_16x16x32_bf16 v[52:55], v[164:167], v[180:183], v[52:55]
	v_mfma_f32_16x16x32_bf16 v[48:51], v[172:175], v[180:183], v[48:51]
	v_mfma_f32_16x16x32_bf16 v[36:39], v[164:167], v[188:191], v[36:39]
	v_mfma_f32_16x16x32_bf16 v[32:35], v[172:175], v[188:191], v[32:35]
	v_mfma_f32_16x16x32_bf16 v[20:23], v[164:167], v[196:199], v[20:23]
	v_mfma_f32_16x16x32_bf16 v[16:19], v[172:175], v[196:199], v[16:19]
	v_mfma_f32_16x16x32_bf16 v[4:7], v[164:167], v[204:207], v[4:7]
	v_mfma_f32_16x16x32_bf16 v[0:3], v[172:175], v[204:207], v[0:3]
	v_mfma_f32_16x16x32_bf16 v[52:55], v[168:171], v[184:187], v[52:55]
	v_mfma_f32_16x16x32_bf16 v[48:51], v[176:179], v[184:187], v[48:51]
	v_mfma_f32_16x16x32_bf16 v[36:39], v[168:171], v[192:195], v[36:39]
	v_mfma_f32_16x16x32_bf16 v[32:35], v[176:179], v[192:195], v[32:35]
	v_mfma_f32_16x16x32_bf16 v[20:23], v[168:171], v[200:203], v[20:23]
	v_mfma_f32_16x16x32_bf16 v[16:19], v[176:179], v[200:203], v[16:19]
	v_mfma_f32_16x16x32_bf16 v[4:7], v[168:171], v[208:211], v[4:7]
	v_mfma_f32_16x16x32_bf16 v[0:3], v[176:179], v[208:211], v[0:3]
	s_barrier
	s_add_i32 s52, s52, 2
	s_add_u32 s24, s24, 0x100
	s_addc_u32 s25, s25, 0
	s_add_u32 s50, s50, 0x100
	s_addc_u32 s51, s51, 0
	s_cmpk_gt_u32 s52, 0x55
	s_cbranch_scc0 .LBB0_111
	s_and_b64 vcc, exec, s[14:15]
	s_cbranch_vccz .LBB0_114
	s_barrier

.LBB0_139:
	v_add_u32_e32 v147, s49, v145
	ds_read_b128 v[148:151], v147
	ds_read_b128 v[152:155], v147 offset:1024
	ds_read_b128 v[156:159], v147 offset:2048
	ds_read_b128 v[160:163], v147 offset:3072
	v_add_u32_e32 v147, s50, v145
	s_add_u32 s28, s10, s24
	ds_read_b128 v[164:167], v147
	ds_read_b128 v[168:171], v147 offset:1024
	ds_read_b128 v[172:175], v147 offset:2048
	ds_read_b128 v[176:179], v147 offset:3072
	s_addc_u32 s29, s11, s25
	s_add_u32 s28, s28, 0x100
	s_addc_u32 s29, s29, 0
	s_add_u32 s33, s17, s24
	s_addc_u32 s55, s53, s25
	s_cmpk_eq_i32 s24, 0x2b00
	s_cselect_b32 s31, s19, s29
	s_cselect_b32 s30, s18, s28
	s_cselect_b32 s29, s5, s55
	s_cselect_b32 s28, s4, s33
	v_lshl_add_u64 v[212:213], v[140:141], 0, s[24:25]
	s_add_i32 m0, s42, 0xc000
	ds_read_b128 v[180:183], v146
	ds_read_b128 v[184:187], v146 offset:1024
	ds_read_b128 v[188:191], v146 offset:2048
	ds_read_b128 v[192:195], v146 offset:3072
	ds_read_b128 v[196:199], v146 offset:4096
	ds_read_b128 v[200:203], v146 offset:5120
	ds_read_b128 v[204:207], v146 offset:6144
	ds_read_b128 v[208:211], v146 offset:7168
	global_load_lds_dwordx4 v[212:213], off
	v_lshl_add_u64 v[212:213], v[142:143], 0, s[24:25]
	s_add_i32 m0, s42, 0xe000
	s_nop 0
	global_load_lds_dwordx4 v[212:213], off
	s_waitcnt vmcnt(8)
	s_waitcnt lgkmcnt(0)
	s_barrier
	s_waitcnt lgkmcnt(0)
	v_mfma_f32_16x16x32_bf16 v[124:127], v[148:151], v[180:183], v[124:127]
	v_mfma_f32_16x16x32_bf16 v[120:123], v[156:159], v[180:183], v[120:123]
	v_mfma_f32_16x16x32_bf16 v[108:111], v[148:151], v[188:191], v[108:111]
	v_mfma_f32_16x16x32_bf16 v[104:107], v[156:159], v[188:191], v[104:107]
	v_mfma_f32_16x16x32_bf16 v[92:95], v[148:151], v[196:199], v[92:95]
	v_mfma_f32_16x16x32_bf16 v[88:91], v[156:159], v[196:199], v[88:91]
	v_mfma_f32_16x16x32_bf16 v[76:79], v[148:151], v[204:207], v[76:79]
	v_mfma_f32_16x16x32_bf16 v[72:75], v[156:159], v[204:207], v[72:75]
	v_mfma_f32_16x16x32_bf16 v[124:127], v[152:155], v[184:187], v[124:127]
	v_mfma_f32_16x16x32_bf16 v[120:123], v[160:163], v[184:187], v[120:123]
	v_mfma_f32_16x16x32_bf16 v[108:111], v[152:155], v[192:195], v[108:111]
	v_mfma_f32_16x16x32_bf16 v[104:107], v[160:163], v[192:195], v[104:107]
	v_mfma_f32_16x16x32_bf16 v[92:95], v[152:155], v[200:203], v[92:95]
	v_mfma_f32_16x16x32_bf16 v[88:91], v[160:163], v[200:203], v[88:91]
	v_mfma_f32_16x16x32_bf16 v[76:79], v[152:155], v[208:211], v[76:79]
	v_mfma_f32_16x16x32_bf16 v[72:75], v[160:163], v[208:211], v[72:75]
	v_mfma_f32_16x16x32_bf16 v[116:119], v[164:167], v[180:183], v[116:119]
	v_mfma_f32_16x16x32_bf16 v[112:115], v[172:175], v[180:183], v[112:115]
	v_mfma_f32_16x16x32_bf16 v[100:103], v[164:167], v[188:191], v[100:103]
	v_mfma_f32_16x16x32_bf16 v[96:99], v[172:175], v[188:191], v[96:99]
	v_mfma_f32_16x16x32_bf16 v[84:87], v[164:167], v[196:199], v[84:87]
	v_mfma_f32_16x16x32_bf16 v[80:83], v[172:175], v[196:199], v[80:83]
	v_mfma_f32_16x16x32_bf16 v[68:71], v[164:167], v[204:207], v[68:71]
	v_mfma_f32_16x16x32_bf16 v[64:67], v[172:175], v[204:207], v[64:67]
	v_mfma_f32_16x16x32_bf16 v[116:119], v[168:171], v[184:187], v[116:119]
	v_mfma_f32_16x16x32_bf16 v[112:115], v[176:179], v[184:187], v[112:115]
	v_mfma_f32_16x16x32_bf16 v[100:103], v[168:171], v[192:195], v[100:103]
	v_mfma_f32_16x16x32_bf16 v[96:99], v[176:179], v[192:195], v[96:99]
	v_mfma_f32_16x16x32_bf16 v[84:87], v[168:171], v[200:203], v[84:87]
	v_mfma_f32_16x16x32_bf16 v[80:83], v[176:179], v[200:203], v[80:83]
	v_mfma_f32_16x16x32_bf16 v[68:71], v[168:171], v[208:211], v[68:71]
	v_mfma_f32_16x16x32_bf16 v[64:67], v[176:179], v[208:211], v[64:67]
	s_barrier
	s_add_i32 s33, s49, s41
	v_lshl_add_u64 v[212:213], s[28:29], 0, v[128:129]
	s_mov_b32 m0, s33
	ds_read_b128 v[180:183], v146 offset:16384
	ds_read_b128 v[184:187], v146 offset:17408
	ds_read_b128 v[188:191], v146 offset:18432
	ds_read_b128 v[192:195], v146 offset:19456
	ds_read_b128 v[196:199], v146 offset:20480
	ds_read_b128 v[200:203], v146 offset:21504
	ds_read_b128 v[204:207], v146 offset:22528
	ds_read_b128 v[208:211], v146 offset:23552
	global_load_lds_dwordx4 v[212:213], off
	s_add_i32 m0, s33, 0x2000
	s_add_u32 s56, s28, 0x160000
	v_lshl_add_u64 v[214:215], s[28:29], 0, v[130:131]
	s_addc_u32 s57, s29, 0
	s_add_i32 s33, s50, s41
	global_load_lds_dwordx4 v[214:215], off
	v_lshl_add_u64 v[216:217], s[56:57], 0, v[128:129]
	s_mov_b32 m0, s33
	v_lshl_add_u64 v[218:219], s[30:31], 0, v[130:131]
	global_load_lds_dwordx4 v[216:217], off
	v_lshl_add_u64 v[216:217], s[56:57], 0, v[130:131]
	s_add_i32 m0, s33, 0x2000
	s_nop 0
	global_load_lds_dwordx4 v[216:217], off
	v_lshl_add_u64 v[216:217], s[30:31], 0, v[128:129]
	s_mov_b32 m0, s42
	s_nop 0
	global_load_lds_dwordx4 v[216:217], off
	s_mov_b32 m0, s43
	s_nop 0
	global_load_lds_dwordx4 v[218:219], off
	s_waitcnt vmcnt(8)
	s_waitcnt lgkmcnt(0)
	s_barrier
	s_waitcnt lgkmcnt(0)
	v_mfma_f32_16x16x32_bf16 v[60:63], v[148:151], v[180:183], v[60:63]
	v_mfma_f32_16x16x32_bf16 v[56:59], v[156:159], v[180:183], v[56:59]
	v_mfma_f32_16x16x32_bf16 v[44:47], v[148:151], v[188:191], v[44:47]
	v_mfma_f32_16x16x32_bf16 v[40:43], v[156:159], v[188:191], v[40:43]
	v_mfma_f32_16x16x32_bf16 v[28:31], v[148:151], v[196:199], v[28:31]
	v_mfma_f32_16x16x32_bf16 v[24:27], v[156:159], v[196:199], v[24:27]
	v_mfma_f32_16x16x32_bf16 v[12:15], v[148:151], v[204:207], v[12:15]
	v_mfma_f32_16x16x32_bf16 v[8:11], v[156:159], v[204:207], v[8:11]
	v_mfma_f32_16x16x32_bf16 v[60:63], v[152:155], v[184:187], v[60:63]
	v_mfma_f32_16x16x32_bf16 v[56:59], v[160:163], v[184:187], v[56:59]
	v_mfma_f32_16x16x32_bf16 v[44:47], v[152:155], v[192:195], v[44:47]
	v_mfma_f32_16x16x32_bf16 v[40:43], v[160:163], v[192:195], v[40:43]
	v_mfma_f32_16x16x32_bf16 v[28:31], v[152:155], v[200:203], v[28:31]
	v_mfma_f32_16x16x32_bf16 v[24:27], v[160:163], v[200:203], v[24:27]
	v_mfma_f32_16x16x32_bf16 v[12:15], v[152:155], v[208:211], v[12:15]
	v_mfma_f32_16x16x32_bf16 v[8:11], v[160:163], v[208:211], v[8:11]
	v_mfma_f32_16x16x32_bf16 v[52:55], v[164:167], v[180:183], v[52:55]
	v_mfma_f32_16x16x32_bf16 v[48:51], v[172:175], v[180:183], v[48:51]
	v_mfma_f32_16x16x32_bf16 v[36:39], v[164:167], v[188:191], v[36:39]
	v_mfma_f32_16x16x32_bf16 v[32:35], v[172:175], v[188:191], v[32:35]
	v_mfma_f32_16x16x32_bf16 v[20:23], v[164:167], v[196:199], v[20:23]
	v_mfma_f32_16x16x32_bf16 v[16:19], v[172:175], v[196:199], v[16:19]
	v_mfma_f32_16x16x32_bf16 v[4:7], v[164:167], v[204:207], v[4:7]
	v_mfma_f32_16x16x32_bf16 v[0:3], v[172:175], v[204:207], v[0:3]
	v_mfma_f32_16x16x32_bf16 v[52:55], v[168:171], v[184:187], v[52:55]
	v_mfma_f32_16x16x32_bf16 v[48:51], v[176:179], v[184:187], v[48:51]
	v_mfma_f32_16x16x32_bf16 v[36:39], v[168:171], v[192:195], v[36:39]
	v_mfma_f32_16x16x32_bf16 v[32:35], v[176:179], v[192:195], v[32:35]
	v_mfma_f32_16x16x32_bf16 v[20:23], v[168:171], v[200:203], v[20:23]
	v_mfma_f32_16x16x32_bf16 v[16:19], v[176:179], v[200:203], v[16:19]
	v_mfma_f32_16x16x32_bf16 v[4:7], v[168:171], v[208:211], v[4:7]
	v_mfma_f32_16x16x32_bf16 v[0:3], v[176:179], v[208:211], v[0:3]
	s_barrier
	s_add_i32 s33, 0, 0x18000
	v_add_u32_e32 v147, s33, v145
	s_add_i32 s55, 0, 0x1c000
	ds_read_b128 v[148:151], v147
	ds_read_b128 v[152:155], v147 offset:1024
	ds_read_b128 v[156:159], v147 offset:2048
	ds_read_b128 v[160:163], v147 offset:3072
	v_add_u32_e32 v147, s55, v145
	ds_read_b128 v[164:167], v147
	ds_read_b128 v[168:171], v147 offset:1024
	ds_read_b128 v[172:175], v147 offset:2048
	ds_read_b128 v[176:179], v147 offset:3072
	s_add_u32 s30, s30, 0x160000
	s_addc_u32 s31, s31, 0
	s_mov_b32 m0, s44
	v_lshl_add_u64 v[224:225], s[30:31], 0, v[128:129]
	ds_read_b128 v[180:183], v146 offset:32768
	ds_read_b128 v[184:187], v146 offset:33792
	ds_read_b128 v[188:191], v146 offset:34816
	ds_read_b128 v[192:195], v146 offset:35840
	ds_read_b128 v[196:199], v146 offset:36864
	ds_read_b128 v[200:203], v146 offset:37888
	ds_read_b128 v[204:207], v146 offset:38912
	ds_read_b128 v[208:211], v146 offset:39936
	global_load_lds_dwordx4 v[224:225], off
	v_lshl_add_u64 v[224:225], s[30:31], 0, v[130:131]
	s_mov_b32 m0, s45
	s_nop 0
	global_load_lds_dwordx4 v[224:225], off
	s_waitcnt vmcnt(8)
	s_waitcnt lgkmcnt(0)
	s_barrier
	s_waitcnt lgkmcnt(0)
	v_mfma_f32_16x16x32_bf16 v[124:127], v[148:151], v[180:183], v[124:127]
	v_mfma_f32_16x16x32_bf16 v[120:123], v[156:159], v[180:183], v[120:123]
	v_mfma_f32_16x16x32_bf16 v[108:111], v[148:151], v[188:191], v[108:111]
	v_mfma_f32_16x16x32_bf16 v[104:107], v[156:159], v[188:191], v[104:107]
	v_mfma_f32_16x16x32_bf16 v[92:95], v[148:151], v[196:199], v[92:95]
	v_mfma_f32_16x16x32_bf16 v[88:91], v[156:159], v[196:199], v[88:91]
	v_mfma_f32_16x16x32_bf16 v[76:79], v[148:151], v[204:207], v[76:79]
	v_mfma_f32_16x16x32_bf16 v[72:75], v[156:159], v[204:207], v[72:75]
	v_mfma_f32_16x16x32_bf16 v[124:127], v[152:155], v[184:187], v[124:127]
	v_mfma_f32_16x16x32_bf16 v[120:123], v[160:163], v[184:187], v[120:123]
	v_mfma_f32_16x16x32_bf16 v[108:111], v[152:155], v[192:195], v[108:111]
	v_mfma_f32_16x16x32_bf16 v[104:107], v[160:163], v[192:195], v[104:107]
	v_mfma_f32_16x16x32_bf16 v[92:95], v[152:155], v[200:203], v[92:95]
	v_mfma_f32_16x16x32_bf16 v[88:91], v[160:163], v[200:203], v[88:91]
	v_mfma_f32_16x16x32_bf16 v[76:79], v[152:155], v[208:211], v[76:79]
	v_mfma_f32_16x16x32_bf16 v[72:75], v[160:163], v[208:211], v[72:75]
	v_mfma_f32_16x16x32_bf16 v[116:119], v[164:167], v[180:183], v[116:119]
	v_mfma_f32_16x16x32_bf16 v[112:115], v[172:175], v[180:183], v[112:115]
	v_mfma_f32_16x16x32_bf16 v[100:103], v[164:167], v[188:191], v[100:103]
	v_mfma_f32_16x16x32_bf16 v[96:99], v[172:175], v[188:191], v[96:99]
	v_mfma_f32_16x16x32_bf16 v[84:87], v[164:167], v[196:199], v[84:87]
	v_mfma_f32_16x16x32_bf16 v[80:83], v[172:175], v[196:199], v[80:83]
	v_mfma_f32_16x16x32_bf16 v[68:71], v[164:167], v[204:207], v[68:71]
	v_mfma_f32_16x16x32_bf16 v[64:67], v[172:175], v[204:207], v[64:67]
	v_mfma_f32_16x16x32_bf16 v[116:119], v[168:171], v[184:187], v[116:119]
	v_mfma_f32_16x16x32_bf16 v[112:115], v[176:179], v[184:187], v[112:115]
	v_mfma_f32_16x16x32_bf16 v[100:103], v[168:171], v[192:195], v[100:103]
	v_mfma_f32_16x16x32_bf16 v[96:99], v[176:179], v[192:195], v[96:99]
	v_mfma_f32_16x16x32_bf16 v[84:87], v[168:171], v[200:203], v[84:87]
	v_mfma_f32_16x16x32_bf16 v[80:83], v[176:179], v[200:203], v[80:83]
	v_mfma_f32_16x16x32_bf16 v[68:71], v[168:171], v[208:211], v[68:71]
	v_mfma_f32_16x16x32_bf16 v[64:67], v[176:179], v[208:211], v[64:67]
	s_barrier
	s_add_i32 s30, s33, s41
	v_lshl_add_u64 v[212:213], v[212:213], 0, s[14:15]
	s_mov_b32 m0, s30
	ds_read_b128 v[180:183], v146 offset:49152
	ds_read_b128 v[184:187], v146 offset:50176
	ds_read_b128 v[188:191], v146 offset:51200
	ds_read_b128 v[192:195], v146 offset:52224
	ds_read_b128 v[196:199], v146 offset:53248
	ds_read_b128 v[200:203], v146 offset:54272
	ds_read_b128 v[204:207], v146 offset:55296
	ds_read_b128 v[208:211], v146 offset:56320
	global_load_lds_dwordx4 v[212:213], off
	s_add_i32 m0, s30, 0x2000
	s_add_u32 s28, s28, 0x160080
	v_lshl_add_u64 v[212:213], v[214:215], 0, s[14:15]
	s_addc_u32 s29, s29, 0
	s_add_i32 s30, s55, s41
	global_load_lds_dwordx4 v[212:213], off
	v_lshl_add_u64 v[212:213], s[28:29], 0, v[128:129]
	s_mov_b32 m0, s30
	s_nop 0
	global_load_lds_dwordx4 v[212:213], off
	v_lshl_add_u64 v[212:213], s[28:29], 0, v[130:131]
	s_add_i32 m0, s30, 0x2000
	s_nop 0
	global_load_lds_dwordx4 v[212:213], off
	v_lshl_add_u64 v[212:213], v[216:217], 0, s[14:15]
	s_mov_b32 m0, s46
	s_nop 0
	global_load_lds_dwordx4 v[212:213], off
	v_lshl_add_u64 v[212:213], v[218:219], 0, s[14:15]
	s_mov_b32 m0, s47
	s_nop 0
	global_load_lds_dwordx4 v[212:213], off
	s_waitcnt vmcnt(8)
	s_waitcnt lgkmcnt(0)
	s_barrier
	s_waitcnt lgkmcnt(0)
	v_mfma_f32_16x16x32_bf16 v[60:63], v[148:151], v[180:183], v[60:63]
	v_mfma_f32_16x16x32_bf16 v[56:59], v[156:159], v[180:183], v[56:59]
	v_mfma_f32_16x16x32_bf16 v[44:47], v[148:151], v[188:191], v[44:47]
	v_mfma_f32_16x16x32_bf16 v[40:43], v[156:159], v[188:191], v[40:43]
	v_mfma_f32_16x16x32_bf16 v[28:31], v[148:151], v[196:199], v[28:31]
	v_mfma_f32_16x16x32_bf16 v[24:27], v[156:159], v[196:199], v[24:27]
	v_mfma_f32_16x16x32_bf16 v[12:15], v[148:151], v[204:207], v[12:15]
	v_mfma_f32_16x16x32_bf16 v[8:11], v[156:159], v[204:207], v[8:11]
	v_mfma_f32_16x16x32_bf16 v[60:63], v[152:155], v[184:187], v[60:63]
	v_mfma_f32_16x16x32_bf16 v[56:59], v[160:163], v[184:187], v[56:59]
	v_mfma_f32_16x16x32_bf16 v[44:47], v[152:155], v[192:195], v[44:47]
	v_mfma_f32_16x16x32_bf16 v[40:43], v[160:163], v[192:195], v[40:43]
	v_mfma_f32_16x16x32_bf16 v[28:31], v[152:155], v[200:203], v[28:31]
	v_mfma_f32_16x16x32_bf16 v[24:27], v[160:163], v[200:203], v[24:27]
	v_mfma_f32_16x16x32_bf16 v[12:15], v[152:155], v[208:211], v[12:15]
	v_mfma_f32_16x16x32_bf16 v[8:11], v[160:163], v[208:211], v[8:11]
	v_mfma_f32_16x16x32_bf16 v[52:55], v[164:167], v[180:183], v[52:55]
	v_mfma_f32_16x16x32_bf16 v[48:51], v[172:175], v[180:183], v[48:51]
	v_mfma_f32_16x16x32_bf16 v[36:39], v[164:167], v[188:191], v[36:39]
	v_mfma_f32_16x16x32_bf16 v[32:35], v[172:175], v[188:191], v[32:35]
	v_mfma_f32_16x16x32_bf16 v[20:23], v[164:167], v[196:199], v[20:23]
	v_mfma_f32_16x16x32_bf16 v[16:19], v[172:175], v[196:199], v[16:19]
	v_mfma_f32_16x16x32_bf16 v[4:7], v[164:167], v[204:207], v[4:7]
	v_mfma_f32_16x16x32_bf16 v[0:3], v[172:175], v[204:207], v[0:3]
	v_mfma_f32_16x16x32_bf16 v[52:55], v[168:171], v[184:187], v[52:55]
	v_mfma_f32_16x16x32_bf16 v[48:51], v[176:179], v[184:187], v[48:51]
	v_mfma_f32_16x16x32_bf16 v[36:39], v[168:171], v[192:195], v[36:39]
	v_mfma_f32_16x16x32_bf16 v[32:35], v[176:179], v[192:195], v[32:35]
	v_mfma_f32_16x16x32_bf16 v[20:23], v[168:171], v[200:203], v[20:23]
	v_mfma_f32_16x16x32_bf16 v[16:19], v[176:179], v[200:203], v[16:19]
	v_mfma_f32_16x16x32_bf16 v[4:7], v[168:171], v[208:211], v[4:7]
	v_mfma_f32_16x16x32_bf16 v[0:3], v[176:179], v[208:211], v[0:3]
	s_barrier
	s_add_i32 s54, s54, 2
	s_add_u32 s24, s24, 0x100
	s_addc_u32 s25, s25, 0
	s_cmpk_gt_u32 s54, 0x55
	s_cbranch_scc0 .LBB0_139
	s_add_u32 s24, s17, 0xffffff00
	s_addc_u32 s25, s53, -1
	s_and_b64 vcc, exec, s[2:3]
	s_cbranch_vccnz .LBB0_142
	v_mov_b32_e32 v0, 0
	s_mov_b32 s38, s51
	s_mov_b32 s35, s52
	s_mov_b64 s[10:11], s[18:19]
	s_mov_b32 s48, s16
	v_mov_b32_e32 v1, v0
	v_mov_b32_e32 v2, v0
	v_mov_b32_e32 v3, v0
	v_mov_b32_e32 v4, v0
	v_mov_b32_e32 v5, v0
	v_mov_b32_e32 v6, v0
	v_mov_b32_e32 v7, v0
	v_mov_b32_e32 v16, v0
	v_mov_b32_e32 v17, v0
	v_mov_b32_e32 v18, v0
	v_mov_b32_e32 v19, v0
	v_mov_b32_e32 v20, v0
	v_mov_b32_e32 v21, v0
	v_mov_b32_e32 v22, v0
	v_mov_b32_e32 v23, v0
	v_mov_b32_e32 v32, v0
	v_mov_b32_e32 v33, v0
	v_mov_b32_e32 v34, v0
	v_mov_b32_e32 v35, v0
	v_mov_b32_e32 v36, v0
	v_mov_b32_e32 v37, v0
	v_mov_b32_e32 v38, v0
	v_mov_b32_e32 v39, v0
	v_mov_b32_e32 v48, v0
	v_mov_b32_e32 v49, v0
	v_mov_b32_e32 v50, v0
	v_mov_b32_e32 v51, v0
	v_mov_b32_e32 v52, v0
	v_mov_b32_e32 v53, v0
	v_mov_b32_e32 v54, v0
	v_mov_b32_e32 v55, v0
	v_mov_b32_e32 v8, v0
	v_mov_b32_e32 v9, v0
	v_mov_b32_e32 v10, v0
	v_mov_b32_e32 v11, v0
	v_mov_b32_e32 v12, v0
	v_mov_b32_e32 v13, v0
	v_mov_b32_e32 v14, v0
	v_mov_b32_e32 v15, v0
	v_mov_b32_e32 v24, v0
	v_mov_b32_e32 v25, v0
	v_mov_b32_e32 v26, v0
	v_mov_b32_e32 v27, v0
	v_mov_b32_e32 v28, v0
	v_mov_b32_e32 v29, v0
	v_mov_b32_e32 v30, v0
	v_mov_b32_e32 v31, v0
	v_mov_b32_e32 v40, v0
	v_mov_b32_e32 v41, v0
	v_mov_b32_e32 v42, v0
	v_mov_b32_e32 v43, v0
	v_mov_b32_e32 v44, v0
	v_mov_b32_e32 v45, v0
	v_mov_b32_e32 v46, v0
	v_mov_b32_e32 v47, v0
	v_mov_b32_e32 v56, v0
	v_mov_b32_e32 v57, v0
	v_mov_b32_e32 v58, v0
	v_mov_b32_e32 v59, v0
	v_mov_b32_e32 v60, v0
	v_mov_b32_e32 v61, v0
	v_mov_b32_e32 v62, v0
	v_mov_b32_e32 v63, v0
	v_mov_b32_e32 v64, v0
	v_mov_b32_e32 v65, v0
	v_mov_b32_e32 v66, v0
	v_mov_b32_e32 v67, v0
	v_mov_b32_e32 v68, v0
	v_mov_b32_e32 v69, v0
	v_mov_b32_e32 v70, v0
	v_mov_b32_e32 v71, v0
	v_mov_b32_e32 v80, v0
	v_mov_b32_e32 v81, v0
	v_mov_b32_e32 v82, v0
	v_mov_b32_e32 v83, v0
	v_mov_b32_e32 v84, v0
	v_mov_b32_e32 v85, v0
	v_mov_b32_e32 v86, v0
	v_mov_b32_e32 v87, v0
	v_mov_b32_e32 v96, v0
	v_mov_b32_e32 v97, v0
	v_mov_b32_e32 v98, v0
	v_mov_b32_e32 v99, v0
	v_mov_b32_e32 v100, v0
	v_mov_b32_e32 v101, v0
	v_mov_b32_e32 v102, v0
	v_mov_b32_e32 v103, v0
	v_mov_b32_e32 v112, v0
	v_mov_b32_e32 v113, v0
	v_mov_b32_e32 v114, v0
	v_mov_b32_e32 v115, v0
	v_mov_b32_e32 v116, v0
	v_mov_b32_e32 v117, v0
	v_mov_b32_e32 v118, v0
	v_mov_b32_e32 v119, v0
	v_mov_b32_e32 v72, v0
	v_mov_b32_e32 v73, v0
	v_mov_b32_e32 v74, v0
	v_mov_b32_e32 v75, v0
	v_mov_b32_e32 v76, v0
	v_mov_b32_e32 v77, v0
	v_mov_b32_e32 v78, v0
	v_mov_b32_e32 v79, v0
	v_mov_b32_e32 v88, v0
	v_mov_b32_e32 v89, v0
	v_mov_b32_e32 v90, v0
	v_mov_b32_e32 v91, v0
	v_mov_b32_e32 v92, v0
	v_mov_b32_e32 v93, v0
	v_mov_b32_e32 v94, v0
	v_mov_b32_e32 v95, v0
	v_mov_b32_e32 v104, v0
	v_mov_b32_e32 v105, v0
	v_mov_b32_e32 v106, v0
	v_mov_b32_e32 v107, v0
	v_mov_b32_e32 v108, v0
	v_mov_b32_e32 v109, v0
	v_mov_b32_e32 v110, v0
	v_mov_b32_e32 v111, v0
	v_mov_b32_e32 v120, v0
	v_mov_b32_e32 v121, v0
	v_mov_b32_e32 v122, v0
	v_mov_b32_e32 v123, v0
	v_mov_b32_e32 v124, v0
	v_mov_b32_e32 v125, v0
	v_mov_b32_e32 v126, v0
	v_mov_b32_e32 v127, v0
	s_andn2_b64 vcc, exec, s[0:1]
	s_cbranch_vccnz .LBB0_143
	s_branch .LBB0_144

.LBB0_331:
	ds_read_b128 v[158:161], v155
	ds_read_b128 v[162:165], v155 offset:1024
	ds_read_b128 v[166:169], v155 offset:2048
	ds_read_b128 v[170:173], v155 offset:3072
	ds_read_b128 v[174:177], v156
	ds_read_b128 v[178:181], v156 offset:1024
	ds_read_b128 v[182:185], v156 offset:2048
	ds_read_b128 v[186:189], v156 offset:3072
	s_add_u32 s24, s22, 0xfff80080
	s_addc_u32 s25, s23, -1
	s_cmp_eq_u32 s51, 28
	s_cselect_b32 s29, s15, s25
	s_cselect_b32 s28, s47, s24
	s_cselect_b32 s25, s13, s50
	s_cselect_b32 s24, s48, s49
	v_lshl_add_u64 v[218:219], s[22:23], 0, v[136:137]
	s_add_i32 m0, s21, 0xc000
	ds_read_b128 v[190:193], v157
	ds_read_b128 v[194:197], v157 offset:1024
	ds_read_b128 v[198:201], v157 offset:2048
	ds_read_b128 v[202:205], v157 offset:3072
	ds_read_b128 v[206:209], v157 offset:4096
	ds_read_b128 v[210:213], v157 offset:5120
	ds_read_b128 v[214:217], v157 offset:6144
	ds_read_b128 v[222:225], v157 offset:7168
	global_load_lds_dwordx4 v[218:219], off
	v_lshl_add_u64 v[218:219], s[22:23], 0, v[138:139]
	s_add_i32 m0, s21, 0xe000
	s_nop 0
	global_load_lds_dwordx4 v[218:219], off
	s_waitcnt vmcnt(8)
	s_waitcnt lgkmcnt(0)
	s_barrier
	s_waitcnt lgkmcnt(0)
	v_mfma_f32_16x16x32_bf16 v[124:127], v[158:161], v[190:193], v[124:127]
	v_mfma_f32_16x16x32_bf16 v[120:123], v[166:169], v[190:193], v[120:123]
	v_mfma_f32_16x16x32_bf16 v[116:119], v[158:161], v[198:201], v[116:119]
	v_mfma_f32_16x16x32_bf16 v[108:111], v[166:169], v[198:201], v[108:111]
	v_mfma_f32_16x16x32_bf16 v[100:103], v[158:161], v[206:209], v[100:103]
	v_mfma_f32_16x16x32_bf16 v[92:95], v[166:169], v[206:209], v[92:95]
	v_mfma_f32_16x16x32_bf16 v[84:87], v[158:161], v[214:217], v[84:87]
	v_mfma_f32_16x16x32_bf16 v[76:79], v[166:169], v[214:217], v[76:79]
	v_mfma_f32_16x16x32_bf16 v[124:127], v[162:165], v[194:197], v[124:127]
	v_mfma_f32_16x16x32_bf16 v[120:123], v[170:173], v[194:197], v[120:123]
	v_mfma_f32_16x16x32_bf16 v[116:119], v[162:165], v[202:205], v[116:119]
	v_mfma_f32_16x16x32_bf16 v[108:111], v[170:173], v[202:205], v[108:111]
	v_mfma_f32_16x16x32_bf16 v[100:103], v[162:165], v[210:213], v[100:103]
	v_mfma_f32_16x16x32_bf16 v[92:95], v[170:173], v[210:213], v[92:95]
	v_mfma_f32_16x16x32_bf16 v[84:87], v[162:165], v[222:225], v[84:87]
	v_mfma_f32_16x16x32_bf16 v[76:79], v[170:173], v[222:225], v[76:79]
	v_mfma_f32_16x16x32_bf16 v[112:115], v[174:177], v[190:193], v[112:115]
	v_mfma_f32_16x16x32_bf16 v[104:107], v[182:185], v[190:193], v[104:107]
	v_mfma_f32_16x16x32_bf16 v[96:99], v[174:177], v[198:201], v[96:99]
	v_mfma_f32_16x16x32_bf16 v[88:91], v[182:185], v[198:201], v[88:91]
	v_mfma_f32_16x16x32_bf16 v[80:83], v[174:177], v[206:209], v[80:83]
	v_mfma_f32_16x16x32_bf16 v[72:75], v[182:185], v[206:209], v[72:75]
	v_mfma_f32_16x16x32_bf16 v[68:71], v[174:177], v[214:217], v[68:71]
	v_mfma_f32_16x16x32_bf16 v[64:67], v[182:185], v[214:217], v[64:67]
	v_mfma_f32_16x16x32_bf16 v[112:115], v[178:181], v[194:197], v[112:115]
	v_mfma_f32_16x16x32_bf16 v[104:107], v[186:189], v[194:197], v[104:107]
	v_mfma_f32_16x16x32_bf16 v[96:99], v[178:181], v[202:205], v[96:99]
	v_mfma_f32_16x16x32_bf16 v[88:91], v[186:189], v[202:205], v[88:91]
	v_mfma_f32_16x16x32_bf16 v[80:83], v[178:181], v[210:213], v[80:83]
	v_mfma_f32_16x16x32_bf16 v[72:75], v[186:189], v[210:213], v[72:75]
	v_mfma_f32_16x16x32_bf16 v[68:71], v[178:181], v[222:225], v[68:71]
	v_mfma_f32_16x16x32_bf16 v[64:67], v[186:189], v[222:225], v[64:67]
	s_barrier
	s_add_i32 s33, s43, s30
	v_lshl_add_u64 v[218:219], s[24:25], 0, v[130:131]
	s_mov_b32 m0, s33
	ds_read_b128 v[190:193], v157 offset:16384
	ds_read_b128 v[194:197], v157 offset:17408
	ds_read_b128 v[198:201], v157 offset:18432
	ds_read_b128 v[202:205], v157 offset:19456
	ds_read_b128 v[206:209], v157 offset:20480
	ds_read_b128 v[210:213], v157 offset:21504
	ds_read_b128 v[214:217], v157 offset:22528
	ds_read_b128 v[222:225], v157 offset:23552
	global_load_lds_dwordx4 v[218:219], off
	s_add_i32 m0, s33, 0x2000
	s_add_u32 s52, s24, 0x80000
	v_lshl_add_u64 v[226:227], s[24:25], 0, v[134:135]
	s_addc_u32 s53, s25, 0
	s_add_i32 s33, s44, s30
	global_load_lds_dwordx4 v[226:227], off
	v_lshl_add_u64 v[228:229], s[52:53], 0, v[130:131]
	s_mov_b32 m0, s33
	v_lshl_add_u64 v[230:231], s[28:29], 0, v[132:133]
	global_load_lds_dwordx4 v[228:229], off
	v_lshl_add_u64 v[228:229], s[52:53], 0, v[134:135]
	s_add_i32 m0, s33, 0x2000
	s_nop 0
	global_load_lds_dwordx4 v[228:229], off
	v_lshl_add_u64 v[228:229], s[28:29], 0, v[128:129]
	s_mov_b32 m0, s21
	s_nop 0
	global_load_lds_dwordx4 v[228:229], off
	s_mov_b32 m0, s35
	s_nop 0
	global_load_lds_dwordx4 v[230:231], off
	s_waitcnt vmcnt(8)
	s_waitcnt lgkmcnt(0)
	s_barrier
	s_waitcnt lgkmcnt(0)
	v_mfma_f32_16x16x32_bf16 v[60:63], v[158:161], v[190:193], v[60:63]
	v_mfma_f32_16x16x32_bf16 v[56:59], v[166:169], v[190:193], v[56:59]
	v_mfma_f32_16x16x32_bf16 v[52:55], v[158:161], v[198:201], v[52:55]
	v_mfma_f32_16x16x32_bf16 v[44:47], v[166:169], v[198:201], v[44:47]
	v_mfma_f32_16x16x32_bf16 v[36:39], v[158:161], v[206:209], v[36:39]
	v_mfma_f32_16x16x32_bf16 v[28:31], v[166:169], v[206:209], v[28:31]
	v_mfma_f32_16x16x32_bf16 v[20:23], v[158:161], v[214:217], v[20:23]
	v_mfma_f32_16x16x32_bf16 v[12:15], v[166:169], v[214:217], v[12:15]
	v_mfma_f32_16x16x32_bf16 v[60:63], v[162:165], v[194:197], v[60:63]
	v_mfma_f32_16x16x32_bf16 v[56:59], v[170:173], v[194:197], v[56:59]
	v_mfma_f32_16x16x32_bf16 v[52:55], v[162:165], v[202:205], v[52:55]
	v_mfma_f32_16x16x32_bf16 v[44:47], v[170:173], v[202:205], v[44:47]
	v_mfma_f32_16x16x32_bf16 v[36:39], v[162:165], v[210:213], v[36:39]
	v_mfma_f32_16x16x32_bf16 v[28:31], v[170:173], v[210:213], v[28:31]
	v_mfma_f32_16x16x32_bf16 v[20:23], v[162:165], v[222:225], v[20:23]
	v_mfma_f32_16x16x32_bf16 v[12:15], v[170:173], v[222:225], v[12:15]
	v_mfma_f32_16x16x32_bf16 v[48:51], v[174:177], v[190:193], v[48:51]
	v_mfma_f32_16x16x32_bf16 v[40:43], v[182:185], v[190:193], v[40:43]
	v_mfma_f32_16x16x32_bf16 v[32:35], v[174:177], v[198:201], v[32:35]
	v_mfma_f32_16x16x32_bf16 v[24:27], v[182:185], v[198:201], v[24:27]
	v_mfma_f32_16x16x32_bf16 v[16:19], v[174:177], v[206:209], v[16:19]
	v_mfma_f32_16x16x32_bf16 v[8:11], v[182:185], v[206:209], v[8:11]
	v_mfma_f32_16x16x32_bf16 v[4:7], v[174:177], v[214:217], v[4:7]
	v_mfma_f32_16x16x32_bf16 v[0:3], v[182:185], v[214:217], v[0:3]
	v_mfma_f32_16x16x32_bf16 v[48:51], v[178:181], v[194:197], v[48:51]
	v_mfma_f32_16x16x32_bf16 v[40:43], v[186:189], v[194:197], v[40:43]
	v_mfma_f32_16x16x32_bf16 v[32:35], v[178:181], v[202:205], v[32:35]
	v_mfma_f32_16x16x32_bf16 v[24:27], v[186:189], v[202:205], v[24:27]
	v_mfma_f32_16x16x32_bf16 v[16:19], v[178:181], v[210:213], v[16:19]
	v_mfma_f32_16x16x32_bf16 v[8:11], v[186:189], v[210:213], v[8:11]
	v_mfma_f32_16x16x32_bf16 v[4:7], v[178:181], v[222:225], v[4:7]
	v_mfma_f32_16x16x32_bf16 v[0:3], v[186:189], v[222:225], v[0:3]
	s_barrier
	s_add_i32 s33, 0, 0x18000
	s_add_i32 s52, 0, 0x1c000
	v_add_u32_e32 v170, s33, v153
	v_add_u32_e32 v186, s52, v153
	ds_read_b128 v[158:161], v170
	ds_read_b128 v[162:165], v170 offset:1024
	ds_read_b128 v[166:169], v170 offset:2048
	ds_read_b128 v[170:173], v170 offset:3072
	ds_read_b128 v[174:177], v186
	ds_read_b128 v[178:181], v186 offset:1024
	ds_read_b128 v[182:185], v186 offset:2048
	ds_read_b128 v[186:189], v186 offset:3072
	s_add_u32 s28, s28, 0x80000
	s_addc_u32 s29, s29, 0
	s_mov_b32 m0, s37
	v_lshl_add_u64 v[232:233], s[28:29], 0, v[128:129]
	ds_read_b128 v[190:193], v157 offset:32768
	ds_read_b128 v[194:197], v157 offset:33792
	ds_read_b128 v[198:201], v157 offset:34816
	ds_read_b128 v[202:205], v157 offset:35840
	ds_read_b128 v[206:209], v157 offset:36864
	ds_read_b128 v[210:213], v157 offset:37888
	ds_read_b128 v[214:217], v157 offset:38912
	ds_read_b128 v[222:225], v157 offset:39936
	global_load_lds_dwordx4 v[232:233], off
	v_lshl_add_u64 v[232:233], s[28:29], 0, v[132:133]
	s_mov_b32 m0, s38
	s_nop 0
	global_load_lds_dwordx4 v[232:233], off
	s_waitcnt vmcnt(8)
	s_waitcnt lgkmcnt(0)
	s_barrier
	s_waitcnt lgkmcnt(0)
	v_mfma_f32_16x16x32_bf16 v[124:127], v[158:161], v[190:193], v[124:127]
	v_mfma_f32_16x16x32_bf16 v[120:123], v[166:169], v[190:193], v[120:123]
	v_mfma_f32_16x16x32_bf16 v[116:119], v[158:161], v[198:201], v[116:119]
	v_mfma_f32_16x16x32_bf16 v[108:111], v[166:169], v[198:201], v[108:111]
	v_mfma_f32_16x16x32_bf16 v[100:103], v[158:161], v[206:209], v[100:103]
	v_mfma_f32_16x16x32_bf16 v[92:95], v[166:169], v[206:209], v[92:95]
	v_mfma_f32_16x16x32_bf16 v[84:87], v[158:161], v[214:217], v[84:87]
	v_mfma_f32_16x16x32_bf16 v[76:79], v[166:169], v[214:217], v[76:79]
	v_mfma_f32_16x16x32_bf16 v[124:127], v[162:165], v[194:197], v[124:127]
	v_mfma_f32_16x16x32_bf16 v[120:123], v[170:173], v[194:197], v[120:123]
	v_mfma_f32_16x16x32_bf16 v[116:119], v[162:165], v[202:205], v[116:119]
	v_mfma_f32_16x16x32_bf16 v[108:111], v[170:173], v[202:205], v[108:111]
	v_mfma_f32_16x16x32_bf16 v[100:103], v[162:165], v[210:213], v[100:103]
	v_mfma_f32_16x16x32_bf16 v[92:95], v[170:173], v[210:213], v[92:95]
	v_mfma_f32_16x16x32_bf16 v[84:87], v[162:165], v[222:225], v[84:87]
	v_mfma_f32_16x16x32_bf16 v[76:79], v[170:173], v[222:225], v[76:79]
	v_mfma_f32_16x16x32_bf16 v[112:115], v[174:177], v[190:193], v[112:115]
	v_mfma_f32_16x16x32_bf16 v[104:107], v[182:185], v[190:193], v[104:107]
	v_mfma_f32_16x16x32_bf16 v[96:99], v[174:177], v[198:201], v[96:99]
	v_mfma_f32_16x16x32_bf16 v[88:91], v[182:185], v[198:201], v[88:91]
	v_mfma_f32_16x16x32_bf16 v[80:83], v[174:177], v[206:209], v[80:83]
	v_mfma_f32_16x16x32_bf16 v[72:75], v[182:185], v[206:209], v[72:75]
	v_mfma_f32_16x16x32_bf16 v[68:71], v[174:177], v[214:217], v[68:71]
	v_mfma_f32_16x16x32_bf16 v[64:67], v[182:185], v[214:217], v[64:67]
	v_mfma_f32_16x16x32_bf16 v[112:115], v[178:181], v[194:197], v[112:115]
	v_mfma_f32_16x16x32_bf16 v[104:107], v[186:189], v[194:197], v[104:107]
	v_mfma_f32_16x16x32_bf16 v[96:99], v[178:181], v[202:205], v[96:99]
	v_mfma_f32_16x16x32_bf16 v[88:91], v[186:189], v[202:205], v[88:91]
	v_mfma_f32_16x16x32_bf16 v[80:83], v[178:181], v[210:213], v[80:83]
	v_mfma_f32_16x16x32_bf16 v[72:75], v[186:189], v[210:213], v[72:75]
	v_mfma_f32_16x16x32_bf16 v[68:71], v[178:181], v[222:225], v[68:71]
	v_mfma_f32_16x16x32_bf16 v[64:67], v[186:189], v[222:225], v[64:67]
	s_barrier
	s_add_i32 s28, s33, s30
	v_lshl_add_u64 v[218:219], v[218:219], 0, s[8:9]
	s_mov_b32 m0, s28
	ds_read_b128 v[190:193], v157 offset:49152
	ds_read_b128 v[194:197], v157 offset:50176
	ds_read_b128 v[198:201], v157 offset:51200
	ds_read_b128 v[202:205], v157 offset:52224
	ds_read_b128 v[206:209], v157 offset:53248
	ds_read_b128 v[210:213], v157 offset:54272
	ds_read_b128 v[214:217], v157 offset:55296
	ds_read_b128 v[222:225], v157 offset:56320
	global_load_lds_dwordx4 v[218:219], off
	s_add_i32 m0, s28, 0x2000
	s_add_u32 s24, s24, 0x80080
	v_lshl_add_u64 v[218:219], v[226:227], 0, s[8:9]
	s_addc_u32 s25, s25, 0
	s_add_i32 s28, s52, s30
	global_load_lds_dwordx4 v[218:219], off
	v_lshl_add_u64 v[218:219], s[24:25], 0, v[130:131]
	s_mov_b32 m0, s28
	s_nop 0
	global_load_lds_dwordx4 v[218:219], off
	v_lshl_add_u64 v[218:219], s[24:25], 0, v[134:135]
	s_add_i32 m0, s28, 0x2000
	s_nop 0
	global_load_lds_dwordx4 v[218:219], off
	v_lshl_add_u64 v[218:219], v[228:229], 0, s[8:9]
	s_mov_b32 m0, s40
	s_nop 0
	global_load_lds_dwordx4 v[218:219], off
	v_lshl_add_u64 v[218:219], v[230:231], 0, s[8:9]
	s_mov_b32 m0, s41
	s_nop 0
	global_load_lds_dwordx4 v[218:219], off
	s_waitcnt vmcnt(8)
	s_waitcnt lgkmcnt(0)
	s_barrier
	s_waitcnt lgkmcnt(0)
	v_mfma_f32_16x16x32_bf16 v[60:63], v[158:161], v[190:193], v[60:63]
	v_mfma_f32_16x16x32_bf16 v[56:59], v[166:169], v[190:193], v[56:59]
	v_mfma_f32_16x16x32_bf16 v[52:55], v[158:161], v[198:201], v[52:55]
	v_mfma_f32_16x16x32_bf16 v[44:47], v[166:169], v[198:201], v[44:47]
	v_mfma_f32_16x16x32_bf16 v[36:39], v[158:161], v[206:209], v[36:39]
	v_mfma_f32_16x16x32_bf16 v[28:31], v[166:169], v[206:209], v[28:31]
	v_mfma_f32_16x16x32_bf16 v[20:23], v[158:161], v[214:217], v[20:23]
	v_mfma_f32_16x16x32_bf16 v[12:15], v[166:169], v[214:217], v[12:15]
	v_mfma_f32_16x16x32_bf16 v[60:63], v[162:165], v[194:197], v[60:63]
	v_mfma_f32_16x16x32_bf16 v[56:59], v[170:173], v[194:197], v[56:59]
	v_mfma_f32_16x16x32_bf16 v[52:55], v[162:165], v[202:205], v[52:55]
	v_mfma_f32_16x16x32_bf16 v[44:47], v[170:173], v[202:205], v[44:47]
	v_mfma_f32_16x16x32_bf16 v[36:39], v[162:165], v[210:213], v[36:39]
	v_mfma_f32_16x16x32_bf16 v[28:31], v[170:173], v[210:213], v[28:31]
	v_mfma_f32_16x16x32_bf16 v[20:23], v[162:165], v[222:225], v[20:23]
	v_mfma_f32_16x16x32_bf16 v[12:15], v[170:173], v[222:225], v[12:15]
	v_mfma_f32_16x16x32_bf16 v[48:51], v[174:177], v[190:193], v[48:51]
	v_mfma_f32_16x16x32_bf16 v[40:43], v[182:185], v[190:193], v[40:43]
	v_mfma_f32_16x16x32_bf16 v[32:35], v[174:177], v[198:201], v[32:35]
	v_mfma_f32_16x16x32_bf16 v[24:27], v[182:185], v[198:201], v[24:27]
	v_mfma_f32_16x16x32_bf16 v[16:19], v[174:177], v[206:209], v[16:19]
	v_mfma_f32_16x16x32_bf16 v[8:11], v[182:185], v[206:209], v[8:11]
	v_mfma_f32_16x16x32_bf16 v[4:7], v[174:177], v[214:217], v[4:7]
	v_mfma_f32_16x16x32_bf16 v[0:3], v[182:185], v[214:217], v[0:3]
	v_mfma_f32_16x16x32_bf16 v[48:51], v[178:181], v[194:197], v[48:51]
	v_mfma_f32_16x16x32_bf16 v[40:43], v[186:189], v[194:197], v[40:43]
	v_mfma_f32_16x16x32_bf16 v[32:35], v[178:181], v[202:205], v[32:35]
	v_mfma_f32_16x16x32_bf16 v[24:27], v[186:189], v[202:205], v[24:27]
	v_mfma_f32_16x16x32_bf16 v[16:19], v[178:181], v[210:213], v[16:19]
	v_mfma_f32_16x16x32_bf16 v[8:11], v[186:189], v[210:213], v[8:11]
	v_mfma_f32_16x16x32_bf16 v[4:7], v[178:181], v[222:225], v[4:7]
	v_mfma_f32_16x16x32_bf16 v[0:3], v[186:189], v[222:225], v[0:3]
	s_barrier
	s_add_i32 s51, s51, 2
	s_add_u32 s22, s22, 0x100
	s_addc_u32 s23, s23, 0
	s_add_u32 s49, s49, 0x100
	s_addc_u32 s50, s50, 0
	s_cmp_gt_u32 s51, 29
	s_cbranch_scc0 .LBB0_331
	s_and_b64 vcc, exec, s[10:11]
	s_cbranch_vccz .LBB0_334
	s_barrier

.LBB0_363:
	ds_read_b128 v[154:157], v144
	ds_read_b128 v[158:161], v144 offset:1024
	ds_read_b128 v[162:165], v144 offset:2048
	ds_read_b128 v[166:169], v144 offset:3072
	ds_read_b128 v[170:173], v145
	ds_read_b128 v[174:177], v145 offset:1024
	ds_read_b128 v[178:181], v145 offset:2048
	ds_read_b128 v[182:185], v145 offset:3072
	s_add_u32 s30, s28, 0xfff80080
	s_addc_u32 s31, s29, -1
	s_cmp_eq_u32 s50, 28
	s_cselect_b32 s35, s15, s31
	s_cselect_b32 s34, s46, s30
	s_cselect_b32 s31, s17, s49
	s_cselect_b32 s30, s47, s48
	v_lshl_add_u64 v[150:151], s[28:29], 0, v[136:137]
	s_add_i32 m0, s23, 0xc000
	ds_read_b128 v[186:189], v146
	ds_read_b128 v[190:193], v146 offset:1024
	ds_read_b128 v[194:197], v146 offset:2048
	ds_read_b128 v[198:201], v146 offset:3072
	ds_read_b128 v[202:205], v146 offset:4096
	ds_read_b128 v[206:209], v146 offset:5120
	ds_read_b128 v[210:213], v146 offset:6144
	ds_read_b128 v[214:217], v146 offset:7168
	global_load_lds_dwordx4 v[150:151], off
	v_lshl_add_u64 v[150:151], s[28:29], 0, v[138:139]
	s_add_i32 m0, s23, 0xe000
	s_nop 0
	global_load_lds_dwordx4 v[150:151], off
	s_waitcnt vmcnt(8)
	s_waitcnt lgkmcnt(0)
	s_barrier
	s_waitcnt lgkmcnt(0)
	v_mfma_f32_16x16x32_bf16 v[124:127], v[154:157], v[186:189], v[124:127]
	v_mfma_f32_16x16x32_bf16 v[120:123], v[162:165], v[186:189], v[120:123]
	v_mfma_f32_16x16x32_bf16 v[116:119], v[154:157], v[194:197], v[116:119]
	v_mfma_f32_16x16x32_bf16 v[108:111], v[162:165], v[194:197], v[108:111]
	v_mfma_f32_16x16x32_bf16 v[100:103], v[154:157], v[202:205], v[100:103]
	v_mfma_f32_16x16x32_bf16 v[92:95], v[162:165], v[202:205], v[92:95]
	v_mfma_f32_16x16x32_bf16 v[84:87], v[154:157], v[210:213], v[84:87]
	v_mfma_f32_16x16x32_bf16 v[76:79], v[162:165], v[210:213], v[76:79]
	v_mfma_f32_16x16x32_bf16 v[124:127], v[158:161], v[190:193], v[124:127]
	v_mfma_f32_16x16x32_bf16 v[120:123], v[166:169], v[190:193], v[120:123]
	v_mfma_f32_16x16x32_bf16 v[116:119], v[158:161], v[198:201], v[116:119]
	v_mfma_f32_16x16x32_bf16 v[108:111], v[166:169], v[198:201], v[108:111]
	v_mfma_f32_16x16x32_bf16 v[100:103], v[158:161], v[206:209], v[100:103]
	v_mfma_f32_16x16x32_bf16 v[92:95], v[166:169], v[206:209], v[92:95]
	v_mfma_f32_16x16x32_bf16 v[84:87], v[158:161], v[214:217], v[84:87]
	v_mfma_f32_16x16x32_bf16 v[76:79], v[166:169], v[214:217], v[76:79]
	v_mfma_f32_16x16x32_bf16 v[112:115], v[170:173], v[186:189], v[112:115]
	v_mfma_f32_16x16x32_bf16 v[104:107], v[178:181], v[186:189], v[104:107]
	v_mfma_f32_16x16x32_bf16 v[96:99], v[170:173], v[194:197], v[96:99]
	v_mfma_f32_16x16x32_bf16 v[88:91], v[178:181], v[194:197], v[88:91]
	v_mfma_f32_16x16x32_bf16 v[80:83], v[170:173], v[202:205], v[80:83]
	v_mfma_f32_16x16x32_bf16 v[72:75], v[178:181], v[202:205], v[72:75]
	v_mfma_f32_16x16x32_bf16 v[68:71], v[170:173], v[210:213], v[68:71]
	v_mfma_f32_16x16x32_bf16 v[64:67], v[178:181], v[210:213], v[64:67]
	v_mfma_f32_16x16x32_bf16 v[112:115], v[174:177], v[190:193], v[112:115]
	v_mfma_f32_16x16x32_bf16 v[104:107], v[182:185], v[190:193], v[104:107]
	v_mfma_f32_16x16x32_bf16 v[96:99], v[174:177], v[198:201], v[96:99]
	v_mfma_f32_16x16x32_bf16 v[88:91], v[182:185], v[198:201], v[88:91]
	v_mfma_f32_16x16x32_bf16 v[80:83], v[174:177], v[206:209], v[80:83]
	v_mfma_f32_16x16x32_bf16 v[72:75], v[182:185], v[206:209], v[72:75]
	v_mfma_f32_16x16x32_bf16 v[68:71], v[174:177], v[214:217], v[68:71]
	v_mfma_f32_16x16x32_bf16 v[64:67], v[182:185], v[214:217], v[64:67]
	s_barrier
	s_add_i32 s33, s43, s38
	v_lshl_add_u64 v[150:151], s[30:31], 0, v[130:131]
	s_mov_b32 m0, s33
	ds_read_b128 v[186:189], v146 offset:16384
	ds_read_b128 v[190:193], v146 offset:17408
	ds_read_b128 v[194:197], v146 offset:18432
	ds_read_b128 v[198:201], v146 offset:19456
	ds_read_b128 v[202:205], v146 offset:20480
	ds_read_b128 v[206:209], v146 offset:21504
	ds_read_b128 v[210:213], v146 offset:22528
	ds_read_b128 v[214:217], v146 offset:23552
	global_load_lds_dwordx4 v[150:151], off
	s_add_i32 m0, s33, 0x2000
	s_add_u32 s52, s30, 0x80000
	v_lshl_add_u64 v[218:219], s[30:31], 0, v[134:135]
	s_addc_u32 s53, s31, 0
	s_add_i32 s33, s44, s38
	global_load_lds_dwordx4 v[218:219], off
	v_lshl_add_u64 v[222:223], s[52:53], 0, v[130:131]
	s_mov_b32 m0, s33
	v_lshl_add_u64 v[224:225], s[34:35], 0, v[132:133]
	global_load_lds_dwordx4 v[222:223], off
	v_lshl_add_u64 v[222:223], s[52:53], 0, v[134:135]
	s_add_i32 m0, s33, 0x2000
	s_nop 0
	global_load_lds_dwordx4 v[222:223], off
	v_lshl_add_u64 v[222:223], s[34:35], 0, v[128:129]
	s_mov_b32 m0, s23
	s_nop 0
	global_load_lds_dwordx4 v[222:223], off
	s_mov_b32 m0, s25
	s_nop 0
	global_load_lds_dwordx4 v[224:225], off
	s_waitcnt vmcnt(8)
	s_waitcnt lgkmcnt(0)
	s_barrier
	s_waitcnt lgkmcnt(0)
	v_mfma_f32_16x16x32_bf16 v[60:63], v[154:157], v[186:189], v[60:63]
	v_mfma_f32_16x16x32_bf16 v[56:59], v[162:165], v[186:189], v[56:59]
	v_mfma_f32_16x16x32_bf16 v[52:55], v[154:157], v[194:197], v[52:55]
	v_mfma_f32_16x16x32_bf16 v[44:47], v[162:165], v[194:197], v[44:47]
	v_mfma_f32_16x16x32_bf16 v[36:39], v[154:157], v[202:205], v[36:39]
	v_mfma_f32_16x16x32_bf16 v[28:31], v[162:165], v[202:205], v[28:31]
	v_mfma_f32_16x16x32_bf16 v[20:23], v[154:157], v[210:213], v[20:23]
	v_mfma_f32_16x16x32_bf16 v[12:15], v[162:165], v[210:213], v[12:15]
	v_mfma_f32_16x16x32_bf16 v[60:63], v[158:161], v[190:193], v[60:63]
	v_mfma_f32_16x16x32_bf16 v[56:59], v[166:169], v[190:193], v[56:59]
	v_mfma_f32_16x16x32_bf16 v[52:55], v[158:161], v[198:201], v[52:55]
	v_mfma_f32_16x16x32_bf16 v[44:47], v[166:169], v[198:201], v[44:47]
	v_mfma_f32_16x16x32_bf16 v[36:39], v[158:161], v[206:209], v[36:39]
	v_mfma_f32_16x16x32_bf16 v[28:31], v[166:169], v[206:209], v[28:31]
	v_mfma_f32_16x16x32_bf16 v[20:23], v[158:161], v[214:217], v[20:23]
	v_mfma_f32_16x16x32_bf16 v[12:15], v[166:169], v[214:217], v[12:15]
	v_mfma_f32_16x16x32_bf16 v[48:51], v[170:173], v[186:189], v[48:51]
	v_mfma_f32_16x16x32_bf16 v[40:43], v[178:181], v[186:189], v[40:43]
	v_mfma_f32_16x16x32_bf16 v[32:35], v[170:173], v[194:197], v[32:35]
	v_mfma_f32_16x16x32_bf16 v[24:27], v[178:181], v[194:197], v[24:27]
	v_mfma_f32_16x16x32_bf16 v[16:19], v[170:173], v[202:205], v[16:19]
	v_mfma_f32_16x16x32_bf16 v[8:11], v[178:181], v[202:205], v[8:11]
	v_mfma_f32_16x16x32_bf16 v[4:7], v[170:173], v[210:213], v[4:7]
	v_mfma_f32_16x16x32_bf16 v[0:3], v[178:181], v[210:213], v[0:3]
	v_mfma_f32_16x16x32_bf16 v[48:51], v[174:177], v[190:193], v[48:51]
	v_mfma_f32_16x16x32_bf16 v[40:43], v[182:185], v[190:193], v[40:43]
	v_mfma_f32_16x16x32_bf16 v[32:35], v[174:177], v[198:201], v[32:35]
	v_mfma_f32_16x16x32_bf16 v[24:27], v[182:185], v[198:201], v[24:27]
	v_mfma_f32_16x16x32_bf16 v[16:19], v[174:177], v[206:209], v[16:19]
	v_mfma_f32_16x16x32_bf16 v[8:11], v[182:185], v[206:209], v[8:11]
	v_mfma_f32_16x16x32_bf16 v[4:7], v[174:177], v[214:217], v[4:7]
	v_mfma_f32_16x16x32_bf16 v[0:3], v[182:185], v[214:217], v[0:3]
	s_barrier
	s_add_i32 s33, 0, 0x18000
	v_add_u32_e32 v148, s33, v149
	s_add_i32 s51, 0, 0x1c000
	ds_read_b128 v[154:157], v148
	ds_read_b128 v[158:161], v148 offset:1024
	ds_read_b128 v[162:165], v148 offset:2048
	ds_read_b128 v[166:169], v148 offset:3072
	v_add_u32_e32 v148, s51, v149
	ds_read_b128 v[170:173], v148
	ds_read_b128 v[174:177], v148 offset:1024
	ds_read_b128 v[178:181], v148 offset:2048
	ds_read_b128 v[182:185], v148 offset:3072
	s_add_u32 s34, s34, 0x80000
	s_addc_u32 s35, s35, 0
	s_mov_b32 m0, s39
	v_lshl_add_u64 v[226:227], s[34:35], 0, v[128:129]
	ds_read_b128 v[186:189], v146 offset:32768
	ds_read_b128 v[190:193], v146 offset:33792
	ds_read_b128 v[194:197], v146 offset:34816
	ds_read_b128 v[198:201], v146 offset:35840
	ds_read_b128 v[202:205], v146 offset:36864
	ds_read_b128 v[206:209], v146 offset:37888
	ds_read_b128 v[210:213], v146 offset:38912
	ds_read_b128 v[214:217], v146 offset:39936
	global_load_lds_dwordx4 v[226:227], off
	v_lshl_add_u64 v[226:227], s[34:35], 0, v[132:133]
	s_mov_b32 m0, s40
	s_nop 0
	global_load_lds_dwordx4 v[226:227], off
	s_waitcnt vmcnt(8)
	s_waitcnt lgkmcnt(0)
	s_barrier
	s_waitcnt lgkmcnt(0)
	v_mfma_f32_16x16x32_bf16 v[124:127], v[154:157], v[186:189], v[124:127]
	v_mfma_f32_16x16x32_bf16 v[120:123], v[162:165], v[186:189], v[120:123]
	v_mfma_f32_16x16x32_bf16 v[116:119], v[154:157], v[194:197], v[116:119]
	v_mfma_f32_16x16x32_bf16 v[108:111], v[162:165], v[194:197], v[108:111]
	v_mfma_f32_16x16x32_bf16 v[100:103], v[154:157], v[202:205], v[100:103]
	v_mfma_f32_16x16x32_bf16 v[92:95], v[162:165], v[202:205], v[92:95]
	v_mfma_f32_16x16x32_bf16 v[84:87], v[154:157], v[210:213], v[84:87]
	v_mfma_f32_16x16x32_bf16 v[76:79], v[162:165], v[210:213], v[76:79]
	v_mfma_f32_16x16x32_bf16 v[124:127], v[158:161], v[190:193], v[124:127]
	v_mfma_f32_16x16x32_bf16 v[120:123], v[166:169], v[190:193], v[120:123]
	v_mfma_f32_16x16x32_bf16 v[116:119], v[158:161], v[198:201], v[116:119]
	v_mfma_f32_16x16x32_bf16 v[108:111], v[166:169], v[198:201], v[108:111]
	v_mfma_f32_16x16x32_bf16 v[100:103], v[158:161], v[206:209], v[100:103]
	v_mfma_f32_16x16x32_bf16 v[92:95], v[166:169], v[206:209], v[92:95]
	v_mfma_f32_16x16x32_bf16 v[84:87], v[158:161], v[214:217], v[84:87]
	v_mfma_f32_16x16x32_bf16 v[76:79], v[166:169], v[214:217], v[76:79]
	v_mfma_f32_16x16x32_bf16 v[112:115], v[170:173], v[186:189], v[112:115]
	v_mfma_f32_16x16x32_bf16 v[104:107], v[178:181], v[186:189], v[104:107]
	v_mfma_f32_16x16x32_bf16 v[96:99], v[170:173], v[194:197], v[96:99]
	v_mfma_f32_16x16x32_bf16 v[88:91], v[178:181], v[194:197], v[88:91]
	v_mfma_f32_16x16x32_bf16 v[80:83], v[170:173], v[202:205], v[80:83]
	v_mfma_f32_16x16x32_bf16 v[72:75], v[178:181], v[202:205], v[72:75]
	v_mfma_f32_16x16x32_bf16 v[68:71], v[170:173], v[210:213], v[68:71]
	v_mfma_f32_16x16x32_bf16 v[64:67], v[178:181], v[210:213], v[64:67]
	v_mfma_f32_16x16x32_bf16 v[112:115], v[174:177], v[190:193], v[112:115]
	v_mfma_f32_16x16x32_bf16 v[104:107], v[182:185], v[190:193], v[104:107]
	v_mfma_f32_16x16x32_bf16 v[96:99], v[174:177], v[198:201], v[96:99]
	v_mfma_f32_16x16x32_bf16 v[88:91], v[182:185], v[198:201], v[88:91]
	v_mfma_f32_16x16x32_bf16 v[80:83], v[174:177], v[206:209], v[80:83]
	v_mfma_f32_16x16x32_bf16 v[72:75], v[182:185], v[206:209], v[72:75]
	v_mfma_f32_16x16x32_bf16 v[68:71], v[174:177], v[214:217], v[68:71]
	v_mfma_f32_16x16x32_bf16 v[64:67], v[182:185], v[214:217], v[64:67]
	s_barrier
	s_add_i32 s33, s33, s38
	v_lshl_add_u64 v[150:151], v[150:151], 0, s[10:11]
	s_mov_b32 m0, s33
	ds_read_b128 v[186:189], v146 offset:49152
	ds_read_b128 v[190:193], v146 offset:50176
	ds_read_b128 v[194:197], v146 offset:51200
	ds_read_b128 v[198:201], v146 offset:52224
	ds_read_b128 v[202:205], v146 offset:53248
	ds_read_b128 v[206:209], v146 offset:54272
	ds_read_b128 v[210:213], v146 offset:55296
	ds_read_b128 v[214:217], v146 offset:56320
	global_load_lds_dwordx4 v[150:151], off
	s_add_i32 m0, s33, 0x2000
	s_add_u32 s30, s30, 0x80080
	v_lshl_add_u64 v[150:151], v[218:219], 0, s[10:11]
	s_addc_u32 s31, s31, 0
	s_add_i32 s33, s51, s38
	global_load_lds_dwordx4 v[150:151], off
	v_lshl_add_u64 v[150:151], s[30:31], 0, v[130:131]
	s_mov_b32 m0, s33
	s_nop 0
	global_load_lds_dwordx4 v[150:151], off
	v_lshl_add_u64 v[150:151], s[30:31], 0, v[134:135]
	s_add_i32 m0, s33, 0x2000
	s_nop 0
	global_load_lds_dwordx4 v[150:151], off
	v_lshl_add_u64 v[150:151], v[222:223], 0, s[10:11]
	s_mov_b32 m0, s41
	s_nop 0
	global_load_lds_dwordx4 v[150:151], off
	v_lshl_add_u64 v[150:151], v[224:225], 0, s[10:11]
	s_mov_b32 m0, s42
	s_nop 0
	global_load_lds_dwordx4 v[150:151], off
	s_waitcnt vmcnt(8)
	s_waitcnt lgkmcnt(0)
	s_barrier
	s_waitcnt lgkmcnt(0)
	v_mfma_f32_16x16x32_bf16 v[60:63], v[154:157], v[186:189], v[60:63]
	v_mfma_f32_16x16x32_bf16 v[56:59], v[162:165], v[186:189], v[56:59]
	v_mfma_f32_16x16x32_bf16 v[52:55], v[154:157], v[194:197], v[52:55]
	v_mfma_f32_16x16x32_bf16 v[44:47], v[162:165], v[194:197], v[44:47]
	v_mfma_f32_16x16x32_bf16 v[36:39], v[154:157], v[202:205], v[36:39]
	v_mfma_f32_16x16x32_bf16 v[28:31], v[162:165], v[202:205], v[28:31]
	v_mfma_f32_16x16x32_bf16 v[20:23], v[154:157], v[210:213], v[20:23]
	v_mfma_f32_16x16x32_bf16 v[12:15], v[162:165], v[210:213], v[12:15]
	v_mfma_f32_16x16x32_bf16 v[60:63], v[158:161], v[190:193], v[60:63]
	v_mfma_f32_16x16x32_bf16 v[56:59], v[166:169], v[190:193], v[56:59]
	v_mfma_f32_16x16x32_bf16 v[52:55], v[158:161], v[198:201], v[52:55]
	v_mfma_f32_16x16x32_bf16 v[44:47], v[166:169], v[198:201], v[44:47]
	v_mfma_f32_16x16x32_bf16 v[36:39], v[158:161], v[206:209], v[36:39]
	v_mfma_f32_16x16x32_bf16 v[28:31], v[166:169], v[206:209], v[28:31]
	v_mfma_f32_16x16x32_bf16 v[20:23], v[158:161], v[214:217], v[20:23]
	v_mfma_f32_16x16x32_bf16 v[12:15], v[166:169], v[214:217], v[12:15]
	v_mfma_f32_16x16x32_bf16 v[48:51], v[170:173], v[186:189], v[48:51]
	v_mfma_f32_16x16x32_bf16 v[40:43], v[178:181], v[186:189], v[40:43]
	v_mfma_f32_16x16x32_bf16 v[32:35], v[170:173], v[194:197], v[32:35]
	v_mfma_f32_16x16x32_bf16 v[24:27], v[178:181], v[194:197], v[24:27]
	v_mfma_f32_16x16x32_bf16 v[16:19], v[170:173], v[202:205], v[16:19]
	v_mfma_f32_16x16x32_bf16 v[8:11], v[178:181], v[202:205], v[8:11]
	v_mfma_f32_16x16x32_bf16 v[4:7], v[170:173], v[210:213], v[4:7]
	v_mfma_f32_16x16x32_bf16 v[0:3], v[178:181], v[210:213], v[0:3]
	v_mfma_f32_16x16x32_bf16 v[48:51], v[174:177], v[190:193], v[48:51]
	v_mfma_f32_16x16x32_bf16 v[40:43], v[182:185], v[190:193], v[40:43]
	v_mfma_f32_16x16x32_bf16 v[32:35], v[174:177], v[198:201], v[32:35]
	v_mfma_f32_16x16x32_bf16 v[24:27], v[182:185], v[198:201], v[24:27]
	v_mfma_f32_16x16x32_bf16 v[16:19], v[174:177], v[206:209], v[16:19]
	v_mfma_f32_16x16x32_bf16 v[8:11], v[182:185], v[206:209], v[8:11]
	v_mfma_f32_16x16x32_bf16 v[4:7], v[174:177], v[214:217], v[4:7]
	v_mfma_f32_16x16x32_bf16 v[0:3], v[182:185], v[214:217], v[0:3]
	s_barrier
	s_add_i32 s50, s50, 2
	s_add_u32 s28, s28, 0x100
	s_addc_u32 s29, s29, 0
	s_add_u32 s48, s48, 0x100
	s_addc_u32 s49, s49, 0
	s_cmp_gt_u32 s50, 29
	s_cbranch_scc0 .LBB0_363
	s_and_b64 vcc, exec, s[12:13]
	s_cbranch_vccz .LBB0_366
	s_barrier

.LBB0_530:
	ds_read_b128 v[150:153], v147
	ds_read_b128 v[154:157], v147 offset:1024
	ds_read_b128 v[158:161], v147 offset:2048
	ds_read_b128 v[162:165], v147 offset:3072
	ds_read_b128 v[166:169], v148
	ds_read_b128 v[170:173], v148 offset:1024
	ds_read_b128 v[174:177], v148 offset:2048
	ds_read_b128 v[178:181], v148 offset:3072
	s_add_u32 s22, s20, 0xfff80080
	s_addc_u32 s23, s21, -1
	s_cmp_eq_u32 s44, 28
	s_cselect_b32 s25, s11, s23
	s_cselect_b32 s24, s40, s22
	s_cselect_b32 s23, s13, s43
	s_cselect_b32 s22, s41, s42
	v_lshl_add_u64 v[214:215], s[20:21], 0, v[136:137]
	s_add_i32 m0, s19, 0xc000
	ds_read_b128 v[182:185], v149
	ds_read_b128 v[186:189], v149 offset:1024
	ds_read_b128 v[190:193], v149 offset:2048
	ds_read_b128 v[194:197], v149 offset:3072
	ds_read_b128 v[198:201], v149 offset:4096
	ds_read_b128 v[202:205], v149 offset:5120
	ds_read_b128 v[206:209], v149 offset:6144
	ds_read_b128 v[210:213], v149 offset:7168
	global_load_lds_dwordx4 v[214:215], off
	v_lshl_add_u64 v[214:215], s[20:21], 0, v[138:139]
	s_add_i32 m0, s19, 0xe000
	s_nop 0
	global_load_lds_dwordx4 v[214:215], off
	s_waitcnt vmcnt(8)
	s_waitcnt lgkmcnt(0)
	s_barrier
	s_waitcnt lgkmcnt(0)
	v_mfma_f32_16x16x32_bf16 v[124:127], v[150:153], v[182:185], v[124:127]
	v_mfma_f32_16x16x32_bf16 v[120:123], v[158:161], v[182:185], v[120:123]
	v_mfma_f32_16x16x32_bf16 v[116:119], v[150:153], v[190:193], v[116:119]
	v_mfma_f32_16x16x32_bf16 v[108:111], v[158:161], v[190:193], v[108:111]
	v_mfma_f32_16x16x32_bf16 v[100:103], v[150:153], v[198:201], v[100:103]
	v_mfma_f32_16x16x32_bf16 v[92:95], v[158:161], v[198:201], v[92:95]
	v_mfma_f32_16x16x32_bf16 v[84:87], v[150:153], v[206:209], v[84:87]
	v_mfma_f32_16x16x32_bf16 v[76:79], v[158:161], v[206:209], v[76:79]
	v_mfma_f32_16x16x32_bf16 v[124:127], v[154:157], v[186:189], v[124:127]
	v_mfma_f32_16x16x32_bf16 v[120:123], v[162:165], v[186:189], v[120:123]
	v_mfma_f32_16x16x32_bf16 v[116:119], v[154:157], v[194:197], v[116:119]
	v_mfma_f32_16x16x32_bf16 v[108:111], v[162:165], v[194:197], v[108:111]
	v_mfma_f32_16x16x32_bf16 v[100:103], v[154:157], v[202:205], v[100:103]
	v_mfma_f32_16x16x32_bf16 v[92:95], v[162:165], v[202:205], v[92:95]
	v_mfma_f32_16x16x32_bf16 v[84:87], v[154:157], v[210:213], v[84:87]
	v_mfma_f32_16x16x32_bf16 v[76:79], v[162:165], v[210:213], v[76:79]
	v_mfma_f32_16x16x32_bf16 v[112:115], v[166:169], v[182:185], v[112:115]
	v_mfma_f32_16x16x32_bf16 v[104:107], v[174:177], v[182:185], v[104:107]
	v_mfma_f32_16x16x32_bf16 v[96:99], v[166:169], v[190:193], v[96:99]
	v_mfma_f32_16x16x32_bf16 v[88:91], v[174:177], v[190:193], v[88:91]
	v_mfma_f32_16x16x32_bf16 v[80:83], v[166:169], v[198:201], v[80:83]
	v_mfma_f32_16x16x32_bf16 v[72:75], v[174:177], v[198:201], v[72:75]
	v_mfma_f32_16x16x32_bf16 v[68:71], v[166:169], v[206:209], v[68:71]
	v_mfma_f32_16x16x32_bf16 v[64:67], v[174:177], v[206:209], v[64:67]
	v_mfma_f32_16x16x32_bf16 v[112:115], v[170:173], v[186:189], v[112:115]
	v_mfma_f32_16x16x32_bf16 v[104:107], v[178:181], v[186:189], v[104:107]
	v_mfma_f32_16x16x32_bf16 v[96:99], v[170:173], v[194:197], v[96:99]
	v_mfma_f32_16x16x32_bf16 v[88:91], v[178:181], v[194:197], v[88:91]
	v_mfma_f32_16x16x32_bf16 v[80:83], v[170:173], v[202:205], v[80:83]
	v_mfma_f32_16x16x32_bf16 v[72:75], v[178:181], v[202:205], v[72:75]
	v_mfma_f32_16x16x32_bf16 v[68:71], v[170:173], v[210:213], v[68:71]
	v_mfma_f32_16x16x32_bf16 v[64:67], v[178:181], v[210:213], v[64:67]
	s_barrier
	s_add_i32 s33, s35, s27
	v_lshl_add_u64 v[214:215], s[22:23], 0, v[130:131]
	s_mov_b32 m0, s33
	ds_read_b128 v[182:185], v149 offset:16384
	ds_read_b128 v[186:189], v149 offset:17408
	ds_read_b128 v[190:193], v149 offset:18432
	ds_read_b128 v[194:197], v149 offset:19456
	ds_read_b128 v[198:201], v149 offset:20480
	ds_read_b128 v[202:205], v149 offset:21504
	ds_read_b128 v[206:209], v149 offset:22528
	ds_read_b128 v[210:213], v149 offset:23552
	global_load_lds_dwordx4 v[214:215], off
	s_add_i32 m0, s33, 0x2000
	s_add_u32 s46, s22, 0x80000
	v_lshl_add_u64 v[216:217], s[22:23], 0, v[134:135]
	s_addc_u32 s47, s23, 0
	s_add_i32 s33, s37, s27
	global_load_lds_dwordx4 v[216:217], off
	v_lshl_add_u64 v[218:219], s[46:47], 0, v[130:131]
	s_mov_b32 m0, s33
	v_lshl_add_u64 v[222:223], s[24:25], 0, v[132:133]
	global_load_lds_dwordx4 v[218:219], off
	v_lshl_add_u64 v[218:219], s[46:47], 0, v[134:135]
	s_add_i32 m0, s33, 0x2000
	s_nop 0
	global_load_lds_dwordx4 v[218:219], off
	v_lshl_add_u64 v[218:219], s[24:25], 0, v[128:129]
	s_mov_b32 m0, s19
	s_nop 0
	global_load_lds_dwordx4 v[218:219], off
	s_mov_b32 m0, s28
	s_nop 0
	global_load_lds_dwordx4 v[222:223], off
	s_waitcnt vmcnt(8)
	s_waitcnt lgkmcnt(0)
	s_barrier
	s_waitcnt lgkmcnt(0)
	v_mfma_f32_16x16x32_bf16 v[60:63], v[150:153], v[182:185], v[60:63]
	v_mfma_f32_16x16x32_bf16 v[56:59], v[158:161], v[182:185], v[56:59]
	v_mfma_f32_16x16x32_bf16 v[52:55], v[150:153], v[190:193], v[52:55]
	v_mfma_f32_16x16x32_bf16 v[44:47], v[158:161], v[190:193], v[44:47]
	v_mfma_f32_16x16x32_bf16 v[36:39], v[150:153], v[198:201], v[36:39]
	v_mfma_f32_16x16x32_bf16 v[28:31], v[158:161], v[198:201], v[28:31]
	v_mfma_f32_16x16x32_bf16 v[20:23], v[150:153], v[206:209], v[20:23]
	v_mfma_f32_16x16x32_bf16 v[12:15], v[158:161], v[206:209], v[12:15]
	v_mfma_f32_16x16x32_bf16 v[60:63], v[154:157], v[186:189], v[60:63]
	v_mfma_f32_16x16x32_bf16 v[56:59], v[162:165], v[186:189], v[56:59]
	v_mfma_f32_16x16x32_bf16 v[52:55], v[154:157], v[194:197], v[52:55]
	v_mfma_f32_16x16x32_bf16 v[44:47], v[162:165], v[194:197], v[44:47]
	v_mfma_f32_16x16x32_bf16 v[36:39], v[154:157], v[202:205], v[36:39]
	v_mfma_f32_16x16x32_bf16 v[28:31], v[162:165], v[202:205], v[28:31]
	v_mfma_f32_16x16x32_bf16 v[20:23], v[154:157], v[210:213], v[20:23]
	v_mfma_f32_16x16x32_bf16 v[12:15], v[162:165], v[210:213], v[12:15]
	v_mfma_f32_16x16x32_bf16 v[48:51], v[166:169], v[182:185], v[48:51]
	v_mfma_f32_16x16x32_bf16 v[40:43], v[174:177], v[182:185], v[40:43]
	v_mfma_f32_16x16x32_bf16 v[32:35], v[166:169], v[190:193], v[32:35]
	v_mfma_f32_16x16x32_bf16 v[24:27], v[174:177], v[190:193], v[24:27]
	v_mfma_f32_16x16x32_bf16 v[16:19], v[166:169], v[198:201], v[16:19]
	v_mfma_f32_16x16x32_bf16 v[8:11], v[174:177], v[198:201], v[8:11]
	v_mfma_f32_16x16x32_bf16 v[4:7], v[166:169], v[206:209], v[4:7]
	v_mfma_f32_16x16x32_bf16 v[0:3], v[174:177], v[206:209], v[0:3]
	v_mfma_f32_16x16x32_bf16 v[48:51], v[170:173], v[186:189], v[48:51]
	v_mfma_f32_16x16x32_bf16 v[40:43], v[178:181], v[186:189], v[40:43]
	v_mfma_f32_16x16x32_bf16 v[32:35], v[170:173], v[194:197], v[32:35]
	v_mfma_f32_16x16x32_bf16 v[24:27], v[178:181], v[194:197], v[24:27]
	v_mfma_f32_16x16x32_bf16 v[16:19], v[170:173], v[202:205], v[16:19]
	v_mfma_f32_16x16x32_bf16 v[8:11], v[178:181], v[202:205], v[8:11]
	v_mfma_f32_16x16x32_bf16 v[4:7], v[170:173], v[210:213], v[4:7]
	v_mfma_f32_16x16x32_bf16 v[0:3], v[178:181], v[210:213], v[0:3]
	s_barrier
	s_add_i32 s33, 0, 0x18000
	s_add_i32 s36, 0, 0x1c000
	v_add_u32_e32 v162, s33, v145
	v_add_u32_e32 v178, s36, v145
	ds_read_b128 v[150:153], v162
	ds_read_b128 v[154:157], v162 offset:1024
	ds_read_b128 v[158:161], v162 offset:2048
	ds_read_b128 v[162:165], v162 offset:3072
	ds_read_b128 v[166:169], v178
	ds_read_b128 v[170:173], v178 offset:1024
	ds_read_b128 v[174:177], v178 offset:2048
	ds_read_b128 v[178:181], v178 offset:3072
	s_add_u32 s24, s24, 0x80000
	s_addc_u32 s25, s25, 0
	s_mov_b32 m0, s29
	v_lshl_add_u64 v[224:225], s[24:25], 0, v[128:129]
	ds_read_b128 v[182:185], v149 offset:32768
	ds_read_b128 v[186:189], v149 offset:33792
	ds_read_b128 v[190:193], v149 offset:34816
	ds_read_b128 v[194:197], v149 offset:35840
	ds_read_b128 v[198:201], v149 offset:36864
	ds_read_b128 v[202:205], v149 offset:37888
	ds_read_b128 v[206:209], v149 offset:38912
	ds_read_b128 v[210:213], v149 offset:39936
	global_load_lds_dwordx4 v[224:225], off
	v_lshl_add_u64 v[224:225], s[24:25], 0, v[132:133]
	s_mov_b32 m0, s30
	s_nop 0
	global_load_lds_dwordx4 v[224:225], off
	s_waitcnt vmcnt(8)
	s_waitcnt lgkmcnt(0)
	s_barrier
	s_waitcnt lgkmcnt(0)
	v_mfma_f32_16x16x32_bf16 v[124:127], v[150:153], v[182:185], v[124:127]
	v_mfma_f32_16x16x32_bf16 v[120:123], v[158:161], v[182:185], v[120:123]
	v_mfma_f32_16x16x32_bf16 v[116:119], v[150:153], v[190:193], v[116:119]
	v_mfma_f32_16x16x32_bf16 v[108:111], v[158:161], v[190:193], v[108:111]
	v_mfma_f32_16x16x32_bf16 v[100:103], v[150:153], v[198:201], v[100:103]
	v_mfma_f32_16x16x32_bf16 v[92:95], v[158:161], v[198:201], v[92:95]
	v_mfma_f32_16x16x32_bf16 v[84:87], v[150:153], v[206:209], v[84:87]
	v_mfma_f32_16x16x32_bf16 v[76:79], v[158:161], v[206:209], v[76:79]
	v_mfma_f32_16x16x32_bf16 v[124:127], v[154:157], v[186:189], v[124:127]
	v_mfma_f32_16x16x32_bf16 v[120:123], v[162:165], v[186:189], v[120:123]
	v_mfma_f32_16x16x32_bf16 v[116:119], v[154:157], v[194:197], v[116:119]
	v_mfma_f32_16x16x32_bf16 v[108:111], v[162:165], v[194:197], v[108:111]
	v_mfma_f32_16x16x32_bf16 v[100:103], v[154:157], v[202:205], v[100:103]
	v_mfma_f32_16x16x32_bf16 v[92:95], v[162:165], v[202:205], v[92:95]
	v_mfma_f32_16x16x32_bf16 v[84:87], v[154:157], v[210:213], v[84:87]
	v_mfma_f32_16x16x32_bf16 v[76:79], v[162:165], v[210:213], v[76:79]
	v_mfma_f32_16x16x32_bf16 v[112:115], v[166:169], v[182:185], v[112:115]
	v_mfma_f32_16x16x32_bf16 v[104:107], v[174:177], v[182:185], v[104:107]
	v_mfma_f32_16x16x32_bf16 v[96:99], v[166:169], v[190:193], v[96:99]
	v_mfma_f32_16x16x32_bf16 v[88:91], v[174:177], v[190:193], v[88:91]
	v_mfma_f32_16x16x32_bf16 v[80:83], v[166:169], v[198:201], v[80:83]
	v_mfma_f32_16x16x32_bf16 v[72:75], v[174:177], v[198:201], v[72:75]
	v_mfma_f32_16x16x32_bf16 v[68:71], v[166:169], v[206:209], v[68:71]
	v_mfma_f32_16x16x32_bf16 v[64:67], v[174:177], v[206:209], v[64:67]
	v_mfma_f32_16x16x32_bf16 v[112:115], v[170:173], v[186:189], v[112:115]
	v_mfma_f32_16x16x32_bf16 v[104:107], v[178:181], v[186:189], v[104:107]
	v_mfma_f32_16x16x32_bf16 v[96:99], v[170:173], v[194:197], v[96:99]
	v_mfma_f32_16x16x32_bf16 v[88:91], v[178:181], v[194:197], v[88:91]
	v_mfma_f32_16x16x32_bf16 v[80:83], v[170:173], v[202:205], v[80:83]
	v_mfma_f32_16x16x32_bf16 v[72:75], v[178:181], v[202:205], v[72:75]
	v_mfma_f32_16x16x32_bf16 v[68:71], v[170:173], v[210:213], v[68:71]
	v_mfma_f32_16x16x32_bf16 v[64:67], v[178:181], v[210:213], v[64:67]
	s_barrier
	s_add_i32 s24, s33, s27
	v_lshl_add_u64 v[214:215], v[214:215], 0, s[6:7]
	s_mov_b32 m0, s24
	ds_read_b128 v[182:185], v149 offset:49152
	ds_read_b128 v[186:189], v149 offset:50176
	ds_read_b128 v[190:193], v149 offset:51200
	ds_read_b128 v[194:197], v149 offset:52224
	ds_read_b128 v[198:201], v149 offset:53248
	ds_read_b128 v[202:205], v149 offset:54272
	ds_read_b128 v[206:209], v149 offset:55296
	ds_read_b128 v[210:213], v149 offset:56320
	global_load_lds_dwordx4 v[214:215], off
	s_add_i32 m0, s24, 0x2000
	s_add_u32 s22, s22, 0x80080
	v_lshl_add_u64 v[214:215], v[216:217], 0, s[6:7]
	s_addc_u32 s23, s23, 0
	s_add_i32 s24, s36, s27
	global_load_lds_dwordx4 v[214:215], off
	v_lshl_add_u64 v[214:215], s[22:23], 0, v[130:131]
	s_mov_b32 m0, s24
	s_nop 0
	global_load_lds_dwordx4 v[214:215], off
	v_lshl_add_u64 v[214:215], s[22:23], 0, v[134:135]
	s_add_i32 m0, s24, 0x2000
	s_nop 0
	global_load_lds_dwordx4 v[214:215], off
	v_lshl_add_u64 v[214:215], v[218:219], 0, s[6:7]
	s_mov_b32 m0, s31
	s_nop 0
	global_load_lds_dwordx4 v[214:215], off
	v_lshl_add_u64 v[214:215], v[222:223], 0, s[6:7]
	s_mov_b32 m0, s34
	s_nop 0
	global_load_lds_dwordx4 v[214:215], off
	s_waitcnt vmcnt(8)
	s_waitcnt lgkmcnt(0)
	s_barrier
	s_waitcnt lgkmcnt(0)
	v_mfma_f32_16x16x32_bf16 v[60:63], v[150:153], v[182:185], v[60:63]
	v_mfma_f32_16x16x32_bf16 v[56:59], v[158:161], v[182:185], v[56:59]
	v_mfma_f32_16x16x32_bf16 v[52:55], v[150:153], v[190:193], v[52:55]
	v_mfma_f32_16x16x32_bf16 v[44:47], v[158:161], v[190:193], v[44:47]
	v_mfma_f32_16x16x32_bf16 v[36:39], v[150:153], v[198:201], v[36:39]
	v_mfma_f32_16x16x32_bf16 v[28:31], v[158:161], v[198:201], v[28:31]
	v_mfma_f32_16x16x32_bf16 v[20:23], v[150:153], v[206:209], v[20:23]
	v_mfma_f32_16x16x32_bf16 v[12:15], v[158:161], v[206:209], v[12:15]
	v_mfma_f32_16x16x32_bf16 v[60:63], v[154:157], v[186:189], v[60:63]
	v_mfma_f32_16x16x32_bf16 v[56:59], v[162:165], v[186:189], v[56:59]
	v_mfma_f32_16x16x32_bf16 v[52:55], v[154:157], v[194:197], v[52:55]
	v_mfma_f32_16x16x32_bf16 v[44:47], v[162:165], v[194:197], v[44:47]
	v_mfma_f32_16x16x32_bf16 v[36:39], v[154:157], v[202:205], v[36:39]
	v_mfma_f32_16x16x32_bf16 v[28:31], v[162:165], v[202:205], v[28:31]
	v_mfma_f32_16x16x32_bf16 v[20:23], v[154:157], v[210:213], v[20:23]
	v_mfma_f32_16x16x32_bf16 v[12:15], v[162:165], v[210:213], v[12:15]
	v_mfma_f32_16x16x32_bf16 v[48:51], v[166:169], v[182:185], v[48:51]
	v_mfma_f32_16x16x32_bf16 v[40:43], v[174:177], v[182:185], v[40:43]
	v_mfma_f32_16x16x32_bf16 v[32:35], v[166:169], v[190:193], v[32:35]
	v_mfma_f32_16x16x32_bf16 v[24:27], v[174:177], v[190:193], v[24:27]
	v_mfma_f32_16x16x32_bf16 v[16:19], v[166:169], v[198:201], v[16:19]
	v_mfma_f32_16x16x32_bf16 v[8:11], v[174:177], v[198:201], v[8:11]
	v_mfma_f32_16x16x32_bf16 v[4:7], v[166:169], v[206:209], v[4:7]
	v_mfma_f32_16x16x32_bf16 v[0:3], v[174:177], v[206:209], v[0:3]
	v_mfma_f32_16x16x32_bf16 v[48:51], v[170:173], v[186:189], v[48:51]
	v_mfma_f32_16x16x32_bf16 v[40:43], v[178:181], v[186:189], v[40:43]
	v_mfma_f32_16x16x32_bf16 v[32:35], v[170:173], v[194:197], v[32:35]
	v_mfma_f32_16x16x32_bf16 v[24:27], v[178:181], v[194:197], v[24:27]
	v_mfma_f32_16x16x32_bf16 v[16:19], v[170:173], v[202:205], v[16:19]
	v_mfma_f32_16x16x32_bf16 v[8:11], v[178:181], v[202:205], v[8:11]
	v_mfma_f32_16x16x32_bf16 v[4:7], v[170:173], v[210:213], v[4:7]
	v_mfma_f32_16x16x32_bf16 v[0:3], v[178:181], v[210:213], v[0:3]
	s_barrier
	s_add_i32 s44, s44, 2
	s_add_u32 s20, s20, 0x100
	s_addc_u32 s21, s21, 0
	s_add_u32 s42, s42, 0x100
	s_addc_u32 s43, s43, 0
	s_cmp_gt_u32 s44, 29
	s_cbranch_scc0 .LBB0_530
	s_and_b64 vcc, exec, s[8:9]
	s_cbranch_vccz .LBB0_533
	s_barrier

.LBB0_601:
	ds_read_b128 v[148:151], v145
	ds_read_b128 v[152:155], v145 offset:1024
	ds_read_b128 v[156:159], v145 offset:2048
	ds_read_b128 v[160:163], v145 offset:3072
	ds_read_b128 v[164:167], v146
	ds_read_b128 v[168:171], v146 offset:1024
	ds_read_b128 v[172:175], v146 offset:2048
	ds_read_b128 v[176:179], v146 offset:3072
	s_add_u32 s33, s34, 0xfff80080
	s_addc_u32 s36, s35, -1
	s_cmp_eq_u32 s56, 28
	s_cselect_b32 s39, s25, s36
	s_cselect_b32 s38, s52, s33
	s_cselect_b32 s37, s23, s55
	s_cselect_b32 s36, s53, s54
	v_lshl_add_u64 v[140:141], s[34:35], 0, v[132:133]
	s_add_i32 m0, s31, 0xc000
	ds_read_b128 v[180:183], v147
	ds_read_b128 v[184:187], v147 offset:1024
	ds_read_b128 v[188:191], v147 offset:2048
	ds_read_b128 v[192:195], v147 offset:3072
	ds_read_b128 v[196:199], v147 offset:4096
	ds_read_b128 v[200:203], v147 offset:5120
	ds_read_b128 v[204:207], v147 offset:6144
	ds_read_b128 v[208:211], v147 offset:7168
	global_load_lds_dwordx4 v[140:141], off
	v_lshl_add_u64 v[140:141], s[34:35], 0, v[134:135]
	s_add_i32 m0, s31, 0xe000
	s_nop 0
	global_load_lds_dwordx4 v[140:141], off
	s_waitcnt vmcnt(8)
	s_waitcnt lgkmcnt(0)
	s_barrier
	s_waitcnt lgkmcnt(0)
	v_mfma_f32_16x16x32_bf16 v[124:127], v[148:151], v[180:183], v[124:127]
	v_mfma_f32_16x16x32_bf16 v[120:123], v[156:159], v[180:183], v[120:123]
	v_mfma_f32_16x16x32_bf16 v[112:115], v[148:151], v[188:191], v[112:115]
	v_mfma_f32_16x16x32_bf16 v[108:111], v[156:159], v[188:191], v[108:111]
	v_mfma_f32_16x16x32_bf16 v[96:99], v[148:151], v[196:199], v[96:99]
	v_mfma_f32_16x16x32_bf16 v[92:95], v[156:159], v[196:199], v[92:95]
	v_mfma_f32_16x16x32_bf16 v[80:83], v[148:151], v[204:207], v[80:83]
	v_mfma_f32_16x16x32_bf16 v[76:79], v[156:159], v[204:207], v[76:79]
	v_mfma_f32_16x16x32_bf16 v[124:127], v[152:155], v[184:187], v[124:127]
	v_mfma_f32_16x16x32_bf16 v[120:123], v[160:163], v[184:187], v[120:123]
	v_mfma_f32_16x16x32_bf16 v[112:115], v[152:155], v[192:195], v[112:115]
	v_mfma_f32_16x16x32_bf16 v[108:111], v[160:163], v[192:195], v[108:111]
	v_mfma_f32_16x16x32_bf16 v[96:99], v[152:155], v[200:203], v[96:99]
	v_mfma_f32_16x16x32_bf16 v[92:95], v[160:163], v[200:203], v[92:95]
	v_mfma_f32_16x16x32_bf16 v[80:83], v[152:155], v[208:211], v[80:83]
	v_mfma_f32_16x16x32_bf16 v[76:79], v[160:163], v[208:211], v[76:79]
	v_mfma_f32_16x16x32_bf16 v[116:119], v[164:167], v[180:183], v[116:119]
	v_mfma_f32_16x16x32_bf16 v[104:107], v[172:175], v[180:183], v[104:107]
	v_mfma_f32_16x16x32_bf16 v[100:103], v[164:167], v[188:191], v[100:103]
	v_mfma_f32_16x16x32_bf16 v[88:91], v[172:175], v[188:191], v[88:91]
	v_mfma_f32_16x16x32_bf16 v[84:87], v[164:167], v[196:199], v[84:87]
	v_mfma_f32_16x16x32_bf16 v[72:75], v[172:175], v[196:199], v[72:75]
	v_mfma_f32_16x16x32_bf16 v[68:71], v[164:167], v[204:207], v[68:71]
	v_mfma_f32_16x16x32_bf16 v[64:67], v[172:175], v[204:207], v[64:67]
	v_mfma_f32_16x16x32_bf16 v[116:119], v[168:171], v[184:187], v[116:119]
	v_mfma_f32_16x16x32_bf16 v[104:107], v[176:179], v[184:187], v[104:107]
	v_mfma_f32_16x16x32_bf16 v[100:103], v[168:171], v[192:195], v[100:103]
	v_mfma_f32_16x16x32_bf16 v[88:91], v[176:179], v[192:195], v[88:91]
	v_mfma_f32_16x16x32_bf16 v[84:87], v[168:171], v[200:203], v[84:87]
	v_mfma_f32_16x16x32_bf16 v[72:75], v[176:179], v[200:203], v[72:75]
	v_mfma_f32_16x16x32_bf16 v[68:71], v[168:171], v[208:211], v[68:71]
	v_mfma_f32_16x16x32_bf16 v[64:67], v[176:179], v[208:211], v[64:67]
	s_barrier
	s_add_i32 s33, s49, s41
	v_lshl_add_u64 v[140:141], s[36:37], 0, v[128:129]
	s_mov_b32 m0, s33
	ds_read_b128 v[180:183], v147 offset:16384
	ds_read_b128 v[184:187], v147 offset:17408
	ds_read_b128 v[188:191], v147 offset:18432
	ds_read_b128 v[192:195], v147 offset:19456
	ds_read_b128 v[196:199], v147 offset:20480
	ds_read_b128 v[200:203], v147 offset:21504
	ds_read_b128 v[204:207], v147 offset:22528
	ds_read_b128 v[208:211], v147 offset:23552
	global_load_lds_dwordx4 v[140:141], off
	s_add_i32 m0, s33, 0x2000
	s_add_u32 s58, s36, 0x80000
	v_lshl_add_u64 v[212:213], s[36:37], 0, v[130:131]
	s_addc_u32 s59, s37, 0
	s_add_i32 s33, s50, s41
	global_load_lds_dwordx4 v[212:213], off
	v_lshl_add_u64 v[214:215], s[58:59], 0, v[128:129]
	s_mov_b32 m0, s33
	v_lshl_add_u64 v[216:217], s[38:39], 0, v[130:131]
	global_load_lds_dwordx4 v[214:215], off
	v_lshl_add_u64 v[214:215], s[58:59], 0, v[130:131]
	s_add_i32 m0, s33, 0x2000
	s_nop 0
	global_load_lds_dwordx4 v[214:215], off
	v_lshl_add_u64 v[214:215], s[38:39], 0, v[128:129]
	s_mov_b32 m0, s31
	s_nop 0
	global_load_lds_dwordx4 v[214:215], off
	s_mov_b32 m0, s42
	s_nop 0
	global_load_lds_dwordx4 v[216:217], off
	s_waitcnt vmcnt(8)
	s_waitcnt lgkmcnt(0)
	s_barrier
	s_waitcnt lgkmcnt(0)
	v_mfma_f32_16x16x32_bf16 v[60:63], v[148:151], v[180:183], v[60:63]
	v_mfma_f32_16x16x32_bf16 v[56:59], v[156:159], v[180:183], v[56:59]
	v_mfma_f32_16x16x32_bf16 v[48:51], v[148:151], v[188:191], v[48:51]
	v_mfma_f32_16x16x32_bf16 v[44:47], v[156:159], v[188:191], v[44:47]
	v_mfma_f32_16x16x32_bf16 v[32:35], v[148:151], v[196:199], v[32:35]
	v_mfma_f32_16x16x32_bf16 v[28:31], v[156:159], v[196:199], v[28:31]
	v_mfma_f32_16x16x32_bf16 v[16:19], v[148:151], v[204:207], v[16:19]
	v_mfma_f32_16x16x32_bf16 v[12:15], v[156:159], v[204:207], v[12:15]
	v_mfma_f32_16x16x32_bf16 v[60:63], v[152:155], v[184:187], v[60:63]
	v_mfma_f32_16x16x32_bf16 v[56:59], v[160:163], v[184:187], v[56:59]
	v_mfma_f32_16x16x32_bf16 v[48:51], v[152:155], v[192:195], v[48:51]
	v_mfma_f32_16x16x32_bf16 v[44:47], v[160:163], v[192:195], v[44:47]
	v_mfma_f32_16x16x32_bf16 v[32:35], v[152:155], v[200:203], v[32:35]
	v_mfma_f32_16x16x32_bf16 v[28:31], v[160:163], v[200:203], v[28:31]
	v_mfma_f32_16x16x32_bf16 v[16:19], v[152:155], v[208:211], v[16:19]
	v_mfma_f32_16x16x32_bf16 v[12:15], v[160:163], v[208:211], v[12:15]
	v_mfma_f32_16x16x32_bf16 v[52:55], v[164:167], v[180:183], v[52:55]
	v_mfma_f32_16x16x32_bf16 v[40:43], v[172:175], v[180:183], v[40:43]
	v_mfma_f32_16x16x32_bf16 v[36:39], v[164:167], v[188:191], v[36:39]
	v_mfma_f32_16x16x32_bf16 v[24:27], v[172:175], v[188:191], v[24:27]
	v_mfma_f32_16x16x32_bf16 v[20:23], v[164:167], v[196:199], v[20:23]
	v_mfma_f32_16x16x32_bf16 v[8:11], v[172:175], v[196:199], v[8:11]
	v_mfma_f32_16x16x32_bf16 v[4:7], v[164:167], v[204:207], v[4:7]
	v_mfma_f32_16x16x32_bf16 v[0:3], v[172:175], v[204:207], v[0:3]
	v_mfma_f32_16x16x32_bf16 v[52:55], v[168:171], v[184:187], v[52:55]
	v_mfma_f32_16x16x32_bf16 v[40:43], v[176:179], v[184:187], v[40:43]
	v_mfma_f32_16x16x32_bf16 v[36:39], v[168:171], v[192:195], v[36:39]
	v_mfma_f32_16x16x32_bf16 v[24:27], v[176:179], v[192:195], v[24:27]
	v_mfma_f32_16x16x32_bf16 v[20:23], v[168:171], v[200:203], v[20:23]
	v_mfma_f32_16x16x32_bf16 v[8:11], v[176:179], v[200:203], v[8:11]
	v_mfma_f32_16x16x32_bf16 v[4:7], v[168:171], v[208:211], v[4:7]
	v_mfma_f32_16x16x32_bf16 v[0:3], v[176:179], v[208:211], v[0:3]
	s_barrier
	s_add_i32 s33, 0, 0x18000
	s_add_i32 s57, 0, 0x1c000
	v_add_u32_e32 v160, s33, v143
	v_add_u32_e32 v176, s57, v143
	ds_read_b128 v[148:151], v160
	ds_read_b128 v[152:155], v160 offset:1024
	ds_read_b128 v[156:159], v160 offset:2048
	ds_read_b128 v[160:163], v160 offset:3072
	ds_read_b128 v[164:167], v176
	ds_read_b128 v[168:171], v176 offset:1024
	ds_read_b128 v[172:175], v176 offset:2048
	ds_read_b128 v[176:179], v176 offset:3072
	s_add_u32 s38, s38, 0x80000
	s_addc_u32 s39, s39, 0
	s_mov_b32 m0, s43
	v_lshl_add_u64 v[218:219], s[38:39], 0, v[128:129]
	ds_read_b128 v[180:183], v147 offset:32768
	ds_read_b128 v[184:187], v147 offset:33792
	ds_read_b128 v[188:191], v147 offset:34816
	ds_read_b128 v[192:195], v147 offset:35840
	ds_read_b128 v[196:199], v147 offset:36864
	ds_read_b128 v[200:203], v147 offset:37888
	ds_read_b128 v[204:207], v147 offset:38912
	ds_read_b128 v[208:211], v147 offset:39936
	global_load_lds_dwordx4 v[218:219], off
	v_lshl_add_u64 v[218:219], s[38:39], 0, v[130:131]
	s_mov_b32 m0, s44
	s_nop 0
	global_load_lds_dwordx4 v[218:219], off
	s_waitcnt vmcnt(8)
	s_waitcnt lgkmcnt(0)
	s_barrier
	s_waitcnt lgkmcnt(0)
	v_mfma_f32_16x16x32_bf16 v[124:127], v[148:151], v[180:183], v[124:127]
	v_mfma_f32_16x16x32_bf16 v[120:123], v[156:159], v[180:183], v[120:123]
	v_mfma_f32_16x16x32_bf16 v[112:115], v[148:151], v[188:191], v[112:115]
	v_mfma_f32_16x16x32_bf16 v[108:111], v[156:159], v[188:191], v[108:111]
	v_mfma_f32_16x16x32_bf16 v[96:99], v[148:151], v[196:199], v[96:99]
	v_mfma_f32_16x16x32_bf16 v[92:95], v[156:159], v[196:199], v[92:95]
	v_mfma_f32_16x16x32_bf16 v[80:83], v[148:151], v[204:207], v[80:83]
	v_mfma_f32_16x16x32_bf16 v[76:79], v[156:159], v[204:207], v[76:79]
	v_mfma_f32_16x16x32_bf16 v[124:127], v[152:155], v[184:187], v[124:127]
	v_mfma_f32_16x16x32_bf16 v[120:123], v[160:163], v[184:187], v[120:123]
	v_mfma_f32_16x16x32_bf16 v[112:115], v[152:155], v[192:195], v[112:115]
	v_mfma_f32_16x16x32_bf16 v[108:111], v[160:163], v[192:195], v[108:111]
	v_mfma_f32_16x16x32_bf16 v[96:99], v[152:155], v[200:203], v[96:99]
	v_mfma_f32_16x16x32_bf16 v[92:95], v[160:163], v[200:203], v[92:95]
	v_mfma_f32_16x16x32_bf16 v[80:83], v[152:155], v[208:211], v[80:83]
	v_mfma_f32_16x16x32_bf16 v[76:79], v[160:163], v[208:211], v[76:79]
	v_mfma_f32_16x16x32_bf16 v[116:119], v[164:167], v[180:183], v[116:119]
	v_mfma_f32_16x16x32_bf16 v[104:107], v[172:175], v[180:183], v[104:107]
	v_mfma_f32_16x16x32_bf16 v[100:103], v[164:167], v[188:191], v[100:103]
	v_mfma_f32_16x16x32_bf16 v[88:91], v[172:175], v[188:191], v[88:91]
	v_mfma_f32_16x16x32_bf16 v[84:87], v[164:167], v[196:199], v[84:87]
	v_mfma_f32_16x16x32_bf16 v[72:75], v[172:175], v[196:199], v[72:75]
	v_mfma_f32_16x16x32_bf16 v[68:71], v[164:167], v[204:207], v[68:71]
	v_mfma_f32_16x16x32_bf16 v[64:67], v[172:175], v[204:207], v[64:67]
	v_mfma_f32_16x16x32_bf16 v[116:119], v[168:171], v[184:187], v[116:119]
	v_mfma_f32_16x16x32_bf16 v[104:107], v[176:179], v[184:187], v[104:107]
	v_mfma_f32_16x16x32_bf16 v[100:103], v[168:171], v[192:195], v[100:103]
	v_mfma_f32_16x16x32_bf16 v[88:91], v[176:179], v[192:195], v[88:91]
	v_mfma_f32_16x16x32_bf16 v[84:87], v[168:171], v[200:203], v[84:87]
	v_mfma_f32_16x16x32_bf16 v[72:75], v[176:179], v[200:203], v[72:75]
	v_mfma_f32_16x16x32_bf16 v[68:71], v[168:171], v[208:211], v[68:71]
	v_mfma_f32_16x16x32_bf16 v[64:67], v[176:179], v[208:211], v[64:67]
	s_barrier
	s_add_i32 s33, s33, s41
	v_lshl_add_u64 v[140:141], v[140:141], 0, s[6:7]
	s_mov_b32 m0, s33
	ds_read_b128 v[180:183], v147 offset:49152
	ds_read_b128 v[184:187], v147 offset:50176
	ds_read_b128 v[188:191], v147 offset:51200
	ds_read_b128 v[192:195], v147 offset:52224
	ds_read_b128 v[196:199], v147 offset:53248
	ds_read_b128 v[200:203], v147 offset:54272
	ds_read_b128 v[204:207], v147 offset:55296
	ds_read_b128 v[208:211], v147 offset:56320
	global_load_lds_dwordx4 v[140:141], off
	s_add_i32 m0, s33, 0x2000
	s_add_u32 s36, s36, 0x80080
	v_lshl_add_u64 v[140:141], v[212:213], 0, s[6:7]
	s_addc_u32 s37, s37, 0
	s_add_i32 s33, s57, s41
	global_load_lds_dwordx4 v[140:141], off
	v_lshl_add_u64 v[140:141], s[36:37], 0, v[128:129]
	s_mov_b32 m0, s33
	s_nop 0
	global_load_lds_dwordx4 v[140:141], off
	v_lshl_add_u64 v[140:141], s[36:37], 0, v[130:131]
	s_add_i32 m0, s33, 0x2000
	s_nop 0
	global_load_lds_dwordx4 v[140:141], off
	v_lshl_add_u64 v[140:141], v[214:215], 0, s[6:7]
	s_mov_b32 m0, s46
	s_nop 0
	global_load_lds_dwordx4 v[140:141], off
	v_lshl_add_u64 v[140:141], v[216:217], 0, s[6:7]
	s_mov_b32 m0, s47
	s_nop 0
	global_load_lds_dwordx4 v[140:141], off
	s_waitcnt vmcnt(8)
	s_waitcnt lgkmcnt(0)
	s_barrier
	s_waitcnt lgkmcnt(0)
	v_mfma_f32_16x16x32_bf16 v[60:63], v[148:151], v[180:183], v[60:63]
	v_mfma_f32_16x16x32_bf16 v[56:59], v[156:159], v[180:183], v[56:59]
	v_mfma_f32_16x16x32_bf16 v[48:51], v[148:151], v[188:191], v[48:51]
	v_mfma_f32_16x16x32_bf16 v[44:47], v[156:159], v[188:191], v[44:47]
	v_mfma_f32_16x16x32_bf16 v[32:35], v[148:151], v[196:199], v[32:35]
	v_mfma_f32_16x16x32_bf16 v[28:31], v[156:159], v[196:199], v[28:31]
	v_mfma_f32_16x16x32_bf16 v[16:19], v[148:151], v[204:207], v[16:19]
	v_mfma_f32_16x16x32_bf16 v[12:15], v[156:159], v[204:207], v[12:15]
	v_mfma_f32_16x16x32_bf16 v[60:63], v[152:155], v[184:187], v[60:63]
	v_mfma_f32_16x16x32_bf16 v[56:59], v[160:163], v[184:187], v[56:59]
	v_mfma_f32_16x16x32_bf16 v[48:51], v[152:155], v[192:195], v[48:51]
	v_mfma_f32_16x16x32_bf16 v[44:47], v[160:163], v[192:195], v[44:47]
	v_mfma_f32_16x16x32_bf16 v[32:35], v[152:155], v[200:203], v[32:35]
	v_mfma_f32_16x16x32_bf16 v[28:31], v[160:163], v[200:203], v[28:31]
	v_mfma_f32_16x16x32_bf16 v[16:19], v[152:155], v[208:211], v[16:19]
	v_mfma_f32_16x16x32_bf16 v[12:15], v[160:163], v[208:211], v[12:15]
	v_mfma_f32_16x16x32_bf16 v[52:55], v[164:167], v[180:183], v[52:55]
	v_mfma_f32_16x16x32_bf16 v[40:43], v[172:175], v[180:183], v[40:43]
	v_mfma_f32_16x16x32_bf16 v[36:39], v[164:167], v[188:191], v[36:39]
	v_mfma_f32_16x16x32_bf16 v[24:27], v[172:175], v[188:191], v[24:27]
	v_mfma_f32_16x16x32_bf16 v[20:23], v[164:167], v[196:199], v[20:23]
	v_mfma_f32_16x16x32_bf16 v[8:11], v[172:175], v[196:199], v[8:11]
	v_mfma_f32_16x16x32_bf16 v[4:7], v[164:167], v[204:207], v[4:7]
	v_mfma_f32_16x16x32_bf16 v[0:3], v[172:175], v[204:207], v[0:3]
	v_mfma_f32_16x16x32_bf16 v[52:55], v[168:171], v[184:187], v[52:55]
	v_mfma_f32_16x16x32_bf16 v[40:43], v[176:179], v[184:187], v[40:43]
	v_mfma_f32_16x16x32_bf16 v[36:39], v[168:171], v[192:195], v[36:39]
	v_mfma_f32_16x16x32_bf16 v[24:27], v[176:179], v[192:195], v[24:27]
	v_mfma_f32_16x16x32_bf16 v[20:23], v[168:171], v[200:203], v[20:23]
	v_mfma_f32_16x16x32_bf16 v[8:11], v[176:179], v[200:203], v[8:11]
	v_mfma_f32_16x16x32_bf16 v[4:7], v[168:171], v[208:211], v[4:7]
	v_mfma_f32_16x16x32_bf16 v[0:3], v[176:179], v[208:211], v[0:3]
	s_barrier
	s_add_i32 s56, s56, 2
	s_add_u32 s34, s34, 0x100
	s_addc_u32 s35, s35, 0
	s_add_u32 s54, s54, 0x100
	s_addc_u32 s55, s55, 0
	s_cmp_gt_u32 s56, 29
	s_cbranch_scc0 .LBB0_601
	s_and_b64 vcc, exec, s[10:11]
	s_cbranch_vccz .LBB0_604
	s_barrier

.LBB0_625:
	v_add_u32_e32 v147, s45, v145
	ds_read_b128 v[148:151], v147
	ds_read_b128 v[152:155], v147 offset:1024
	ds_read_b128 v[156:159], v147 offset:2048
	ds_read_b128 v[160:163], v147 offset:3072
	v_add_u32_e32 v147, s46, v145
	s_add_u32 s26, s10, s24
	ds_read_b128 v[164:167], v147
	ds_read_b128 v[168:171], v147 offset:1024
	ds_read_b128 v[172:175], v147 offset:2048
	ds_read_b128 v[178:181], v147 offset:3072
	s_addc_u32 s27, s11, s25
	s_add_u32 s26, s26, 0x100
	s_addc_u32 s27, s27, 0
	s_add_u32 s33, s21, s24
	s_addc_u32 s51, s47, s25
	s_cmpk_eq_i32 s24, 0xf00
	s_cselect_b32 s29, s17, s27
	s_cselect_b32 s28, s48, s26
	s_cselect_b32 s27, s15, s51
	s_cselect_b32 s26, s49, s33
	v_lshl_add_u64 v[214:215], v[140:141], 0, s[24:25]
	s_add_i32 m0, s37, 0xc000
	ds_read_b128 v[182:185], v146
	ds_read_b128 v[186:189], v146 offset:1024
	ds_read_b128 v[190:193], v146 offset:2048
	ds_read_b128 v[194:197], v146 offset:3072
	ds_read_b128 v[198:201], v146 offset:4096
	ds_read_b128 v[202:205], v146 offset:5120
	ds_read_b128 v[206:209], v146 offset:6144
	ds_read_b128 v[210:213], v146 offset:7168
	global_load_lds_dwordx4 v[214:215], off
	v_lshl_add_u64 v[214:215], v[142:143], 0, s[24:25]
	s_add_i32 m0, s37, 0xe000
	s_nop 0
	global_load_lds_dwordx4 v[214:215], off
	s_waitcnt vmcnt(8)
	s_waitcnt lgkmcnt(0)
	s_barrier
	s_waitcnt lgkmcnt(0)
	v_mfma_f32_16x16x32_bf16 v[124:127], v[148:151], v[182:185], v[124:127]
	v_mfma_f32_16x16x32_bf16 v[120:123], v[156:159], v[182:185], v[120:123]
	v_mfma_f32_16x16x32_bf16 v[108:111], v[148:151], v[190:193], v[108:111]
	v_mfma_f32_16x16x32_bf16 v[104:107], v[156:159], v[190:193], v[104:107]
	v_mfma_f32_16x16x32_bf16 v[92:95], v[148:151], v[198:201], v[92:95]
	v_mfma_f32_16x16x32_bf16 v[88:91], v[156:159], v[198:201], v[88:91]
	v_mfma_f32_16x16x32_bf16 v[76:79], v[148:151], v[206:209], v[76:79]
	v_mfma_f32_16x16x32_bf16 v[72:75], v[156:159], v[206:209], v[72:75]
	v_mfma_f32_16x16x32_bf16 v[124:127], v[152:155], v[186:189], v[124:127]
	v_mfma_f32_16x16x32_bf16 v[120:123], v[160:163], v[186:189], v[120:123]
	v_mfma_f32_16x16x32_bf16 v[108:111], v[152:155], v[194:197], v[108:111]
	v_mfma_f32_16x16x32_bf16 v[104:107], v[160:163], v[194:197], v[104:107]
	v_mfma_f32_16x16x32_bf16 v[92:95], v[152:155], v[202:205], v[92:95]
	v_mfma_f32_16x16x32_bf16 v[88:91], v[160:163], v[202:205], v[88:91]
	v_mfma_f32_16x16x32_bf16 v[76:79], v[152:155], v[210:213], v[76:79]
	v_mfma_f32_16x16x32_bf16 v[72:75], v[160:163], v[210:213], v[72:75]
	v_mfma_f32_16x16x32_bf16 v[116:119], v[164:167], v[182:185], v[116:119]
	v_mfma_f32_16x16x32_bf16 v[112:115], v[172:175], v[182:185], v[112:115]
	v_mfma_f32_16x16x32_bf16 v[100:103], v[164:167], v[190:193], v[100:103]
	v_mfma_f32_16x16x32_bf16 v[96:99], v[172:175], v[190:193], v[96:99]
	v_mfma_f32_16x16x32_bf16 v[84:87], v[164:167], v[198:201], v[84:87]
	v_mfma_f32_16x16x32_bf16 v[80:83], v[172:175], v[198:201], v[80:83]
	v_mfma_f32_16x16x32_bf16 v[68:71], v[164:167], v[206:209], v[68:71]
	v_mfma_f32_16x16x32_bf16 v[64:67], v[172:175], v[206:209], v[64:67]
	v_mfma_f32_16x16x32_bf16 v[116:119], v[168:171], v[186:189], v[116:119]
	v_mfma_f32_16x16x32_bf16 v[112:115], v[178:181], v[186:189], v[112:115]
	v_mfma_f32_16x16x32_bf16 v[100:103], v[168:171], v[194:197], v[100:103]
	v_mfma_f32_16x16x32_bf16 v[96:99], v[178:181], v[194:197], v[96:99]
	v_mfma_f32_16x16x32_bf16 v[84:87], v[168:171], v[202:205], v[84:87]
	v_mfma_f32_16x16x32_bf16 v[80:83], v[178:181], v[202:205], v[80:83]
	v_mfma_f32_16x16x32_bf16 v[68:71], v[168:171], v[210:213], v[68:71]
	v_mfma_f32_16x16x32_bf16 v[64:67], v[178:181], v[210:213], v[64:67]
	s_barrier
	s_add_i32 s33, s45, s36
	v_lshl_add_u64 v[214:215], s[26:27], 0, v[128:129]
	s_mov_b32 m0, s33
	ds_read_b128 v[182:185], v146 offset:16384
	ds_read_b128 v[186:189], v146 offset:17408
	ds_read_b128 v[190:193], v146 offset:18432
	ds_read_b128 v[194:197], v146 offset:19456
	ds_read_b128 v[198:201], v146 offset:20480
	ds_read_b128 v[202:205], v146 offset:21504
	ds_read_b128 v[206:209], v146 offset:22528
	ds_read_b128 v[210:213], v146 offset:23552
	global_load_lds_dwordx4 v[214:215], off
	s_add_i32 m0, s33, 0x2000
	s_add_u32 s52, s26, 0x80000
	v_lshl_add_u64 v[216:217], s[26:27], 0, v[130:131]
	s_addc_u32 s53, s27, 0
	s_add_i32 s33, s46, s36
	global_load_lds_dwordx4 v[216:217], off
	v_lshl_add_u64 v[218:219], s[52:53], 0, v[128:129]
	s_mov_b32 m0, s33
	v_lshl_add_u64 v[222:223], s[28:29], 0, v[130:131]
	global_load_lds_dwordx4 v[218:219], off
	v_lshl_add_u64 v[218:219], s[52:53], 0, v[130:131]
	s_add_i32 m0, s33, 0x2000
	s_nop 0
	global_load_lds_dwordx4 v[218:219], off
	v_lshl_add_u64 v[218:219], s[28:29], 0, v[128:129]
	s_mov_b32 m0, s37
	s_nop 0
	global_load_lds_dwordx4 v[218:219], off
	s_mov_b32 m0, s38
	s_nop 0
	global_load_lds_dwordx4 v[222:223], off
	s_waitcnt vmcnt(8)
	s_waitcnt lgkmcnt(0)
	s_barrier
	s_waitcnt lgkmcnt(0)
	v_mfma_f32_16x16x32_bf16 v[60:63], v[148:151], v[182:185], v[60:63]
	v_mfma_f32_16x16x32_bf16 v[56:59], v[156:159], v[182:185], v[56:59]
	v_mfma_f32_16x16x32_bf16 v[44:47], v[148:151], v[190:193], v[44:47]
	v_mfma_f32_16x16x32_bf16 v[40:43], v[156:159], v[190:193], v[40:43]
	v_mfma_f32_16x16x32_bf16 v[28:31], v[148:151], v[198:201], v[28:31]
	v_mfma_f32_16x16x32_bf16 v[24:27], v[156:159], v[198:201], v[24:27]
	v_mfma_f32_16x16x32_bf16 v[12:15], v[148:151], v[206:209], v[12:15]
	v_mfma_f32_16x16x32_bf16 v[8:11], v[156:159], v[206:209], v[8:11]
	v_mfma_f32_16x16x32_bf16 v[60:63], v[152:155], v[186:189], v[60:63]
	v_mfma_f32_16x16x32_bf16 v[56:59], v[160:163], v[186:189], v[56:59]
	v_mfma_f32_16x16x32_bf16 v[44:47], v[152:155], v[194:197], v[44:47]
	v_mfma_f32_16x16x32_bf16 v[40:43], v[160:163], v[194:197], v[40:43]
	v_mfma_f32_16x16x32_bf16 v[28:31], v[152:155], v[202:205], v[28:31]
	v_mfma_f32_16x16x32_bf16 v[24:27], v[160:163], v[202:205], v[24:27]
	v_mfma_f32_16x16x32_bf16 v[12:15], v[152:155], v[210:213], v[12:15]
	v_mfma_f32_16x16x32_bf16 v[8:11], v[160:163], v[210:213], v[8:11]
	v_mfma_f32_16x16x32_bf16 v[52:55], v[164:167], v[182:185], v[52:55]
	v_mfma_f32_16x16x32_bf16 v[48:51], v[172:175], v[182:185], v[48:51]
	v_mfma_f32_16x16x32_bf16 v[36:39], v[164:167], v[190:193], v[36:39]
	v_mfma_f32_16x16x32_bf16 v[32:35], v[172:175], v[190:193], v[32:35]
	v_mfma_f32_16x16x32_bf16 v[20:23], v[164:167], v[198:201], v[20:23]
	v_mfma_f32_16x16x32_bf16 v[16:19], v[172:175], v[198:201], v[16:19]
	v_mfma_f32_16x16x32_bf16 v[4:7], v[164:167], v[206:209], v[4:7]
	v_mfma_f32_16x16x32_bf16 v[0:3], v[172:175], v[206:209], v[0:3]
	v_mfma_f32_16x16x32_bf16 v[52:55], v[168:171], v[186:189], v[52:55]
	v_mfma_f32_16x16x32_bf16 v[48:51], v[178:181], v[186:189], v[48:51]
	v_mfma_f32_16x16x32_bf16 v[36:39], v[168:171], v[194:197], v[36:39]
	v_mfma_f32_16x16x32_bf16 v[32:35], v[178:181], v[194:197], v[32:35]
	v_mfma_f32_16x16x32_bf16 v[20:23], v[168:171], v[202:205], v[20:23]
	v_mfma_f32_16x16x32_bf16 v[16:19], v[178:181], v[202:205], v[16:19]
	v_mfma_f32_16x16x32_bf16 v[4:7], v[168:171], v[210:213], v[4:7]
	v_mfma_f32_16x16x32_bf16 v[0:3], v[178:181], v[210:213], v[0:3]
	s_barrier
	s_add_i32 s33, 0, 0x18000
	v_add_u32_e32 v147, s33, v145
	s_add_i32 s51, 0, 0x1c000
	ds_read_b128 v[148:151], v147
	ds_read_b128 v[152:155], v147 offset:1024
	ds_read_b128 v[156:159], v147 offset:2048
	ds_read_b128 v[160:163], v147 offset:3072
	v_add_u32_e32 v147, s51, v145
	ds_read_b128 v[164:167], v147
	ds_read_b128 v[168:171], v147 offset:1024
	ds_read_b128 v[172:175], v147 offset:2048
	ds_read_b128 v[178:181], v147 offset:3072
	s_add_u32 s28, s28, 0x80000
	s_addc_u32 s29, s29, 0
	s_mov_b32 m0, s39
	v_lshl_add_u64 v[224:225], s[28:29], 0, v[128:129]
	ds_read_b128 v[182:185], v146 offset:32768
	ds_read_b128 v[186:189], v146 offset:33792
	ds_read_b128 v[190:193], v146 offset:34816
	ds_read_b128 v[194:197], v146 offset:35840
	ds_read_b128 v[198:201], v146 offset:36864
	ds_read_b128 v[202:205], v146 offset:37888
	ds_read_b128 v[206:209], v146 offset:38912
	ds_read_b128 v[210:213], v146 offset:39936
	global_load_lds_dwordx4 v[224:225], off
	v_lshl_add_u64 v[224:225], s[28:29], 0, v[130:131]
	s_mov_b32 m0, s41
	s_nop 0
	global_load_lds_dwordx4 v[224:225], off
	s_waitcnt vmcnt(8)
	s_waitcnt lgkmcnt(0)
	s_barrier
	s_waitcnt lgkmcnt(0)
	v_mfma_f32_16x16x32_bf16 v[124:127], v[148:151], v[182:185], v[124:127]
	v_mfma_f32_16x16x32_bf16 v[120:123], v[156:159], v[182:185], v[120:123]
	v_mfma_f32_16x16x32_bf16 v[108:111], v[148:151], v[190:193], v[108:111]
	v_mfma_f32_16x16x32_bf16 v[104:107], v[156:159], v[190:193], v[104:107]
	v_mfma_f32_16x16x32_bf16 v[92:95], v[148:151], v[198:201], v[92:95]
	v_mfma_f32_16x16x32_bf16 v[88:91], v[156:159], v[198:201], v[88:91]
	v_mfma_f32_16x16x32_bf16 v[76:79], v[148:151], v[206:209], v[76:79]
	v_mfma_f32_16x16x32_bf16 v[72:75], v[156:159], v[206:209], v[72:75]
	v_mfma_f32_16x16x32_bf16 v[124:127], v[152:155], v[186:189], v[124:127]
	v_mfma_f32_16x16x32_bf16 v[120:123], v[160:163], v[186:189], v[120:123]
	v_mfma_f32_16x16x32_bf16 v[108:111], v[152:155], v[194:197], v[108:111]
	v_mfma_f32_16x16x32_bf16 v[104:107], v[160:163], v[194:197], v[104:107]
	v_mfma_f32_16x16x32_bf16 v[92:95], v[152:155], v[202:205], v[92:95]
	v_mfma_f32_16x16x32_bf16 v[88:91], v[160:163], v[202:205], v[88:91]
	v_mfma_f32_16x16x32_bf16 v[76:79], v[152:155], v[210:213], v[76:79]
	v_mfma_f32_16x16x32_bf16 v[72:75], v[160:163], v[210:213], v[72:75]
	v_mfma_f32_16x16x32_bf16 v[116:119], v[164:167], v[182:185], v[116:119]
	v_mfma_f32_16x16x32_bf16 v[112:115], v[172:175], v[182:185], v[112:115]
	v_mfma_f32_16x16x32_bf16 v[100:103], v[164:167], v[190:193], v[100:103]
	v_mfma_f32_16x16x32_bf16 v[96:99], v[172:175], v[190:193], v[96:99]
	v_mfma_f32_16x16x32_bf16 v[84:87], v[164:167], v[198:201], v[84:87]
	v_mfma_f32_16x16x32_bf16 v[80:83], v[172:175], v[198:201], v[80:83]
	v_mfma_f32_16x16x32_bf16 v[68:71], v[164:167], v[206:209], v[68:71]
	v_mfma_f32_16x16x32_bf16 v[64:67], v[172:175], v[206:209], v[64:67]
	v_mfma_f32_16x16x32_bf16 v[116:119], v[168:171], v[186:189], v[116:119]
	v_mfma_f32_16x16x32_bf16 v[112:115], v[178:181], v[186:189], v[112:115]
	v_mfma_f32_16x16x32_bf16 v[100:103], v[168:171], v[194:197], v[100:103]
	v_mfma_f32_16x16x32_bf16 v[96:99], v[178:181], v[194:197], v[96:99]
	v_mfma_f32_16x16x32_bf16 v[84:87], v[168:171], v[202:205], v[84:87]
	v_mfma_f32_16x16x32_bf16 v[80:83], v[178:181], v[202:205], v[80:83]
	v_mfma_f32_16x16x32_bf16 v[68:71], v[168:171], v[210:213], v[68:71]
	v_mfma_f32_16x16x32_bf16 v[64:67], v[178:181], v[210:213], v[64:67]
	s_barrier
	s_add_i32 s28, s33, s36
	v_lshl_add_u64 v[214:215], v[214:215], 0, s[12:13]
	s_mov_b32 m0, s28
	ds_read_b128 v[182:185], v146 offset:49152
	ds_read_b128 v[186:189], v146 offset:50176
	ds_read_b128 v[190:193], v146 offset:51200
	ds_read_b128 v[194:197], v146 offset:52224
	ds_read_b128 v[198:201], v146 offset:53248
	ds_read_b128 v[202:205], v146 offset:54272
	ds_read_b128 v[206:209], v146 offset:55296
	ds_read_b128 v[210:213], v146 offset:56320
	global_load_lds_dwordx4 v[214:215], off
	s_add_i32 m0, s28, 0x2000
	s_add_u32 s26, s26, 0x80080
	v_lshl_add_u64 v[214:215], v[216:217], 0, s[12:13]
	s_addc_u32 s27, s27, 0
	s_add_i32 s28, s51, s36
	global_load_lds_dwordx4 v[214:215], off
	v_lshl_add_u64 v[214:215], s[26:27], 0, v[128:129]
	s_mov_b32 m0, s28
	s_nop 0
	global_load_lds_dwordx4 v[214:215], off
	v_lshl_add_u64 v[214:215], s[26:27], 0, v[130:131]
	s_add_i32 m0, s28, 0x2000
	s_nop 0
	global_load_lds_dwordx4 v[214:215], off
	v_lshl_add_u64 v[214:215], v[218:219], 0, s[12:13]
	s_mov_b32 m0, s42
	s_nop 0
	global_load_lds_dwordx4 v[214:215], off
	v_lshl_add_u64 v[214:215], v[222:223], 0, s[12:13]
	s_mov_b32 m0, s43
	s_nop 0
	global_load_lds_dwordx4 v[214:215], off
	s_waitcnt vmcnt(8)
	s_waitcnt lgkmcnt(0)
	s_barrier
	s_waitcnt lgkmcnt(0)
	v_mfma_f32_16x16x32_bf16 v[60:63], v[148:151], v[182:185], v[60:63]
	v_mfma_f32_16x16x32_bf16 v[56:59], v[156:159], v[182:185], v[56:59]
	v_mfma_f32_16x16x32_bf16 v[44:47], v[148:151], v[190:193], v[44:47]
	v_mfma_f32_16x16x32_bf16 v[40:43], v[156:159], v[190:193], v[40:43]
	v_mfma_f32_16x16x32_bf16 v[28:31], v[148:151], v[198:201], v[28:31]
	v_mfma_f32_16x16x32_bf16 v[24:27], v[156:159], v[198:201], v[24:27]
	v_mfma_f32_16x16x32_bf16 v[12:15], v[148:151], v[206:209], v[12:15]
	v_mfma_f32_16x16x32_bf16 v[8:11], v[156:159], v[206:209], v[8:11]
	v_mfma_f32_16x16x32_bf16 v[60:63], v[152:155], v[186:189], v[60:63]
	v_mfma_f32_16x16x32_bf16 v[56:59], v[160:163], v[186:189], v[56:59]
	v_mfma_f32_16x16x32_bf16 v[44:47], v[152:155], v[194:197], v[44:47]
	v_mfma_f32_16x16x32_bf16 v[40:43], v[160:163], v[194:197], v[40:43]
	v_mfma_f32_16x16x32_bf16 v[28:31], v[152:155], v[202:205], v[28:31]
	v_mfma_f32_16x16x32_bf16 v[24:27], v[160:163], v[202:205], v[24:27]
	v_mfma_f32_16x16x32_bf16 v[12:15], v[152:155], v[210:213], v[12:15]
	v_mfma_f32_16x16x32_bf16 v[8:11], v[160:163], v[210:213], v[8:11]
	v_mfma_f32_16x16x32_bf16 v[52:55], v[164:167], v[182:185], v[52:55]
	v_mfma_f32_16x16x32_bf16 v[48:51], v[172:175], v[182:185], v[48:51]
	v_mfma_f32_16x16x32_bf16 v[36:39], v[164:167], v[190:193], v[36:39]
	v_mfma_f32_16x16x32_bf16 v[32:35], v[172:175], v[190:193], v[32:35]
	v_mfma_f32_16x16x32_bf16 v[20:23], v[164:167], v[198:201], v[20:23]
	v_mfma_f32_16x16x32_bf16 v[16:19], v[172:175], v[198:201], v[16:19]
	v_mfma_f32_16x16x32_bf16 v[4:7], v[164:167], v[206:209], v[4:7]
	v_mfma_f32_16x16x32_bf16 v[0:3], v[172:175], v[206:209], v[0:3]
	v_mfma_f32_16x16x32_bf16 v[52:55], v[168:171], v[186:189], v[52:55]
	v_mfma_f32_16x16x32_bf16 v[48:51], v[178:181], v[186:189], v[48:51]
	v_mfma_f32_16x16x32_bf16 v[36:39], v[168:171], v[194:197], v[36:39]
	v_mfma_f32_16x16x32_bf16 v[32:35], v[178:181], v[194:197], v[32:35]
	v_mfma_f32_16x16x32_bf16 v[20:23], v[168:171], v[202:205], v[20:23]
	v_mfma_f32_16x16x32_bf16 v[16:19], v[178:181], v[202:205], v[16:19]
	v_mfma_f32_16x16x32_bf16 v[4:7], v[168:171], v[210:213], v[4:7]
	v_mfma_f32_16x16x32_bf16 v[0:3], v[178:181], v[210:213], v[0:3]
	s_barrier
	s_add_i32 s50, s50, 2
	s_add_u32 s24, s24, 0x100
	s_addc_u32 s25, s25, 0
	s_cmp_gt_u32 s50, 29
	s_cbranch_scc0 .LBB0_625
	s_add_u32 s24, s21, 0xffffff00
	s_addc_u32 s25, s47, -1
	s_andn2_b64 vcc, exec, s[2:3]
	s_cbranch_vccnz .LBB0_628
	v_mov_b32_e32 v0, 0
	s_mov_b32 s31, s14
	s_mov_b32 s6, s16
	s_mov_b64 s[10:11], s[22:23]
	s_mov_b32 s44, s20
	v_mov_b32_e32 v1, v0
	v_mov_b32_e32 v2, v0
	v_mov_b32_e32 v3, v0
	v_mov_b32_e32 v4, v0
	v_mov_b32_e32 v5, v0
	v_mov_b32_e32 v6, v0
	v_mov_b32_e32 v7, v0
	v_mov_b32_e32 v16, v0
	v_mov_b32_e32 v17, v0
	v_mov_b32_e32 v18, v0
	v_mov_b32_e32 v19, v0
	v_mov_b32_e32 v20, v0
	v_mov_b32_e32 v21, v0
	v_mov_b32_e32 v22, v0
	v_mov_b32_e32 v23, v0
	v_mov_b32_e32 v32, v0
	v_mov_b32_e32 v33, v0
	v_mov_b32_e32 v34, v0
	v_mov_b32_e32 v35, v0
	v_mov_b32_e32 v36, v0
	v_mov_b32_e32 v37, v0
	v_mov_b32_e32 v38, v0
	v_mov_b32_e32 v39, v0
	v_mov_b32_e32 v48, v0
	v_mov_b32_e32 v49, v0
	v_mov_b32_e32 v50, v0
	v_mov_b32_e32 v51, v0
	v_mov_b32_e32 v52, v0
	v_mov_b32_e32 v53, v0
	v_mov_b32_e32 v54, v0
	v_mov_b32_e32 v55, v0
	v_mov_b32_e32 v8, v0
	v_mov_b32_e32 v9, v0
	v_mov_b32_e32 v10, v0
	v_mov_b32_e32 v11, v0
	v_mov_b32_e32 v12, v0
	v_mov_b32_e32 v13, v0
	v_mov_b32_e32 v14, v0
	v_mov_b32_e32 v15, v0
	v_mov_b32_e32 v24, v0
	v_mov_b32_e32 v25, v0
	v_mov_b32_e32 v26, v0
	v_mov_b32_e32 v27, v0
	v_mov_b32_e32 v28, v0
	v_mov_b32_e32 v29, v0
	v_mov_b32_e32 v30, v0
	v_mov_b32_e32 v31, v0
	v_mov_b32_e32 v40, v0
	v_mov_b32_e32 v41, v0
	v_mov_b32_e32 v42, v0
	v_mov_b32_e32 v43, v0
	v_mov_b32_e32 v44, v0
	v_mov_b32_e32 v45, v0
	v_mov_b32_e32 v46, v0
	v_mov_b32_e32 v47, v0
	v_mov_b32_e32 v56, v0
	v_mov_b32_e32 v57, v0
	v_mov_b32_e32 v58, v0
	v_mov_b32_e32 v59, v0
	v_mov_b32_e32 v60, v0
	v_mov_b32_e32 v61, v0
	v_mov_b32_e32 v62, v0
	v_mov_b32_e32 v63, v0
	v_mov_b32_e32 v64, v0
	v_mov_b32_e32 v65, v0
	v_mov_b32_e32 v66, v0
	v_mov_b32_e32 v67, v0
	v_mov_b32_e32 v68, v0
	v_mov_b32_e32 v69, v0
	v_mov_b32_e32 v70, v0
	v_mov_b32_e32 v71, v0
	v_mov_b32_e32 v80, v0
	v_mov_b32_e32 v81, v0
	v_mov_b32_e32 v82, v0
	v_mov_b32_e32 v83, v0
	v_mov_b32_e32 v84, v0
	v_mov_b32_e32 v85, v0
	v_mov_b32_e32 v86, v0
	v_mov_b32_e32 v87, v0
	v_mov_b32_e32 v96, v0
	v_mov_b32_e32 v97, v0
	v_mov_b32_e32 v98, v0
	v_mov_b32_e32 v99, v0
	v_mov_b32_e32 v100, v0
	v_mov_b32_e32 v101, v0
	v_mov_b32_e32 v102, v0
	v_mov_b32_e32 v103, v0
	v_mov_b32_e32 v112, v0
	v_mov_b32_e32 v113, v0
	v_mov_b32_e32 v114, v0
	v_mov_b32_e32 v115, v0
	v_mov_b32_e32 v116, v0
	v_mov_b32_e32 v117, v0
	v_mov_b32_e32 v118, v0
	v_mov_b32_e32 v119, v0
	v_mov_b32_e32 v72, v0
	v_mov_b32_e32 v73, v0
	v_mov_b32_e32 v74, v0
	v_mov_b32_e32 v75, v0
	v_mov_b32_e32 v76, v0
	v_mov_b32_e32 v77, v0
	v_mov_b32_e32 v78, v0
	v_mov_b32_e32 v79, v0
	v_mov_b32_e32 v88, v0
	v_mov_b32_e32 v89, v0
	v_mov_b32_e32 v90, v0
	v_mov_b32_e32 v91, v0
	v_mov_b32_e32 v92, v0
	v_mov_b32_e32 v93, v0
	v_mov_b32_e32 v94, v0
	v_mov_b32_e32 v95, v0
	v_mov_b32_e32 v104, v0
	v_mov_b32_e32 v105, v0
	v_mov_b32_e32 v106, v0
	v_mov_b32_e32 v107, v0
	v_mov_b32_e32 v108, v0
	v_mov_b32_e32 v109, v0
	v_mov_b32_e32 v110, v0
	v_mov_b32_e32 v111, v0
	v_mov_b32_e32 v120, v0
	v_mov_b32_e32 v121, v0
	v_mov_b32_e32 v122, v0
	v_mov_b32_e32 v123, v0
	v_mov_b32_e32 v124, v0
	v_mov_b32_e32 v125, v0
	v_mov_b32_e32 v126, v0
	v_mov_b32_e32 v127, v0
	s_andn2_b64 vcc, exec, s[0:1]
	s_cbranch_vccnz .LBB0_629
	s_branch .LBB0_630

.LBB0_715:
	ds_read_b128 v[150:153], v147
	ds_read_b128 v[154:157], v147 offset:1024
	ds_read_b128 v[158:161], v147 offset:2048
	ds_read_b128 v[162:165], v147 offset:3072
	ds_read_b128 v[166:169], v148
	ds_read_b128 v[170:173], v148 offset:1024
	ds_read_b128 v[174:177], v148 offset:2048
	ds_read_b128 v[178:181], v148 offset:3072
	s_add_u32 s26, s24, 0xfff80080
	s_addc_u32 s27, s25, -1
	s_cmp_eq_u32 s51, 28
	s_cselect_b32 s29, s17, s27
	s_cselect_b32 s28, s47, s26
	s_cselect_b32 s27, s15, s50
	s_cselect_b32 s26, s48, s49
	v_lshl_add_u64 v[214:215], s[24:25], 0, v[136:137]
	s_add_i32 m0, s23, 0xc000
	ds_read_b128 v[182:185], v149
	ds_read_b128 v[186:189], v149 offset:1024
	ds_read_b128 v[190:193], v149 offset:2048
	ds_read_b128 v[194:197], v149 offset:3072
	ds_read_b128 v[198:201], v149 offset:4096
	ds_read_b128 v[202:205], v149 offset:5120
	ds_read_b128 v[206:209], v149 offset:6144
	ds_read_b128 v[210:213], v149 offset:7168
	global_load_lds_dwordx4 v[214:215], off
	v_lshl_add_u64 v[214:215], s[24:25], 0, v[138:139]
	s_add_i32 m0, s23, 0xe000
	s_nop 0
	global_load_lds_dwordx4 v[214:215], off
	s_waitcnt vmcnt(8)
	s_waitcnt lgkmcnt(0)
	s_barrier
	s_waitcnt lgkmcnt(0)
	v_mfma_f32_16x16x32_bf16 v[124:127], v[150:153], v[182:185], v[124:127]
	v_mfma_f32_16x16x32_bf16 v[120:123], v[158:161], v[182:185], v[120:123]
	v_mfma_f32_16x16x32_bf16 v[108:111], v[150:153], v[190:193], v[108:111]
	v_mfma_f32_16x16x32_bf16 v[104:107], v[158:161], v[190:193], v[104:107]
	v_mfma_f32_16x16x32_bf16 v[92:95], v[150:153], v[198:201], v[92:95]
	v_mfma_f32_16x16x32_bf16 v[88:91], v[158:161], v[198:201], v[88:91]
	v_mfma_f32_16x16x32_bf16 v[76:79], v[150:153], v[206:209], v[76:79]
	v_mfma_f32_16x16x32_bf16 v[72:75], v[158:161], v[206:209], v[72:75]
	v_mfma_f32_16x16x32_bf16 v[124:127], v[154:157], v[186:189], v[124:127]
	v_mfma_f32_16x16x32_bf16 v[120:123], v[162:165], v[186:189], v[120:123]
	v_mfma_f32_16x16x32_bf16 v[108:111], v[154:157], v[194:197], v[108:111]
	v_mfma_f32_16x16x32_bf16 v[104:107], v[162:165], v[194:197], v[104:107]
	v_mfma_f32_16x16x32_bf16 v[92:95], v[154:157], v[202:205], v[92:95]
	v_mfma_f32_16x16x32_bf16 v[88:91], v[162:165], v[202:205], v[88:91]
	v_mfma_f32_16x16x32_bf16 v[76:79], v[154:157], v[210:213], v[76:79]
	v_mfma_f32_16x16x32_bf16 v[72:75], v[162:165], v[210:213], v[72:75]
	v_mfma_f32_16x16x32_bf16 v[116:119], v[166:169], v[182:185], v[116:119]
	v_mfma_f32_16x16x32_bf16 v[112:115], v[174:177], v[182:185], v[112:115]
	v_mfma_f32_16x16x32_bf16 v[100:103], v[166:169], v[190:193], v[100:103]
	v_mfma_f32_16x16x32_bf16 v[96:99], v[174:177], v[190:193], v[96:99]
	v_mfma_f32_16x16x32_bf16 v[84:87], v[166:169], v[198:201], v[84:87]
	v_mfma_f32_16x16x32_bf16 v[80:83], v[174:177], v[198:201], v[80:83]
	v_mfma_f32_16x16x32_bf16 v[68:71], v[166:169], v[206:209], v[68:71]
	v_mfma_f32_16x16x32_bf16 v[64:67], v[174:177], v[206:209], v[64:67]
	v_mfma_f32_16x16x32_bf16 v[116:119], v[170:173], v[186:189], v[116:119]
	v_mfma_f32_16x16x32_bf16 v[112:115], v[178:181], v[186:189], v[112:115]
	v_mfma_f32_16x16x32_bf16 v[100:103], v[170:173], v[194:197], v[100:103]
	v_mfma_f32_16x16x32_bf16 v[96:99], v[178:181], v[194:197], v[96:99]
	v_mfma_f32_16x16x32_bf16 v[84:87], v[170:173], v[202:205], v[84:87]
	v_mfma_f32_16x16x32_bf16 v[80:83], v[178:181], v[202:205], v[80:83]
	v_mfma_f32_16x16x32_bf16 v[68:71], v[170:173], v[210:213], v[68:71]
	v_mfma_f32_16x16x32_bf16 v[64:67], v[178:181], v[210:213], v[64:67]
	s_barrier
	s_add_i32 s33, s43, s31
	v_lshl_add_u64 v[214:215], s[26:27], 0, v[132:133]
	s_mov_b32 m0, s33
	ds_read_b128 v[182:185], v149 offset:16384
	ds_read_b128 v[186:189], v149 offset:17408
	ds_read_b128 v[190:193], v149 offset:18432
	ds_read_b128 v[194:197], v149 offset:19456
	ds_read_b128 v[198:201], v149 offset:20480
	ds_read_b128 v[202:205], v149 offset:21504
	ds_read_b128 v[206:209], v149 offset:22528
	ds_read_b128 v[210:213], v149 offset:23552
	global_load_lds_dwordx4 v[214:215], off
	s_add_i32 m0, s33, 0x2000
	s_add_u32 s52, s26, 0x80000
	v_lshl_add_u64 v[216:217], s[26:27], 0, v[128:129]
	s_addc_u32 s53, s27, 0
	s_add_i32 s33, s44, s31
	global_load_lds_dwordx4 v[216:217], off
	v_lshl_add_u64 v[218:219], s[52:53], 0, v[132:133]
	s_mov_b32 m0, s33
	v_lshl_add_u64 v[222:223], s[28:29], 0, v[130:131]
	global_load_lds_dwordx4 v[218:219], off
	v_lshl_add_u64 v[218:219], s[52:53], 0, v[128:129]
	s_add_i32 m0, s33, 0x2000
	s_nop 0
	global_load_lds_dwordx4 v[218:219], off
	v_lshl_add_u64 v[218:219], s[28:29], 0, v[134:135]
	s_mov_b32 m0, s23
	s_nop 0
	global_load_lds_dwordx4 v[218:219], off
	s_mov_b32 m0, s36
	s_nop 0
	global_load_lds_dwordx4 v[222:223], off
	s_waitcnt vmcnt(8)
	s_waitcnt lgkmcnt(0)
	s_barrier
	s_waitcnt lgkmcnt(0)
	v_mfma_f32_16x16x32_bf16 v[60:63], v[150:153], v[182:185], v[60:63]
	v_mfma_f32_16x16x32_bf16 v[56:59], v[158:161], v[182:185], v[56:59]
	v_mfma_f32_16x16x32_bf16 v[44:47], v[150:153], v[190:193], v[44:47]
	v_mfma_f32_16x16x32_bf16 v[40:43], v[158:161], v[190:193], v[40:43]
	v_mfma_f32_16x16x32_bf16 v[28:31], v[150:153], v[198:201], v[28:31]
	v_mfma_f32_16x16x32_bf16 v[24:27], v[158:161], v[198:201], v[24:27]
	v_mfma_f32_16x16x32_bf16 v[12:15], v[150:153], v[206:209], v[12:15]
	v_mfma_f32_16x16x32_bf16 v[8:11], v[158:161], v[206:209], v[8:11]
	v_mfma_f32_16x16x32_bf16 v[60:63], v[154:157], v[186:189], v[60:63]
	v_mfma_f32_16x16x32_bf16 v[56:59], v[162:165], v[186:189], v[56:59]
	v_mfma_f32_16x16x32_bf16 v[44:47], v[154:157], v[194:197], v[44:47]
	v_mfma_f32_16x16x32_bf16 v[40:43], v[162:165], v[194:197], v[40:43]
	v_mfma_f32_16x16x32_bf16 v[28:31], v[154:157], v[202:205], v[28:31]
	v_mfma_f32_16x16x32_bf16 v[24:27], v[162:165], v[202:205], v[24:27]
	v_mfma_f32_16x16x32_bf16 v[12:15], v[154:157], v[210:213], v[12:15]
	v_mfma_f32_16x16x32_bf16 v[8:11], v[162:165], v[210:213], v[8:11]
	v_mfma_f32_16x16x32_bf16 v[52:55], v[166:169], v[182:185], v[52:55]
	v_mfma_f32_16x16x32_bf16 v[48:51], v[174:177], v[182:185], v[48:51]
	v_mfma_f32_16x16x32_bf16 v[36:39], v[166:169], v[190:193], v[36:39]
	v_mfma_f32_16x16x32_bf16 v[32:35], v[174:177], v[190:193], v[32:35]
	v_mfma_f32_16x16x32_bf16 v[20:23], v[166:169], v[198:201], v[20:23]
	v_mfma_f32_16x16x32_bf16 v[16:19], v[174:177], v[198:201], v[16:19]
	v_mfma_f32_16x16x32_bf16 v[4:7], v[166:169], v[206:209], v[4:7]
	v_mfma_f32_16x16x32_bf16 v[0:3], v[174:177], v[206:209], v[0:3]
	v_mfma_f32_16x16x32_bf16 v[52:55], v[170:173], v[186:189], v[52:55]
	v_mfma_f32_16x16x32_bf16 v[48:51], v[178:181], v[186:189], v[48:51]
	v_mfma_f32_16x16x32_bf16 v[36:39], v[170:173], v[194:197], v[36:39]
	v_mfma_f32_16x16x32_bf16 v[32:35], v[178:181], v[194:197], v[32:35]
	v_mfma_f32_16x16x32_bf16 v[20:23], v[170:173], v[202:205], v[20:23]
	v_mfma_f32_16x16x32_bf16 v[16:19], v[178:181], v[202:205], v[16:19]
	v_mfma_f32_16x16x32_bf16 v[4:7], v[170:173], v[210:213], v[4:7]
	v_mfma_f32_16x16x32_bf16 v[0:3], v[178:181], v[210:213], v[0:3]
	s_barrier
	s_add_i32 s33, 0, 0x18000
	s_add_i32 s52, 0, 0x1c000
	v_add_u32_e32 v162, s33, v145
	v_add_u32_e32 v178, s52, v145
	ds_read_b128 v[150:153], v162
	ds_read_b128 v[154:157], v162 offset:1024
	ds_read_b128 v[158:161], v162 offset:2048
	ds_read_b128 v[162:165], v162 offset:3072
	ds_read_b128 v[166:169], v178
	ds_read_b128 v[170:173], v178 offset:1024
	ds_read_b128 v[174:177], v178 offset:2048
	ds_read_b128 v[178:181], v178 offset:3072
	s_add_u32 s28, s28, 0x80000
	s_addc_u32 s29, s29, 0
	s_mov_b32 m0, s37
	v_lshl_add_u64 v[224:225], s[28:29], 0, v[134:135]
	ds_read_b128 v[182:185], v149 offset:32768
	ds_read_b128 v[186:189], v149 offset:33792
	ds_read_b128 v[190:193], v149 offset:34816
	ds_read_b128 v[194:197], v149 offset:35840
	ds_read_b128 v[198:201], v149 offset:36864
	ds_read_b128 v[202:205], v149 offset:37888
	ds_read_b128 v[206:209], v149 offset:38912
	ds_read_b128 v[210:213], v149 offset:39936
	global_load_lds_dwordx4 v[224:225], off
	v_lshl_add_u64 v[224:225], s[28:29], 0, v[130:131]
	s_mov_b32 m0, s38
	s_nop 0
	global_load_lds_dwordx4 v[224:225], off
	s_waitcnt vmcnt(8)
	s_waitcnt lgkmcnt(0)
	s_barrier
	s_waitcnt lgkmcnt(0)
	v_mfma_f32_16x16x32_bf16 v[124:127], v[150:153], v[182:185], v[124:127]
	v_mfma_f32_16x16x32_bf16 v[120:123], v[158:161], v[182:185], v[120:123]
	v_mfma_f32_16x16x32_bf16 v[108:111], v[150:153], v[190:193], v[108:111]
	v_mfma_f32_16x16x32_bf16 v[104:107], v[158:161], v[190:193], v[104:107]
	v_mfma_f32_16x16x32_bf16 v[92:95], v[150:153], v[198:201], v[92:95]
	v_mfma_f32_16x16x32_bf16 v[88:91], v[158:161], v[198:201], v[88:91]
	v_mfma_f32_16x16x32_bf16 v[76:79], v[150:153], v[206:209], v[76:79]
	v_mfma_f32_16x16x32_bf16 v[72:75], v[158:161], v[206:209], v[72:75]
	v_mfma_f32_16x16x32_bf16 v[124:127], v[154:157], v[186:189], v[124:127]
	v_mfma_f32_16x16x32_bf16 v[120:123], v[162:165], v[186:189], v[120:123]
	v_mfma_f32_16x16x32_bf16 v[108:111], v[154:157], v[194:197], v[108:111]
	v_mfma_f32_16x16x32_bf16 v[104:107], v[162:165], v[194:197], v[104:107]
	v_mfma_f32_16x16x32_bf16 v[92:95], v[154:157], v[202:205], v[92:95]
	v_mfma_f32_16x16x32_bf16 v[88:91], v[162:165], v[202:205], v[88:91]
	v_mfma_f32_16x16x32_bf16 v[76:79], v[154:157], v[210:213], v[76:79]
	v_mfma_f32_16x16x32_bf16 v[72:75], v[162:165], v[210:213], v[72:75]
	v_mfma_f32_16x16x32_bf16 v[116:119], v[166:169], v[182:185], v[116:119]
	v_mfma_f32_16x16x32_bf16 v[112:115], v[174:177], v[182:185], v[112:115]
	v_mfma_f32_16x16x32_bf16 v[100:103], v[166:169], v[190:193], v[100:103]
	v_mfma_f32_16x16x32_bf16 v[96:99], v[174:177], v[190:193], v[96:99]
	v_mfma_f32_16x16x32_bf16 v[84:87], v[166:169], v[198:201], v[84:87]
	v_mfma_f32_16x16x32_bf16 v[80:83], v[174:177], v[198:201], v[80:83]
	v_mfma_f32_16x16x32_bf16 v[68:71], v[166:169], v[206:209], v[68:71]
	v_mfma_f32_16x16x32_bf16 v[64:67], v[174:177], v[206:209], v[64:67]
	v_mfma_f32_16x16x32_bf16 v[116:119], v[170:173], v[186:189], v[116:119]
	v_mfma_f32_16x16x32_bf16 v[112:115], v[178:181], v[186:189], v[112:115]
	v_mfma_f32_16x16x32_bf16 v[100:103], v[170:173], v[194:197], v[100:103]
	v_mfma_f32_16x16x32_bf16 v[96:99], v[178:181], v[194:197], v[96:99]
	v_mfma_f32_16x16x32_bf16 v[84:87], v[170:173], v[202:205], v[84:87]
	v_mfma_f32_16x16x32_bf16 v[80:83], v[178:181], v[202:205], v[80:83]
	v_mfma_f32_16x16x32_bf16 v[68:71], v[170:173], v[210:213], v[68:71]
	v_mfma_f32_16x16x32_bf16 v[64:67], v[178:181], v[210:213], v[64:67]
	s_barrier
	s_add_i32 s28, s33, s31
	v_lshl_add_u64 v[214:215], v[214:215], 0, s[10:11]
	s_mov_b32 m0, s28
	ds_read_b128 v[182:185], v149 offset:49152
	ds_read_b128 v[186:189], v149 offset:50176
	ds_read_b128 v[190:193], v149 offset:51200
	ds_read_b128 v[194:197], v149 offset:52224
	ds_read_b128 v[198:201], v149 offset:53248
	ds_read_b128 v[202:205], v149 offset:54272
	ds_read_b128 v[206:209], v149 offset:55296
	ds_read_b128 v[210:213], v149 offset:56320
	global_load_lds_dwordx4 v[214:215], off
	s_add_i32 m0, s28, 0x2000
	s_add_u32 s26, s26, 0x80080
	v_lshl_add_u64 v[214:215], v[216:217], 0, s[10:11]
	s_addc_u32 s27, s27, 0
	s_add_i32 s28, s52, s31
	global_load_lds_dwordx4 v[214:215], off
	v_lshl_add_u64 v[214:215], s[26:27], 0, v[132:133]
	s_mov_b32 m0, s28
	s_nop 0
	global_load_lds_dwordx4 v[214:215], off
	v_lshl_add_u64 v[214:215], s[26:27], 0, v[128:129]
	s_add_i32 m0, s28, 0x2000
	s_nop 0
	global_load_lds_dwordx4 v[214:215], off
	v_lshl_add_u64 v[214:215], v[218:219], 0, s[10:11]
	s_mov_b32 m0, s40
	s_nop 0
	global_load_lds_dwordx4 v[214:215], off
	v_lshl_add_u64 v[214:215], v[222:223], 0, s[10:11]
	s_mov_b32 m0, s41
	s_nop 0
	global_load_lds_dwordx4 v[214:215], off
	s_waitcnt vmcnt(8)
	s_waitcnt lgkmcnt(0)
	s_barrier
	s_waitcnt lgkmcnt(0)
	v_mfma_f32_16x16x32_bf16 v[60:63], v[150:153], v[182:185], v[60:63]
	v_mfma_f32_16x16x32_bf16 v[56:59], v[158:161], v[182:185], v[56:59]
	v_mfma_f32_16x16x32_bf16 v[44:47], v[150:153], v[190:193], v[44:47]
	v_mfma_f32_16x16x32_bf16 v[40:43], v[158:161], v[190:193], v[40:43]
	v_mfma_f32_16x16x32_bf16 v[28:31], v[150:153], v[198:201], v[28:31]
	v_mfma_f32_16x16x32_bf16 v[24:27], v[158:161], v[198:201], v[24:27]
	v_mfma_f32_16x16x32_bf16 v[12:15], v[150:153], v[206:209], v[12:15]
	v_mfma_f32_16x16x32_bf16 v[8:11], v[158:161], v[206:209], v[8:11]
	v_mfma_f32_16x16x32_bf16 v[60:63], v[154:157], v[186:189], v[60:63]
	v_mfma_f32_16x16x32_bf16 v[56:59], v[162:165], v[186:189], v[56:59]
	v_mfma_f32_16x16x32_bf16 v[44:47], v[154:157], v[194:197], v[44:47]
	v_mfma_f32_16x16x32_bf16 v[40:43], v[162:165], v[194:197], v[40:43]
	v_mfma_f32_16x16x32_bf16 v[28:31], v[154:157], v[202:205], v[28:31]
	v_mfma_f32_16x16x32_bf16 v[24:27], v[162:165], v[202:205], v[24:27]
	v_mfma_f32_16x16x32_bf16 v[12:15], v[154:157], v[210:213], v[12:15]
	v_mfma_f32_16x16x32_bf16 v[8:11], v[162:165], v[210:213], v[8:11]
	v_mfma_f32_16x16x32_bf16 v[52:55], v[166:169], v[182:185], v[52:55]
	v_mfma_f32_16x16x32_bf16 v[48:51], v[174:177], v[182:185], v[48:51]
	v_mfma_f32_16x16x32_bf16 v[36:39], v[166:169], v[190:193], v[36:39]
	v_mfma_f32_16x16x32_bf16 v[32:35], v[174:177], v[190:193], v[32:35]
	v_mfma_f32_16x16x32_bf16 v[20:23], v[166:169], v[198:201], v[20:23]
	v_mfma_f32_16x16x32_bf16 v[16:19], v[174:177], v[198:201], v[16:19]
	v_mfma_f32_16x16x32_bf16 v[4:7], v[166:169], v[206:209], v[4:7]
	v_mfma_f32_16x16x32_bf16 v[0:3], v[174:177], v[206:209], v[0:3]
	v_mfma_f32_16x16x32_bf16 v[52:55], v[170:173], v[186:189], v[52:55]
	v_mfma_f32_16x16x32_bf16 v[48:51], v[178:181], v[186:189], v[48:51]
	v_mfma_f32_16x16x32_bf16 v[36:39], v[170:173], v[194:197], v[36:39]
	v_mfma_f32_16x16x32_bf16 v[32:35], v[178:181], v[194:197], v[32:35]
	v_mfma_f32_16x16x32_bf16 v[20:23], v[170:173], v[202:205], v[20:23]
	v_mfma_f32_16x16x32_bf16 v[16:19], v[178:181], v[202:205], v[16:19]
	v_mfma_f32_16x16x32_bf16 v[4:7], v[170:173], v[210:213], v[4:7]
	v_mfma_f32_16x16x32_bf16 v[0:3], v[178:181], v[210:213], v[0:3]
	s_barrier
	s_add_i32 s51, s51, 2
	s_add_u32 s24, s24, 0x100
	s_addc_u32 s25, s25, 0
	s_add_u32 s49, s49, 0x100
	s_addc_u32 s50, s50, 0
	s_cmp_gt_u32 s51, 29
	s_cbranch_scc0 .LBB0_715
	s_and_b64 vcc, exec, s[12:13]
	s_cbranch_vccz .LBB0_718
	s_barrier

.LBB0_770:
	ds_read_b128 v[148:151], v145
	ds_read_b128 v[152:155], v145 offset:1024
	ds_read_b128 v[156:159], v145 offset:2048
	ds_read_b128 v[160:163], v145 offset:3072
	ds_read_b128 v[164:167], v146
	ds_read_b128 v[168:171], v146 offset:1024
	ds_read_b128 v[172:175], v146 offset:2048
	ds_read_b128 v[176:179], v146 offset:3072
	s_add_u32 s30, s28, 0xffea0080
	s_addc_u32 s31, s29, -1
	s_cmpk_eq_i32 s54, 0x54
	s_cselect_b32 s35, s5, s31
	s_cselect_b32 s34, s4, s30
	s_cselect_b32 s31, s27, s53
	s_cselect_b32 s30, s26, s52
	v_lshl_add_u64 v[140:141], s[28:29], 0, v[132:133]
	s_add_i32 m0, s38, 0xc000
	ds_read_b128 v[180:183], v147
	ds_read_b128 v[184:187], v147 offset:1024
	ds_read_b128 v[188:191], v147 offset:2048
	ds_read_b128 v[192:195], v147 offset:3072
	ds_read_b128 v[196:199], v147 offset:4096
	ds_read_b128 v[200:203], v147 offset:5120
	ds_read_b128 v[204:207], v147 offset:6144
	ds_read_b128 v[208:211], v147 offset:7168
	global_load_lds_dwordx4 v[140:141], off
	v_lshl_add_u64 v[140:141], s[28:29], 0, v[134:135]
	s_add_i32 m0, s38, 0xe000
	s_nop 0
	global_load_lds_dwordx4 v[140:141], off
	s_waitcnt vmcnt(8)
	s_waitcnt lgkmcnt(0)
	s_barrier
	s_waitcnt lgkmcnt(0)
	v_mfma_f32_16x16x32_bf16 v[124:127], v[148:151], v[180:183], v[124:127]
	v_mfma_f32_16x16x32_bf16 v[120:123], v[156:159], v[180:183], v[120:123]
	v_mfma_f32_16x16x32_bf16 v[112:115], v[148:151], v[188:191], v[112:115]
	v_mfma_f32_16x16x32_bf16 v[104:107], v[156:159], v[188:191], v[104:107]
	v_mfma_f32_16x16x32_bf16 v[96:99], v[148:151], v[196:199], v[96:99]
	v_mfma_f32_16x16x32_bf16 v[88:91], v[156:159], v[196:199], v[88:91]
	v_mfma_f32_16x16x32_bf16 v[80:83], v[148:151], v[204:207], v[80:83]
	v_mfma_f32_16x16x32_bf16 v[72:75], v[156:159], v[204:207], v[72:75]
	v_mfma_f32_16x16x32_bf16 v[124:127], v[152:155], v[184:187], v[124:127]
	v_mfma_f32_16x16x32_bf16 v[120:123], v[160:163], v[184:187], v[120:123]
	v_mfma_f32_16x16x32_bf16 v[112:115], v[152:155], v[192:195], v[112:115]
	v_mfma_f32_16x16x32_bf16 v[104:107], v[160:163], v[192:195], v[104:107]
	v_mfma_f32_16x16x32_bf16 v[96:99], v[152:155], v[200:203], v[96:99]
	v_mfma_f32_16x16x32_bf16 v[88:91], v[160:163], v[200:203], v[88:91]
	v_mfma_f32_16x16x32_bf16 v[80:83], v[152:155], v[208:211], v[80:83]
	v_mfma_f32_16x16x32_bf16 v[72:75], v[160:163], v[208:211], v[72:75]
	v_mfma_f32_16x16x32_bf16 v[116:119], v[164:167], v[180:183], v[116:119]
	v_mfma_f32_16x16x32_bf16 v[108:111], v[172:175], v[180:183], v[108:111]
	v_mfma_f32_16x16x32_bf16 v[100:103], v[164:167], v[188:191], v[100:103]
	v_mfma_f32_16x16x32_bf16 v[92:95], v[172:175], v[188:191], v[92:95]
	v_mfma_f32_16x16x32_bf16 v[84:87], v[164:167], v[196:199], v[84:87]
	v_mfma_f32_16x16x32_bf16 v[76:79], v[172:175], v[196:199], v[76:79]
	v_mfma_f32_16x16x32_bf16 v[68:71], v[164:167], v[204:207], v[68:71]
	v_mfma_f32_16x16x32_bf16 v[64:67], v[172:175], v[204:207], v[64:67]
	v_mfma_f32_16x16x32_bf16 v[116:119], v[168:171], v[184:187], v[116:119]
	v_mfma_f32_16x16x32_bf16 v[108:111], v[176:179], v[184:187], v[108:111]
	v_mfma_f32_16x16x32_bf16 v[100:103], v[168:171], v[192:195], v[100:103]
	v_mfma_f32_16x16x32_bf16 v[92:95], v[176:179], v[192:195], v[92:95]
	v_mfma_f32_16x16x32_bf16 v[84:87], v[168:171], v[200:203], v[84:87]
	v_mfma_f32_16x16x32_bf16 v[76:79], v[176:179], v[200:203], v[76:79]
	v_mfma_f32_16x16x32_bf16 v[68:71], v[168:171], v[208:211], v[68:71]
	v_mfma_f32_16x16x32_bf16 v[64:67], v[176:179], v[208:211], v[64:67]
	s_barrier
	s_add_i32 s33, s63, s37
	v_lshl_add_u64 v[140:141], s[30:31], 0, v[128:129]
	s_mov_b32 m0, s33
	ds_read_b128 v[180:183], v147 offset:16384
	ds_read_b128 v[184:187], v147 offset:17408
	ds_read_b128 v[188:191], v147 offset:18432
	ds_read_b128 v[192:195], v147 offset:19456
	ds_read_b128 v[196:199], v147 offset:20480
	ds_read_b128 v[200:203], v147 offset:21504
	ds_read_b128 v[204:207], v147 offset:22528
	ds_read_b128 v[208:211], v147 offset:23552
	global_load_lds_dwordx4 v[140:141], off
	s_add_i32 m0, s33, 0x2000
	s_add_u32 s56, s30, 0x160000
	v_lshl_add_u64 v[212:213], s[30:31], 0, v[130:131]
	s_addc_u32 s57, s31, 0
	s_add_i32 s33, s64, s37
	global_load_lds_dwordx4 v[212:213], off
	v_lshl_add_u64 v[214:215], s[56:57], 0, v[128:129]
	s_mov_b32 m0, s33
	v_lshl_add_u64 v[216:217], s[34:35], 0, v[130:131]
	global_load_lds_dwordx4 v[214:215], off
	v_lshl_add_u64 v[214:215], s[56:57], 0, v[130:131]
	s_add_i32 m0, s33, 0x2000
	s_nop 0
	global_load_lds_dwordx4 v[214:215], off
	v_lshl_add_u64 v[214:215], s[34:35], 0, v[128:129]
	s_mov_b32 m0, s38
	s_nop 0
	global_load_lds_dwordx4 v[214:215], off
	s_mov_b32 m0, s39
	s_nop 0
	global_load_lds_dwordx4 v[216:217], off
	s_waitcnt vmcnt(8)
	s_waitcnt lgkmcnt(0)
	s_barrier
	s_waitcnt lgkmcnt(0)
	v_mfma_f32_16x16x32_bf16 v[60:63], v[148:151], v[180:183], v[60:63]
	v_mfma_f32_16x16x32_bf16 v[56:59], v[156:159], v[180:183], v[56:59]
	v_mfma_f32_16x16x32_bf16 v[48:51], v[148:151], v[188:191], v[48:51]
	v_mfma_f32_16x16x32_bf16 v[40:43], v[156:159], v[188:191], v[40:43]
	v_mfma_f32_16x16x32_bf16 v[32:35], v[148:151], v[196:199], v[32:35]
	v_mfma_f32_16x16x32_bf16 v[24:27], v[156:159], v[196:199], v[24:27]
	v_mfma_f32_16x16x32_bf16 v[16:19], v[148:151], v[204:207], v[16:19]
	v_mfma_f32_16x16x32_bf16 v[8:11], v[156:159], v[204:207], v[8:11]
	v_mfma_f32_16x16x32_bf16 v[60:63], v[152:155], v[184:187], v[60:63]
	v_mfma_f32_16x16x32_bf16 v[56:59], v[160:163], v[184:187], v[56:59]
	v_mfma_f32_16x16x32_bf16 v[48:51], v[152:155], v[192:195], v[48:51]
	v_mfma_f32_16x16x32_bf16 v[40:43], v[160:163], v[192:195], v[40:43]
	v_mfma_f32_16x16x32_bf16 v[32:35], v[152:155], v[200:203], v[32:35]
	v_mfma_f32_16x16x32_bf16 v[24:27], v[160:163], v[200:203], v[24:27]
	v_mfma_f32_16x16x32_bf16 v[16:19], v[152:155], v[208:211], v[16:19]
	v_mfma_f32_16x16x32_bf16 v[8:11], v[160:163], v[208:211], v[8:11]
	v_mfma_f32_16x16x32_bf16 v[52:55], v[164:167], v[180:183], v[52:55]
	v_mfma_f32_16x16x32_bf16 v[44:47], v[172:175], v[180:183], v[44:47]
	v_mfma_f32_16x16x32_bf16 v[36:39], v[164:167], v[188:191], v[36:39]
	v_mfma_f32_16x16x32_bf16 v[28:31], v[172:175], v[188:191], v[28:31]
	v_mfma_f32_16x16x32_bf16 v[20:23], v[164:167], v[196:199], v[20:23]
	v_mfma_f32_16x16x32_bf16 v[12:15], v[172:175], v[196:199], v[12:15]
	v_mfma_f32_16x16x32_bf16 v[4:7], v[164:167], v[204:207], v[4:7]
	v_mfma_f32_16x16x32_bf16 v[0:3], v[172:175], v[204:207], v[0:3]
	v_mfma_f32_16x16x32_bf16 v[52:55], v[168:171], v[184:187], v[52:55]
	v_mfma_f32_16x16x32_bf16 v[44:47], v[176:179], v[184:187], v[44:47]
	v_mfma_f32_16x16x32_bf16 v[36:39], v[168:171], v[192:195], v[36:39]
	v_mfma_f32_16x16x32_bf16 v[28:31], v[176:179], v[192:195], v[28:31]
	v_mfma_f32_16x16x32_bf16 v[20:23], v[168:171], v[200:203], v[20:23]
	v_mfma_f32_16x16x32_bf16 v[12:15], v[176:179], v[200:203], v[12:15]
	v_mfma_f32_16x16x32_bf16 v[4:7], v[168:171], v[208:211], v[4:7]
	v_mfma_f32_16x16x32_bf16 v[0:3], v[176:179], v[208:211], v[0:3]
	s_barrier
	s_add_i32 s33, 0, 0x18000
	s_add_i32 s55, 0, 0x1c000
	v_add_u32_e32 v160, s33, v143
	v_add_u32_e32 v176, s55, v143
	ds_read_b128 v[148:151], v160
	ds_read_b128 v[152:155], v160 offset:1024
	ds_read_b128 v[156:159], v160 offset:2048
	ds_read_b128 v[160:163], v160 offset:3072
	ds_read_b128 v[164:167], v176
	ds_read_b128 v[168:171], v176 offset:1024
	ds_read_b128 v[172:175], v176 offset:2048
	ds_read_b128 v[176:179], v176 offset:3072
	s_add_u32 s34, s34, 0x160000
	s_addc_u32 s35, s35, 0
	s_mov_b32 m0, s40
	v_lshl_add_u64 v[218:219], s[34:35], 0, v[128:129]
	ds_read_b128 v[180:183], v147 offset:32768
	ds_read_b128 v[184:187], v147 offset:33792
	ds_read_b128 v[188:191], v147 offset:34816
	ds_read_b128 v[192:195], v147 offset:35840
	ds_read_b128 v[196:199], v147 offset:36864
	ds_read_b128 v[200:203], v147 offset:37888
	ds_read_b128 v[204:207], v147 offset:38912
	ds_read_b128 v[208:211], v147 offset:39936
	global_load_lds_dwordx4 v[218:219], off
	v_lshl_add_u64 v[218:219], s[34:35], 0, v[130:131]
	s_mov_b32 m0, s41
	s_nop 0
	global_load_lds_dwordx4 v[218:219], off
	s_waitcnt vmcnt(8)
	s_waitcnt lgkmcnt(0)
	s_barrier
	s_waitcnt lgkmcnt(0)
	v_mfma_f32_16x16x32_bf16 v[124:127], v[148:151], v[180:183], v[124:127]
	v_mfma_f32_16x16x32_bf16 v[120:123], v[156:159], v[180:183], v[120:123]
	v_mfma_f32_16x16x32_bf16 v[112:115], v[148:151], v[188:191], v[112:115]
	v_mfma_f32_16x16x32_bf16 v[104:107], v[156:159], v[188:191], v[104:107]
	v_mfma_f32_16x16x32_bf16 v[96:99], v[148:151], v[196:199], v[96:99]
	v_mfma_f32_16x16x32_bf16 v[88:91], v[156:159], v[196:199], v[88:91]
	v_mfma_f32_16x16x32_bf16 v[80:83], v[148:151], v[204:207], v[80:83]
	v_mfma_f32_16x16x32_bf16 v[72:75], v[156:159], v[204:207], v[72:75]
	v_mfma_f32_16x16x32_bf16 v[124:127], v[152:155], v[184:187], v[124:127]
	v_mfma_f32_16x16x32_bf16 v[120:123], v[160:163], v[184:187], v[120:123]
	v_mfma_f32_16x16x32_bf16 v[112:115], v[152:155], v[192:195], v[112:115]
	v_mfma_f32_16x16x32_bf16 v[104:107], v[160:163], v[192:195], v[104:107]
	v_mfma_f32_16x16x32_bf16 v[96:99], v[152:155], v[200:203], v[96:99]
	v_mfma_f32_16x16x32_bf16 v[88:91], v[160:163], v[200:203], v[88:91]
	v_mfma_f32_16x16x32_bf16 v[80:83], v[152:155], v[208:211], v[80:83]
	v_mfma_f32_16x16x32_bf16 v[72:75], v[160:163], v[208:211], v[72:75]
	v_mfma_f32_16x16x32_bf16 v[116:119], v[164:167], v[180:183], v[116:119]
	v_mfma_f32_16x16x32_bf16 v[108:111], v[172:175], v[180:183], v[108:111]
	v_mfma_f32_16x16x32_bf16 v[100:103], v[164:167], v[188:191], v[100:103]
	v_mfma_f32_16x16x32_bf16 v[92:95], v[172:175], v[188:191], v[92:95]
	v_mfma_f32_16x16x32_bf16 v[84:87], v[164:167], v[196:199], v[84:87]
	v_mfma_f32_16x16x32_bf16 v[76:79], v[172:175], v[196:199], v[76:79]
	v_mfma_f32_16x16x32_bf16 v[68:71], v[164:167], v[204:207], v[68:71]
	v_mfma_f32_16x16x32_bf16 v[64:67], v[172:175], v[204:207], v[64:67]
	v_mfma_f32_16x16x32_bf16 v[116:119], v[168:171], v[184:187], v[116:119]
	v_mfma_f32_16x16x32_bf16 v[108:111], v[176:179], v[184:187], v[108:111]
	v_mfma_f32_16x16x32_bf16 v[100:103], v[168:171], v[192:195], v[100:103]
	v_mfma_f32_16x16x32_bf16 v[92:95], v[176:179], v[192:195], v[92:95]
	v_mfma_f32_16x16x32_bf16 v[84:87], v[168:171], v[200:203], v[84:87]
	v_mfma_f32_16x16x32_bf16 v[76:79], v[176:179], v[200:203], v[76:79]
	v_mfma_f32_16x16x32_bf16 v[68:71], v[168:171], v[208:211], v[68:71]
	v_mfma_f32_16x16x32_bf16 v[64:67], v[176:179], v[208:211], v[64:67]
	s_barrier
	s_add_i32 s33, s33, s37
	v_lshl_add_u64 v[140:141], v[140:141], 0, s[14:15]
	s_mov_b32 m0, s33
	ds_read_b128 v[180:183], v147 offset:49152
	ds_read_b128 v[184:187], v147 offset:50176
	ds_read_b128 v[188:191], v147 offset:51200
	ds_read_b128 v[192:195], v147 offset:52224
	ds_read_b128 v[196:199], v147 offset:53248
	ds_read_b128 v[200:203], v147 offset:54272
	ds_read_b128 v[204:207], v147 offset:55296
	ds_read_b128 v[208:211], v147 offset:56320
	global_load_lds_dwordx4 v[140:141], off
	s_add_i32 m0, s33, 0x2000
	s_add_u32 s30, s30, 0x160080
	v_lshl_add_u64 v[140:141], v[212:213], 0, s[14:15]
	s_addc_u32 s31, s31, 0
	s_add_i32 s33, s55, s37
	global_load_lds_dwordx4 v[140:141], off
	v_lshl_add_u64 v[140:141], s[30:31], 0, v[128:129]
	s_mov_b32 m0, s33
	s_nop 0
	global_load_lds_dwordx4 v[140:141], off
	v_lshl_add_u64 v[140:141], s[30:31], 0, v[130:131]
	s_add_i32 m0, s33, 0x2000
	s_nop 0
	global_load_lds_dwordx4 v[140:141], off
	v_lshl_add_u64 v[140:141], v[214:215], 0, s[14:15]
	s_mov_b32 m0, s43
	s_nop 0
	global_load_lds_dwordx4 v[140:141], off
	v_lshl_add_u64 v[140:141], v[216:217], 0, s[14:15]
	s_mov_b32 m0, s61
	s_nop 0
	global_load_lds_dwordx4 v[140:141], off
	s_waitcnt vmcnt(8)
	s_waitcnt lgkmcnt(0)
	s_barrier
	s_waitcnt lgkmcnt(0)
	v_mfma_f32_16x16x32_bf16 v[60:63], v[148:151], v[180:183], v[60:63]
	v_mfma_f32_16x16x32_bf16 v[56:59], v[156:159], v[180:183], v[56:59]
	v_mfma_f32_16x16x32_bf16 v[48:51], v[148:151], v[188:191], v[48:51]
	v_mfma_f32_16x16x32_bf16 v[40:43], v[156:159], v[188:191], v[40:43]
	v_mfma_f32_16x16x32_bf16 v[32:35], v[148:151], v[196:199], v[32:35]
	v_mfma_f32_16x16x32_bf16 v[24:27], v[156:159], v[196:199], v[24:27]
	v_mfma_f32_16x16x32_bf16 v[16:19], v[148:151], v[204:207], v[16:19]
	v_mfma_f32_16x16x32_bf16 v[8:11], v[156:159], v[204:207], v[8:11]
	v_mfma_f32_16x16x32_bf16 v[60:63], v[152:155], v[184:187], v[60:63]
	v_mfma_f32_16x16x32_bf16 v[56:59], v[160:163], v[184:187], v[56:59]
	v_mfma_f32_16x16x32_bf16 v[48:51], v[152:155], v[192:195], v[48:51]
	v_mfma_f32_16x16x32_bf16 v[40:43], v[160:163], v[192:195], v[40:43]
	v_mfma_f32_16x16x32_bf16 v[32:35], v[152:155], v[200:203], v[32:35]
	v_mfma_f32_16x16x32_bf16 v[24:27], v[160:163], v[200:203], v[24:27]
	v_mfma_f32_16x16x32_bf16 v[16:19], v[152:155], v[208:211], v[16:19]
	v_mfma_f32_16x16x32_bf16 v[8:11], v[160:163], v[208:211], v[8:11]
	v_mfma_f32_16x16x32_bf16 v[52:55], v[164:167], v[180:183], v[52:55]
	v_mfma_f32_16x16x32_bf16 v[44:47], v[172:175], v[180:183], v[44:47]
	v_mfma_f32_16x16x32_bf16 v[36:39], v[164:167], v[188:191], v[36:39]
	v_mfma_f32_16x16x32_bf16 v[28:31], v[172:175], v[188:191], v[28:31]
	v_mfma_f32_16x16x32_bf16 v[20:23], v[164:167], v[196:199], v[20:23]
	v_mfma_f32_16x16x32_bf16 v[12:15], v[172:175], v[196:199], v[12:15]
	v_mfma_f32_16x16x32_bf16 v[4:7], v[164:167], v[204:207], v[4:7]
	v_mfma_f32_16x16x32_bf16 v[0:3], v[172:175], v[204:207], v[0:3]
	v_mfma_f32_16x16x32_bf16 v[52:55], v[168:171], v[184:187], v[52:55]
	v_mfma_f32_16x16x32_bf16 v[44:47], v[176:179], v[184:187], v[44:47]
	v_mfma_f32_16x16x32_bf16 v[36:39], v[168:171], v[192:195], v[36:39]
	v_mfma_f32_16x16x32_bf16 v[28:31], v[176:179], v[192:195], v[28:31]
	v_mfma_f32_16x16x32_bf16 v[20:23], v[168:171], v[200:203], v[20:23]
	v_mfma_f32_16x16x32_bf16 v[12:15], v[176:179], v[200:203], v[12:15]
	v_mfma_f32_16x16x32_bf16 v[4:7], v[168:171], v[208:211], v[4:7]
	v_mfma_f32_16x16x32_bf16 v[0:3], v[176:179], v[208:211], v[0:3]
	s_barrier
	s_add_i32 s54, s54, 2
	s_add_u32 s28, s28, 0x100
	s_addc_u32 s29, s29, 0
	s_add_u32 s52, s52, 0x100
	s_addc_u32 s53, s53, 0
	s_cmpk_gt_u32 s54, 0x55
	s_cbranch_scc0 .LBB0_770
	s_and_b64 vcc, exec, s[16:17]
	s_cbranch_vccz .LBB0_773
	s_barrier

.LBB0_798:
	v_add_u32_e32 v147, s43, v145
	ds_read_b128 v[148:151], v147
	ds_read_b128 v[152:155], v147 offset:1024
	ds_read_b128 v[156:159], v147 offset:2048
	ds_read_b128 v[160:163], v147 offset:3072
	v_add_u32_e32 v147, s44, v145
	s_add_u32 s22, s12, s20
	ds_read_b128 v[164:167], v147
	ds_read_b128 v[172:175], v147 offset:1024
	ds_read_b128 v[176:179], v147 offset:2048
	ds_read_b128 v[180:183], v147 offset:3072
	s_addc_u32 s23, s13, s21
	s_add_u32 s22, s22, 0x100
	s_addc_u32 s23, s23, 0
	s_add_u32 s33, s17, s20
	s_addc_u32 s49, s47, s21
	s_cmpk_eq_i32 s20, 0x2b00
	s_cselect_b32 s25, s19, s23
	s_cselect_b32 s24, s18, s22
	s_cselect_b32 s23, s7, s49
	s_cselect_b32 s22, s6, s33
	v_lshl_add_u64 v[168:169], v[140:141], 0, s[20:21]
	s_add_i32 m0, s35, 0xc000
	ds_read_b128 v[184:187], v146
	ds_read_b128 v[188:191], v146 offset:1024
	ds_read_b128 v[192:195], v146 offset:2048
	ds_read_b128 v[196:199], v146 offset:3072
	ds_read_b128 v[200:203], v146 offset:4096
	ds_read_b128 v[204:207], v146 offset:5120
	ds_read_b128 v[208:211], v146 offset:6144
	ds_read_b128 v[212:215], v146 offset:7168
	global_load_lds_dwordx4 v[168:169], off
	v_lshl_add_u64 v[168:169], v[142:143], 0, s[20:21]
	s_add_i32 m0, s35, 0xe000
	s_nop 0
	global_load_lds_dwordx4 v[168:169], off
	s_waitcnt vmcnt(8)
	s_waitcnt lgkmcnt(0)
	s_barrier
	s_waitcnt lgkmcnt(0)
	v_mfma_f32_16x16x32_bf16 v[124:127], v[148:151], v[184:187], v[124:127]
	v_mfma_f32_16x16x32_bf16 v[120:123], v[156:159], v[184:187], v[120:123]
	v_mfma_f32_16x16x32_bf16 v[108:111], v[148:151], v[192:195], v[108:111]
	v_mfma_f32_16x16x32_bf16 v[104:107], v[156:159], v[192:195], v[104:107]
	v_mfma_f32_16x16x32_bf16 v[92:95], v[148:151], v[200:203], v[92:95]
	v_mfma_f32_16x16x32_bf16 v[88:91], v[156:159], v[200:203], v[88:91]
	v_mfma_f32_16x16x32_bf16 v[76:79], v[148:151], v[208:211], v[76:79]
	v_mfma_f32_16x16x32_bf16 v[72:75], v[156:159], v[208:211], v[72:75]
	v_mfma_f32_16x16x32_bf16 v[124:127], v[152:155], v[188:191], v[124:127]
	v_mfma_f32_16x16x32_bf16 v[120:123], v[160:163], v[188:191], v[120:123]
	v_mfma_f32_16x16x32_bf16 v[108:111], v[152:155], v[196:199], v[108:111]
	v_mfma_f32_16x16x32_bf16 v[104:107], v[160:163], v[196:199], v[104:107]
	v_mfma_f32_16x16x32_bf16 v[92:95], v[152:155], v[204:207], v[92:95]
	v_mfma_f32_16x16x32_bf16 v[88:91], v[160:163], v[204:207], v[88:91]
	v_mfma_f32_16x16x32_bf16 v[76:79], v[152:155], v[212:215], v[76:79]
	v_mfma_f32_16x16x32_bf16 v[72:75], v[160:163], v[212:215], v[72:75]
	v_mfma_f32_16x16x32_bf16 v[116:119], v[164:167], v[184:187], v[116:119]
	v_mfma_f32_16x16x32_bf16 v[112:115], v[176:179], v[184:187], v[112:115]
	v_mfma_f32_16x16x32_bf16 v[100:103], v[164:167], v[192:195], v[100:103]
	v_mfma_f32_16x16x32_bf16 v[96:99], v[176:179], v[192:195], v[96:99]
	v_mfma_f32_16x16x32_bf16 v[84:87], v[164:167], v[200:203], v[84:87]
	v_mfma_f32_16x16x32_bf16 v[80:83], v[176:179], v[200:203], v[80:83]
	v_mfma_f32_16x16x32_bf16 v[68:71], v[164:167], v[208:211], v[68:71]
	v_mfma_f32_16x16x32_bf16 v[64:67], v[176:179], v[208:211], v[64:67]
	v_mfma_f32_16x16x32_bf16 v[116:119], v[172:175], v[188:191], v[116:119]
	v_mfma_f32_16x16x32_bf16 v[112:115], v[180:183], v[188:191], v[112:115]
	v_mfma_f32_16x16x32_bf16 v[100:103], v[172:175], v[196:199], v[100:103]
	v_mfma_f32_16x16x32_bf16 v[96:99], v[180:183], v[196:199], v[96:99]
	v_mfma_f32_16x16x32_bf16 v[84:87], v[172:175], v[204:207], v[84:87]
	v_mfma_f32_16x16x32_bf16 v[80:83], v[180:183], v[204:207], v[80:83]
	v_mfma_f32_16x16x32_bf16 v[68:71], v[172:175], v[212:215], v[68:71]
	v_mfma_f32_16x16x32_bf16 v[64:67], v[180:183], v[212:215], v[64:67]
	s_barrier
	s_add_i32 s33, s43, s34
	v_lshl_add_u64 v[168:169], s[22:23], 0, v[128:129]
	s_mov_b32 m0, s33
	ds_read_b128 v[184:187], v146 offset:16384
	ds_read_b128 v[188:191], v146 offset:17408
	ds_read_b128 v[192:195], v146 offset:18432
	ds_read_b128 v[196:199], v146 offset:19456
	ds_read_b128 v[200:203], v146 offset:20480
	ds_read_b128 v[204:207], v146 offset:21504
	ds_read_b128 v[208:211], v146 offset:22528
	ds_read_b128 v[212:215], v146 offset:23552
	global_load_lds_dwordx4 v[168:169], off
	s_add_i32 m0, s33, 0x2000
	s_add_u32 s50, s22, 0x160000
	v_lshl_add_u64 v[216:217], s[22:23], 0, v[130:131]
	s_addc_u32 s51, s23, 0
	s_add_i32 s33, s44, s34
	global_load_lds_dwordx4 v[216:217], off
	v_lshl_add_u64 v[218:219], s[50:51], 0, v[128:129]
	s_mov_b32 m0, s33
	v_lshl_add_u64 v[222:223], s[24:25], 0, v[130:131]
	global_load_lds_dwordx4 v[218:219], off
	v_lshl_add_u64 v[218:219], s[50:51], 0, v[130:131]
	s_add_i32 m0, s33, 0x2000
	s_nop 0
	global_load_lds_dwordx4 v[218:219], off
	v_lshl_add_u64 v[218:219], s[24:25], 0, v[128:129]
	s_mov_b32 m0, s35
	s_nop 0
	global_load_lds_dwordx4 v[218:219], off
	s_mov_b32 m0, s37
	s_nop 0
	global_load_lds_dwordx4 v[222:223], off
	s_waitcnt vmcnt(8)
	s_waitcnt lgkmcnt(0)
	s_barrier
	s_waitcnt lgkmcnt(0)
	v_mfma_f32_16x16x32_bf16 v[60:63], v[148:151], v[184:187], v[60:63]
	v_mfma_f32_16x16x32_bf16 v[56:59], v[156:159], v[184:187], v[56:59]
	v_mfma_f32_16x16x32_bf16 v[44:47], v[148:151], v[192:195], v[44:47]
	v_mfma_f32_16x16x32_bf16 v[40:43], v[156:159], v[192:195], v[40:43]
	v_mfma_f32_16x16x32_bf16 v[28:31], v[148:151], v[200:203], v[28:31]
	v_mfma_f32_16x16x32_bf16 v[24:27], v[156:159], v[200:203], v[24:27]
	v_mfma_f32_16x16x32_bf16 v[12:15], v[148:151], v[208:211], v[12:15]
	v_mfma_f32_16x16x32_bf16 v[8:11], v[156:159], v[208:211], v[8:11]
	v_mfma_f32_16x16x32_bf16 v[60:63], v[152:155], v[188:191], v[60:63]
	v_mfma_f32_16x16x32_bf16 v[56:59], v[160:163], v[188:191], v[56:59]
	v_mfma_f32_16x16x32_bf16 v[44:47], v[152:155], v[196:199], v[44:47]
	v_mfma_f32_16x16x32_bf16 v[40:43], v[160:163], v[196:199], v[40:43]
	v_mfma_f32_16x16x32_bf16 v[28:31], v[152:155], v[204:207], v[28:31]
	v_mfma_f32_16x16x32_bf16 v[24:27], v[160:163], v[204:207], v[24:27]
	v_mfma_f32_16x16x32_bf16 v[12:15], v[152:155], v[212:215], v[12:15]
	v_mfma_f32_16x16x32_bf16 v[8:11], v[160:163], v[212:215], v[8:11]
	v_mfma_f32_16x16x32_bf16 v[52:55], v[164:167], v[184:187], v[52:55]
	v_mfma_f32_16x16x32_bf16 v[48:51], v[176:179], v[184:187], v[48:51]
	v_mfma_f32_16x16x32_bf16 v[36:39], v[164:167], v[192:195], v[36:39]
	v_mfma_f32_16x16x32_bf16 v[32:35], v[176:179], v[192:195], v[32:35]
	v_mfma_f32_16x16x32_bf16 v[20:23], v[164:167], v[200:203], v[20:23]
	v_mfma_f32_16x16x32_bf16 v[16:19], v[176:179], v[200:203], v[16:19]
	v_mfma_f32_16x16x32_bf16 v[4:7], v[164:167], v[208:211], v[4:7]
	v_mfma_f32_16x16x32_bf16 v[0:3], v[176:179], v[208:211], v[0:3]
	v_mfma_f32_16x16x32_bf16 v[52:55], v[172:175], v[188:191], v[52:55]
	v_mfma_f32_16x16x32_bf16 v[48:51], v[180:183], v[188:191], v[48:51]
	v_mfma_f32_16x16x32_bf16 v[36:39], v[172:175], v[196:199], v[36:39]
	v_mfma_f32_16x16x32_bf16 v[32:35], v[180:183], v[196:199], v[32:35]
	v_mfma_f32_16x16x32_bf16 v[20:23], v[172:175], v[204:207], v[20:23]
	v_mfma_f32_16x16x32_bf16 v[16:19], v[180:183], v[204:207], v[16:19]
	v_mfma_f32_16x16x32_bf16 v[4:7], v[172:175], v[212:215], v[4:7]
	v_mfma_f32_16x16x32_bf16 v[0:3], v[180:183], v[212:215], v[0:3]
	s_barrier
	s_add_i32 s33, 0, 0x18000
	v_add_u32_e32 v147, s33, v145
	s_add_i32 s49, 0, 0x1c000
	ds_read_b128 v[148:151], v147
	ds_read_b128 v[152:155], v147 offset:1024
	ds_read_b128 v[156:159], v147 offset:2048
	ds_read_b128 v[160:163], v147 offset:3072
	v_add_u32_e32 v147, s49, v145
	ds_read_b128 v[164:167], v147
	ds_read_b128 v[172:175], v147 offset:1024
	ds_read_b128 v[176:179], v147 offset:2048
	ds_read_b128 v[180:183], v147 offset:3072
	s_add_u32 s24, s24, 0x160000
	s_addc_u32 s25, s25, 0
	s_mov_b32 m0, s38
	v_lshl_add_u64 v[224:225], s[24:25], 0, v[128:129]
	ds_read_b128 v[184:187], v146 offset:32768
	ds_read_b128 v[188:191], v146 offset:33792
	ds_read_b128 v[192:195], v146 offset:34816
	ds_read_b128 v[196:199], v146 offset:35840
	ds_read_b128 v[200:203], v146 offset:36864
	ds_read_b128 v[204:207], v146 offset:37888
	ds_read_b128 v[208:211], v146 offset:38912
	ds_read_b128 v[212:215], v146 offset:39936
	global_load_lds_dwordx4 v[224:225], off
	v_lshl_add_u64 v[224:225], s[24:25], 0, v[130:131]
	s_mov_b32 m0, s39
	s_nop 0
	global_load_lds_dwordx4 v[224:225], off
	s_waitcnt vmcnt(8)
	s_waitcnt lgkmcnt(0)
	s_barrier
	s_waitcnt lgkmcnt(0)
	v_mfma_f32_16x16x32_bf16 v[124:127], v[148:151], v[184:187], v[124:127]
	v_mfma_f32_16x16x32_bf16 v[120:123], v[156:159], v[184:187], v[120:123]
	v_mfma_f32_16x16x32_bf16 v[108:111], v[148:151], v[192:195], v[108:111]
	v_mfma_f32_16x16x32_bf16 v[104:107], v[156:159], v[192:195], v[104:107]
	v_mfma_f32_16x16x32_bf16 v[92:95], v[148:151], v[200:203], v[92:95]
	v_mfma_f32_16x16x32_bf16 v[88:91], v[156:159], v[200:203], v[88:91]
	v_mfma_f32_16x16x32_bf16 v[76:79], v[148:151], v[208:211], v[76:79]
	v_mfma_f32_16x16x32_bf16 v[72:75], v[156:159], v[208:211], v[72:75]
	v_mfma_f32_16x16x32_bf16 v[124:127], v[152:155], v[188:191], v[124:127]
	v_mfma_f32_16x16x32_bf16 v[120:123], v[160:163], v[188:191], v[120:123]
	v_mfma_f32_16x16x32_bf16 v[108:111], v[152:155], v[196:199], v[108:111]
	v_mfma_f32_16x16x32_bf16 v[104:107], v[160:163], v[196:199], v[104:107]
	v_mfma_f32_16x16x32_bf16 v[92:95], v[152:155], v[204:207], v[92:95]
	v_mfma_f32_16x16x32_bf16 v[88:91], v[160:163], v[204:207], v[88:91]
	v_mfma_f32_16x16x32_bf16 v[76:79], v[152:155], v[212:215], v[76:79]
	v_mfma_f32_16x16x32_bf16 v[72:75], v[160:163], v[212:215], v[72:75]
	v_mfma_f32_16x16x32_bf16 v[116:119], v[164:167], v[184:187], v[116:119]
	v_mfma_f32_16x16x32_bf16 v[112:115], v[176:179], v[184:187], v[112:115]
	v_mfma_f32_16x16x32_bf16 v[100:103], v[164:167], v[192:195], v[100:103]
	v_mfma_f32_16x16x32_bf16 v[96:99], v[176:179], v[192:195], v[96:99]
	v_mfma_f32_16x16x32_bf16 v[84:87], v[164:167], v[200:203], v[84:87]
	v_mfma_f32_16x16x32_bf16 v[80:83], v[176:179], v[200:203], v[80:83]
	v_mfma_f32_16x16x32_bf16 v[68:71], v[164:167], v[208:211], v[68:71]
	v_mfma_f32_16x16x32_bf16 v[64:67], v[176:179], v[208:211], v[64:67]
	v_mfma_f32_16x16x32_bf16 v[116:119], v[172:175], v[188:191], v[116:119]
	v_mfma_f32_16x16x32_bf16 v[112:115], v[180:183], v[188:191], v[112:115]
	v_mfma_f32_16x16x32_bf16 v[100:103], v[172:175], v[196:199], v[100:103]
	v_mfma_f32_16x16x32_bf16 v[96:99], v[180:183], v[196:199], v[96:99]
	v_mfma_f32_16x16x32_bf16 v[84:87], v[172:175], v[204:207], v[84:87]
	v_mfma_f32_16x16x32_bf16 v[80:83], v[180:183], v[204:207], v[80:83]
	v_mfma_f32_16x16x32_bf16 v[68:71], v[172:175], v[212:215], v[68:71]
	v_mfma_f32_16x16x32_bf16 v[64:67], v[180:183], v[212:215], v[64:67]
	s_barrier
	s_add_i32 s24, s33, s34
	v_lshl_add_u64 v[168:169], v[168:169], 0, s[14:15]
	s_mov_b32 m0, s24
	ds_read_b128 v[184:187], v146 offset:49152
	ds_read_b128 v[188:191], v146 offset:50176
	ds_read_b128 v[192:195], v146 offset:51200
	ds_read_b128 v[196:199], v146 offset:52224
	ds_read_b128 v[200:203], v146 offset:53248
	ds_read_b128 v[204:207], v146 offset:54272
	ds_read_b128 v[208:211], v146 offset:55296
	ds_read_b128 v[212:215], v146 offset:56320
	global_load_lds_dwordx4 v[168:169], off
	s_add_i32 m0, s24, 0x2000
	s_add_u32 s22, s22, 0x160080
	v_lshl_add_u64 v[168:169], v[216:217], 0, s[14:15]
	s_addc_u32 s23, s23, 0
	s_add_i32 s24, s49, s34
	global_load_lds_dwordx4 v[168:169], off
	v_lshl_add_u64 v[168:169], s[22:23], 0, v[128:129]
	s_mov_b32 m0, s24
	s_nop 0
	global_load_lds_dwordx4 v[168:169], off
	v_lshl_add_u64 v[168:169], s[22:23], 0, v[130:131]
	s_add_i32 m0, s24, 0x2000
	s_nop 0
	global_load_lds_dwordx4 v[168:169], off
	v_lshl_add_u64 v[168:169], v[218:219], 0, s[14:15]
	s_mov_b32 m0, s40
	s_nop 0
	global_load_lds_dwordx4 v[168:169], off
	v_lshl_add_u64 v[168:169], v[222:223], 0, s[14:15]
	s_mov_b32 m0, s41
	s_nop 0
	global_load_lds_dwordx4 v[168:169], off
	s_waitcnt vmcnt(8)
	s_waitcnt lgkmcnt(0)
	s_barrier
	s_waitcnt lgkmcnt(0)
	v_mfma_f32_16x16x32_bf16 v[60:63], v[148:151], v[184:187], v[60:63]
	v_mfma_f32_16x16x32_bf16 v[56:59], v[156:159], v[184:187], v[56:59]
	v_mfma_f32_16x16x32_bf16 v[44:47], v[148:151], v[192:195], v[44:47]
	v_mfma_f32_16x16x32_bf16 v[40:43], v[156:159], v[192:195], v[40:43]
	v_mfma_f32_16x16x32_bf16 v[28:31], v[148:151], v[200:203], v[28:31]
	v_mfma_f32_16x16x32_bf16 v[24:27], v[156:159], v[200:203], v[24:27]
	v_mfma_f32_16x16x32_bf16 v[12:15], v[148:151], v[208:211], v[12:15]
	v_mfma_f32_16x16x32_bf16 v[8:11], v[156:159], v[208:211], v[8:11]
	v_mfma_f32_16x16x32_bf16 v[60:63], v[152:155], v[188:191], v[60:63]
	v_mfma_f32_16x16x32_bf16 v[56:59], v[160:163], v[188:191], v[56:59]
	v_mfma_f32_16x16x32_bf16 v[44:47], v[152:155], v[196:199], v[44:47]
	v_mfma_f32_16x16x32_bf16 v[40:43], v[160:163], v[196:199], v[40:43]
	v_mfma_f32_16x16x32_bf16 v[28:31], v[152:155], v[204:207], v[28:31]
	v_mfma_f32_16x16x32_bf16 v[24:27], v[160:163], v[204:207], v[24:27]
	v_mfma_f32_16x16x32_bf16 v[12:15], v[152:155], v[212:215], v[12:15]
	v_mfma_f32_16x16x32_bf16 v[8:11], v[160:163], v[212:215], v[8:11]
	v_mfma_f32_16x16x32_bf16 v[52:55], v[164:167], v[184:187], v[52:55]
	v_mfma_f32_16x16x32_bf16 v[48:51], v[176:179], v[184:187], v[48:51]
	v_mfma_f32_16x16x32_bf16 v[36:39], v[164:167], v[192:195], v[36:39]
	v_mfma_f32_16x16x32_bf16 v[32:35], v[176:179], v[192:195], v[32:35]
	v_mfma_f32_16x16x32_bf16 v[20:23], v[164:167], v[200:203], v[20:23]
	v_mfma_f32_16x16x32_bf16 v[16:19], v[176:179], v[200:203], v[16:19]
	v_mfma_f32_16x16x32_bf16 v[4:7], v[164:167], v[208:211], v[4:7]
	v_mfma_f32_16x16x32_bf16 v[0:3], v[176:179], v[208:211], v[0:3]
	v_mfma_f32_16x16x32_bf16 v[52:55], v[172:175], v[188:191], v[52:55]
	v_mfma_f32_16x16x32_bf16 v[48:51], v[180:183], v[188:191], v[48:51]
	v_mfma_f32_16x16x32_bf16 v[36:39], v[172:175], v[196:199], v[36:39]
	v_mfma_f32_16x16x32_bf16 v[32:35], v[180:183], v[196:199], v[32:35]
	v_mfma_f32_16x16x32_bf16 v[20:23], v[172:175], v[204:207], v[20:23]
	v_mfma_f32_16x16x32_bf16 v[16:19], v[180:183], v[204:207], v[16:19]
	v_mfma_f32_16x16x32_bf16 v[4:7], v[172:175], v[212:215], v[4:7]
	v_mfma_f32_16x16x32_bf16 v[0:3], v[180:183], v[212:215], v[0:3]
	s_barrier
	s_add_i32 s48, s48, 2
	s_add_u32 s20, s20, 0x100
	s_addc_u32 s21, s21, 0
	s_cmpk_gt_u32 s48, 0x55
	s_cbranch_scc0 .LBB0_798
	s_add_u32 s20, s17, 0xffffff00
	s_addc_u32 s21, s47, -1
	s_and_b64 vcc, exec, s[4:5]
	s_cbranch_vccnz .LBB0_801
	v_mov_b32_e32 v0, 0
	s_mov_b32 s29, s45
	s_mov_b32 s26, s46
	s_mov_b64 s[12:13], s[18:19]
	s_mov_b32 s42, s16
	v_mov_b32_e32 v1, v0
	v_mov_b32_e32 v2, v0
	v_mov_b32_e32 v3, v0
	v_mov_b32_e32 v4, v0
	v_mov_b32_e32 v5, v0
	v_mov_b32_e32 v6, v0
	v_mov_b32_e32 v7, v0
	v_mov_b32_e32 v16, v0
	v_mov_b32_e32 v17, v0
	v_mov_b32_e32 v18, v0
	v_mov_b32_e32 v19, v0
	v_mov_b32_e32 v20, v0
	v_mov_b32_e32 v21, v0
	v_mov_b32_e32 v22, v0
	v_mov_b32_e32 v23, v0
	v_mov_b32_e32 v32, v0
	v_mov_b32_e32 v33, v0
	v_mov_b32_e32 v34, v0
	v_mov_b32_e32 v35, v0
	v_mov_b32_e32 v36, v0
	v_mov_b32_e32 v37, v0
	v_mov_b32_e32 v38, v0
	v_mov_b32_e32 v39, v0
	v_mov_b32_e32 v48, v0
	v_mov_b32_e32 v49, v0
	v_mov_b32_e32 v50, v0
	v_mov_b32_e32 v51, v0
	v_mov_b32_e32 v52, v0
	v_mov_b32_e32 v53, v0
	v_mov_b32_e32 v54, v0
	v_mov_b32_e32 v55, v0
	v_mov_b32_e32 v8, v0
	v_mov_b32_e32 v9, v0
	v_mov_b32_e32 v10, v0
	v_mov_b32_e32 v11, v0
	v_mov_b32_e32 v12, v0
	v_mov_b32_e32 v13, v0
	v_mov_b32_e32 v14, v0
	v_mov_b32_e32 v15, v0
	v_mov_b32_e32 v24, v0
	v_mov_b32_e32 v25, v0
	v_mov_b32_e32 v26, v0
	v_mov_b32_e32 v27, v0
	v_mov_b32_e32 v28, v0
	v_mov_b32_e32 v29, v0
	v_mov_b32_e32 v30, v0
	v_mov_b32_e32 v31, v0
	v_mov_b32_e32 v40, v0
	v_mov_b32_e32 v41, v0
	v_mov_b32_e32 v42, v0
	v_mov_b32_e32 v43, v0
	v_mov_b32_e32 v44, v0
	v_mov_b32_e32 v45, v0
	v_mov_b32_e32 v46, v0
	v_mov_b32_e32 v47, v0
	v_mov_b32_e32 v56, v0
	v_mov_b32_e32 v57, v0
	v_mov_b32_e32 v58, v0
	v_mov_b32_e32 v59, v0
	v_mov_b32_e32 v60, v0
	v_mov_b32_e32 v61, v0
	v_mov_b32_e32 v62, v0
	v_mov_b32_e32 v63, v0
	v_mov_b32_e32 v64, v0
	v_mov_b32_e32 v65, v0
	v_mov_b32_e32 v66, v0
	v_mov_b32_e32 v67, v0
	v_mov_b32_e32 v68, v0
	v_mov_b32_e32 v69, v0
	v_mov_b32_e32 v70, v0
	v_mov_b32_e32 v71, v0
	v_mov_b32_e32 v80, v0
	v_mov_b32_e32 v81, v0
	v_mov_b32_e32 v82, v0
	v_mov_b32_e32 v83, v0
	v_mov_b32_e32 v84, v0
	v_mov_b32_e32 v85, v0
	v_mov_b32_e32 v86, v0
	v_mov_b32_e32 v87, v0
	v_mov_b32_e32 v96, v0
	v_mov_b32_e32 v97, v0
	v_mov_b32_e32 v98, v0
	v_mov_b32_e32 v99, v0
	v_mov_b32_e32 v100, v0
	v_mov_b32_e32 v101, v0
	v_mov_b32_e32 v102, v0
	v_mov_b32_e32 v103, v0
	v_mov_b32_e32 v112, v0
	v_mov_b32_e32 v113, v0
	v_mov_b32_e32 v114, v0
	v_mov_b32_e32 v115, v0
	v_mov_b32_e32 v116, v0
	v_mov_b32_e32 v117, v0
	v_mov_b32_e32 v118, v0
	v_mov_b32_e32 v119, v0
	v_mov_b32_e32 v72, v0
	v_mov_b32_e32 v73, v0
	v_mov_b32_e32 v74, v0
	v_mov_b32_e32 v75, v0
	v_mov_b32_e32 v76, v0
	v_mov_b32_e32 v77, v0
	v_mov_b32_e32 v78, v0
	v_mov_b32_e32 v79, v0
	v_mov_b32_e32 v88, v0
	v_mov_b32_e32 v89, v0
	v_mov_b32_e32 v90, v0
	v_mov_b32_e32 v91, v0
	v_mov_b32_e32 v92, v0
	v_mov_b32_e32 v93, v0
	v_mov_b32_e32 v94, v0
	v_mov_b32_e32 v95, v0
	v_mov_b32_e32 v104, v0
	v_mov_b32_e32 v105, v0
	v_mov_b32_e32 v106, v0
	v_mov_b32_e32 v107, v0
	v_mov_b32_e32 v108, v0
	v_mov_b32_e32 v109, v0
	v_mov_b32_e32 v110, v0
	v_mov_b32_e32 v111, v0
	v_mov_b32_e32 v120, v0
	v_mov_b32_e32 v121, v0
	v_mov_b32_e32 v122, v0
	v_mov_b32_e32 v123, v0
	v_mov_b32_e32 v124, v0
	v_mov_b32_e32 v125, v0
	v_mov_b32_e32 v126, v0
	v_mov_b32_e32 v127, v0
	s_andn2_b64 vcc, exec, s[2:3]
	s_cbranch_vccnz .LBB0_802
	s_branch .LBB0_803
